# GATES epilogues: -log2(e) factor of the sigmoid folded into the 8 per-row rinv values (128 fewer f32 multiplies per wave per unit)
# baseline (speedup 1.0000x reference)
; __device__ __forceinline__ float sigmoidf_(float z) { return __builtin_amdgcn_rcpf(1.0f + __builtin_amdgcn_exp2f(-1.4426950408889634f * z)); }
;     __device__ __forceinline__ void load(Pre& p, const pg8::Unit& u, int ai, int m, int wr, int wc, int fr, int fq) const {
;         const int row = u.pm * 256 + ai * 128 + wr * 64 + m * 16 + fr;
;         if (MODE == EM_PROJ || MODE == EM_GATES) p.rs = ((const float*)(ws + WS_RINV0))[row];
;     __device__ __forceinline__ float compute(const Pre& p, f32x4 (&acc)[2][2][4][2], const f32x4 (&cv)[2][2], const pg8::Unit& u, int ai, int m, int wr, int wc, int fr, int fq) const {
;     ...
;             } else if (MODE == EM_GATES) {
;                 const int col = u.pn * 256 + ct; float w[8];
; #pragma unroll
;                 for (int j = 0; j < 8; ++j) w[j] = sigmoidf_(v[j] * rs) * 255.0f + 0.5f;
;                 u32x2 cd; cd.x = (unsigned)w[0] | ((unsigned)w[1] << 8) | ((unsigned)w[2] << 16) | ((unsigned)w[3] << 24); cd.y = (unsigned)w[4] | ((unsigned)w[5] << 8) | ((unsigned)w[6] << 16) | ((unsigned)w[7] << 24);
;                 *(u32x2*)(ws + WS_G8 + (size_t)row * 2048 + col) = cd;
.LBB0_676:
	v_lshl_add_u32 v164, s30, 8, v158
	v_ashrrev_i32_e32 v165, 31, v164
	v_lshl_add_u64 v[142:143], v[164:165], 2, s[10:11]
	global_load_dword v182, v[142:143], off
	v_or_b32_e32 v156, 16, v164
	v_or_b32_e32 v154, 32, v164
	v_or_b32_e32 v152, 48, v164
	v_add_u32_e32 v150, 0x80, v164
	v_add_u32_e32 v148, 0x90, v164
	v_add_u32_e32 v146, 0xa0, v164
	v_add_u32_e32 v144, 0xb0, v164
	v_ashrrev_i32_e32 v157, 31, v156
	v_ashrrev_i32_e32 v155, 31, v154
	v_ashrrev_i32_e32 v153, 31, v152
	v_ashrrev_i32_e32 v151, 31, v150
	v_ashrrev_i32_e32 v149, 31, v148
	v_ashrrev_i32_e32 v147, 31, v146
	v_ashrrev_i32_e32 v145, 31, v144
	v_lshlrev_b64 v[170:171], 11, v[164:165]
	v_lshl_add_u64 v[164:165], v[156:157], 2, s[10:11]
	v_lshl_add_u64 v[166:167], v[154:155], 2, s[10:11]
	v_lshl_add_u64 v[168:169], v[152:153], 2, s[10:11]
	v_lshl_add_u64 v[172:173], v[150:151], 2, s[10:11]
	v_lshl_add_u64 v[174:175], v[148:149], 2, s[10:11]
	v_lshl_add_u64 v[176:177], v[146:147], 2, s[10:11]
	v_lshl_add_u64 v[178:179], v[144:145], 2, s[10:11]
	global_load_dword v183, v[164:165], off
	global_load_dword v184, v[166:167], off
	s_nop 0
	global_load_dword v168, v[168:169], off
	s_nop 0
	global_load_dword v167, v[172:173], off
	global_load_dword v166, v[174:175], off
	global_load_dword v165, v[176:177], off
	global_load_dword v164, v[178:179], off
	v_lshl_or_b32 v142, s60, 8, v160
	v_ashrrev_i32_e32 v143, 31, v142
	v_lshl_add_u64 v[180:181], s[12:13], 0, v[170:171]
	v_lshl_add_u64 v[172:173], v[180:181], 0, v[142:143]
	v_readlane_b32 s66, v255, 7
	v_readlane_b32 s67, v255, 8
	s_waitcnt vmcnt(0)
	v_mul_f32_e32 v182, 0xbfb8aa3b, v182
	v_mul_f32_e32 v183, 0xbfb8aa3b, v183
	v_mul_f32_e32 v184, 0xbfb8aa3b, v184
	v_mul_f32_e32 v168, 0xbfb8aa3b, v168
	v_mul_f32_e32 v167, 0xbfb8aa3b, v167
	v_mul_f32_e32 v166, 0xbfb8aa3b, v166
	v_mul_f32_e32 v165, 0xbfb8aa3b, v165
	v_mul_f32_e32 v164, 0xbfb8aa3b, v164
	v_mul_f32_e32 v125, v125, v182
	v_mul_f32_e32 v121, v121, v182
	v_mul_f32_e32 v124, v124, v182
	v_mul_f32_e32 v126, v126, v182
	v_mul_f32_e32 v120, v120, v182
	v_exp_f32_e32 v125, v125
	v_exp_f32_e32 v121, v121
	v_mul_f32_e32 v127, v127, v182
	v_mul_f32_e32 v122, v122, v182
	v_exp_f32_e32 v124, v124
	v_exp_f32_e32 v126, v126
	v_exp_f32_e32 v120, v120
	v_mul_f32_e32 v123, v123, v182
	v_mul_f32_e32 v117, v117, v182
	v_mul_f32_e32 v116, v116, v182
	v_exp_f32_e32 v127, v127
	v_exp_f32_e32 v122, v122
	v_exp_f32_e32 v123, v123
	v_exp_f32_e32 v174, v117
	v_add_f32_e32 v117, 1.0, v125
	v_add_f32_e32 v121, 1.0, v121
	v_exp_f32_e32 v169, v116
	v_add_f32_e32 v116, 1.0, v124
	v_add_f32_e32 v124, 1.0, v126
	v_add_f32_e32 v126, 1.0, v120
	v_rcp_f32_e32 v120, v117
	v_rcp_f32_e32 v121, v121
	v_rcp_f32_e32 v116, v116
	v_rcp_f32_e32 v117, v126
	v_add_f32_e32 v125, 1.0, v127
	v_add_f32_e32 v127, 1.0, v122
	v_add_f32_e32 v175, 1.0, v123
	v_rcp_f32_e32 v122, v124
	v_rcp_f32_e32 v123, v127
	v_rcp_f32_e32 v124, v125
	v_rcp_f32_e32 v125, v175
	v_pk_fma_f32 v[120:121], v[120:121], s[14:15], 0.5 op_sel_hi:[1,0,0]
	v_pk_fma_f32 v[116:117], v[116:117], s[14:15], 0.5 op_sel_hi:[1,0,0]
	v_cvt_u32_f32_e32 v120, v120
	v_cvt_u32_f32_e32 v116, v116
	v_cvt_u32_f32_e32 v121, v121
	v_pk_fma_f32 v[122:123], v[122:123], s[14:15], 0.5 op_sel_hi:[1,0,0]
	v_cvt_u32_f32_e32 v117, v117
	v_pk_fma_f32 v[124:125], v[124:125], s[14:15], 0.5 op_sel_hi:[1,0,0]
	v_cvt_u32_f32_sdwa v122, v122 dst_sel:WORD_1 dst_unused:UNUSED_PAD src0_sel:DWORD
	v_cvt_u32_f32_sdwa v123, v123 dst_sel:WORD_1 dst_unused:UNUSED_PAD src0_sel:DWORD
	v_mul_f32_e32 v118, v118, v182
	v_cvt_u32_f32_sdwa v124, v124 dst_sel:BYTE_3 dst_unused:UNUSED_PAD src0_sel:DWORD
	v_cvt_u32_f32_sdwa v125, v125 dst_sel:BYTE_3 dst_unused:UNUSED_PAD src0_sel:DWORD
	v_lshlrev_b32_e32 v120, 8, v120
	v_lshlrev_b32_e32 v121, 8, v121
	v_or_b32_e32 v116, v120, v116
	v_exp_f32_e32 v120, v118
	v_mul_f32_e32 v118, v119, v182
	v_or_b32_e32 v117, v121, v117
	v_or_b32_e32 v117, v117, v123
	v_or_b32_e32 v116, v116, v122
	v_exp_f32_e32 v119, v118
	v_or_b32_e32 v117, v117, v125
	v_or_b32_e32 v116, v116, v124
	global_store_dwordx2 v[172:173], v[116:117], off
	v_add_f32_e32 v117, 1.0, v174
	v_mul_f32_e32 v112, v112, v182
	v_rcp_f32_e32 v118, v117
	v_add_f32_e32 v117, 1.0, v120
	v_rcp_f32_e32 v120, v117
	v_add_f32_e32 v117, 1.0, v119
	v_exp_f32_e32 v119, v112
	v_mul_f32_e32 v112, v113, v182
	v_exp_f32_e32 v113, v112
	v_mul_f32_e32 v114, v114, v182
	v_mul_f32_e32 v115, v115, v182
	v_add_f32_e32 v116, 1.0, v169
	v_rcp_f32_e32 v112, v117
	v_add_f32_e32 v117, 1.0, v119
	v_add_f32_e32 v113, 1.0, v113
	v_exp_f32_e32 v114, v114
	v_rcp_f32_e32 v116, v116
	v_rcp_f32_e32 v117, v117
	v_exp_f32_e32 v115, v115
	v_rcp_f32_e32 v119, v113
	v_add_f32_e32 v113, 1.0, v114
	v_rcp_f32_e32 v121, v113
	v_add_f32_e32 v113, 1.0, v115
	v_pk_fma_f32 v[114:115], v[116:117], s[14:15], 0.5 op_sel_hi:[1,0,0]
	v_pk_fma_f32 v[116:117], v[118:119], s[14:15], 0.5 op_sel_hi:[1,0,0]
	v_rcp_f32_e32 v113, v113
	v_cvt_u32_f32_e32 v117, v117
	v_cvt_u32_f32_e32 v116, v116
	v_cvt_u32_f32_e32 v115, v115
	v_cvt_u32_f32_e32 v114, v114
	v_pk_fma_f32 v[118:119], v[120:121], s[14:15], 0.5 op_sel_hi:[1,0,0]
	v_lshlrev_b32_e32 v117, 8, v117
	v_lshlrev_b32_e32 v116, 8, v116
	v_pk_fma_f32 v[112:113], v[112:113], s[14:15], 0.5 op_sel_hi:[1,0,0]
	v_or_b32_e32 v115, v117, v115
	v_or_b32_e32 v114, v116, v114
	v_cvt_u32_f32_sdwa v116, v119 dst_sel:WORD_1 dst_unused:UNUSED_PAD src0_sel:DWORD
	v_cvt_u32_f32_sdwa v117, v118 dst_sel:WORD_1 dst_unused:UNUSED_PAD src0_sel:DWORD
	v_cvt_u32_f32_sdwa v113, v113 dst_sel:BYTE_3 dst_unused:UNUSED_PAD src0_sel:DWORD
	v_cvt_u32_f32_sdwa v112, v112 dst_sel:BYTE_3 dst_unused:UNUSED_PAD src0_sel:DWORD
; __device__ __forceinline__ float sigmoidf_(float z) { return __builtin_amdgcn_rcpf(1.0f + __builtin_amdgcn_exp2f(-1.4426950408889634f * z)); }
;     __device__ __forceinline__ float compute(const Pre& p, f32x4 (&acc)[2][2][4][2], const f32x4 (&cv)[2][2], const pg8::Unit& u, int ai, int m, int wr, int wc, int fr, int fq) const {
;     ...
;             } else if (MODE == EM_GATES) {
;                 const int col = u.pn * 256 + ct; float w[8];
; #pragma unroll
;                 for (int j = 0; j < 8; ++j) w[j] = sigmoidf_(v[j] * rs) * 255.0f + 0.5f;
;                 u32x2 cd; cd.x = (unsigned)w[0] | ((unsigned)w[1] << 8) | ((unsigned)w[2] << 16) | ((unsigned)w[3] << 24); cd.y = (unsigned)w[4] | ((unsigned)w[5] << 8) | ((unsigned)w[6] << 16) | ((unsigned)w[7] << 24);
;                 *(u32x2*)(ws + WS_G8 + (size_t)row * 2048 + col) = cd;
	v_or_b32_e32 v115, v115, v116
	v_or_b32_e32 v114, v114, v117
	v_or_b32_e32 v113, v115, v113
	v_or_b32_e32 v112, v114, v112
	v_lshl_add_u64 v[114:115], s[92:93], 0, v[170:171]
	v_lshl_add_u64 v[114:115], v[114:115], 0, v[142:143]
	v_add_co_u32_e32 v114, vcc, s59, v114
	v_mul_f32_e32 v108, v108, v183
	s_nop 0
	v_addc_co_u32_e32 v115, vcc, 0, v115, vcc
	global_store_dwordx2 v[114:115], v[112:113], off offset:128
	v_exp_f32_e32 v112, v108
	v_mul_f32_e32 v108, v109, v183
	v_mul_f32_e32 v110, v110, v183
	v_exp_f32_e32 v113, v108
	v_exp_f32_e32 v114, v110
	v_mul_f32_e32 v110, v111, v183
	v_add_f32_e32 v113, 1.0, v113
	v_mul_f32_e32 v104, v104, v183
	v_exp_f32_e32 v111, v110
	v_rcp_f32_e32 v110, v113
	v_add_f32_e32 v113, 1.0, v114
	v_rcp_f32_e32 v114, v113
	v_exp_f32_e32 v113, v104
	v_mul_f32_e32 v104, v105, v183
	v_exp_f32_e32 v105, v104
	v_add_f32_e32 v111, 1.0, v111
	v_mul_f32_e32 v106, v106, v183
	v_rcp_f32_e32 v104, v111
	v_add_f32_e32 v111, 1.0, v113
	v_add_f32_e32 v105, 1.0, v105
	v_mul_f32_e32 v107, v107, v183
	v_add_f32_e32 v112, 1.0, v112
	v_rcp_f32_e32 v113, v111
	v_exp_f32_e32 v106, v106
	v_rcp_f32_e32 v111, v105
	v_rcp_f32_e32 v112, v112
	v_exp_f32_e32 v107, v107
	v_add_f32_e32 v105, 1.0, v106
	v_pk_fma_f32 v[110:111], v[110:111], s[14:15], 0.5 op_sel_hi:[1,0,0]
	v_rcp_f32_e32 v115, v105
	v_add_f32_e32 v105, 1.0, v107
	v_pk_fma_f32 v[106:107], v[112:113], s[14:15], 0.5 op_sel_hi:[1,0,0]
	v_cvt_u32_f32_e32 v111, v111
	v_cvt_u32_f32_e32 v110, v110
	v_rcp_f32_e32 v105, v105
	v_cvt_u32_f32_e32 v107, v107
	v_cvt_u32_f32_e32 v106, v106
	v_pk_fma_f32 v[112:113], v[114:115], s[14:15], 0.5 op_sel_hi:[1,0,0]
	v_lshlrev_b32_e32 v111, 8, v111
	v_lshlrev_b32_e32 v110, 8, v110
	v_pk_fma_f32 v[104:105], v[104:105], s[14:15], 0.5 op_sel_hi:[1,0,0]
	v_or_b32_e32 v107, v111, v107
	v_or_b32_e32 v106, v110, v106
	v_cvt_u32_f32_sdwa v110, v113 dst_sel:WORD_1 dst_unused:UNUSED_PAD src0_sel:DWORD
	v_cvt_u32_f32_sdwa v111, v112 dst_sel:WORD_1 dst_unused:UNUSED_PAD src0_sel:DWORD
	v_cvt_u32_f32_sdwa v105, v105 dst_sel:BYTE_3 dst_unused:UNUSED_PAD src0_sel:DWORD
	v_cvt_u32_f32_sdwa v104, v104 dst_sel:BYTE_3 dst_unused:UNUSED_PAD src0_sel:DWORD
	v_lshlrev_b64 v[108:109], 11, v[156:157]
	v_or_b32_e32 v107, v107, v110
	v_or_b32_e32 v106, v106, v111
	v_or_b32_e32 v105, v107, v105
	v_or_b32_e32 v104, v106, v104
	v_lshl_add_u64 v[106:107], s[12:13], 0, v[108:109]
	v_mul_f32_e32 v101, v101, v183
	v_mul_f32_e32 v102, v102, v183
	v_lshl_add_u64 v[106:107], v[106:107], 0, v[142:143]
	v_exp_f32_e32 v101, v101
	global_store_dwordx2 v[106:107], v[104:105], off
	v_exp_f32_e32 v104, v102
	v_mul_f32_e32 v102, v103, v183
	v_exp_f32_e32 v103, v102
	v_add_f32_e32 v101, 1.0, v101
	v_mul_f32_e32 v96, v96, v183
	v_rcp_f32_e32 v102, v101
	v_add_f32_e32 v101, 1.0, v104
	v_mul_f32_e32 v100, v100, v183
	v_rcp_f32_e32 v104, v101
	v_add_f32_e32 v101, 1.0, v103
	v_exp_f32_e32 v103, v96
	v_mul_f32_e32 v96, v97, v183
	v_exp_f32_e32 v100, v100
	v_exp_f32_e32 v97, v96
	v_mul_f32_e32 v98, v98, v183
	v_mul_f32_e32 v99, v99, v183
	v_add_f32_e32 v100, 1.0, v100
	v_rcp_f32_e32 v96, v101
	v_add_f32_e32 v101, 1.0, v103
	v_add_f32_e32 v97, 1.0, v97
	v_exp_f32_e32 v98, v98
	v_rcp_f32_e32 v100, v100
	v_rcp_f32_e32 v101, v101
	v_exp_f32_e32 v99, v99
	v_rcp_f32_e32 v103, v97
	v_add_f32_e32 v97, 1.0, v98
	v_rcp_f32_e32 v105, v97
	v_add_f32_e32 v97, 1.0, v99
	v_pk_fma_f32 v[98:99], v[100:101], s[14:15], 0.5 op_sel_hi:[1,0,0]
	v_pk_fma_f32 v[100:101], v[102:103], s[14:15], 0.5 op_sel_hi:[1,0,0]
	v_rcp_f32_e32 v97, v97
	v_cvt_u32_f32_e32 v101, v101
	v_cvt_u32_f32_e32 v100, v100
	v_cvt_u32_f32_e32 v99, v99
	v_cvt_u32_f32_e32 v98, v98
	v_pk_fma_f32 v[102:103], v[104:105], s[14:15], 0.5 op_sel_hi:[1,0,0]
	v_lshlrev_b32_e32 v101, 8, v101
	v_lshlrev_b32_e32 v100, 8, v100
	v_pk_fma_f32 v[96:97], v[96:97], s[14:15], 0.5 op_sel_hi:[1,0,0]
	v_or_b32_e32 v99, v101, v99
	v_or_b32_e32 v98, v100, v98
	v_cvt_u32_f32_sdwa v100, v103 dst_sel:WORD_1 dst_unused:UNUSED_PAD src0_sel:DWORD
	v_cvt_u32_f32_sdwa v101, v102 dst_sel:WORD_1 dst_unused:UNUSED_PAD src0_sel:DWORD
	v_cvt_u32_f32_sdwa v97, v97 dst_sel:BYTE_3 dst_unused:UNUSED_PAD src0_sel:DWORD
	v_cvt_u32_f32_sdwa v96, v96 dst_sel:BYTE_3 dst_unused:UNUSED_PAD src0_sel:DWORD
	v_or_b32_e32 v99, v99, v100
	v_or_b32_e32 v98, v98, v101
	v_or_b32_e32 v97, v99, v97
	v_or_b32_e32 v96, v98, v96
	v_lshl_add_u64 v[98:99], s[92:93], 0, v[108:109]
	v_lshl_add_u64 v[98:99], v[98:99], 0, v[142:143]
	v_add_co_u32_e32 v98, vcc, s59, v98
	v_mul_f32_e32 v92, v92, v184
	s_nop 0
	v_addc_co_u32_e32 v99, vcc, 0, v99, vcc
	global_store_dwordx2 v[98:99], v[96:97], off offset:128
	v_exp_f32_e32 v96, v92
	v_mul_f32_e32 v92, v93, v184
	v_mul_f32_e32 v94, v94, v184
	v_exp_f32_e32 v97, v92
	v_exp_f32_e32 v98, v94
	v_mul_f32_e32 v94, v95, v184
	v_add_f32_e32 v97, 1.0, v97
	v_mul_f32_e32 v88, v88, v184
	v_exp_f32_e32 v95, v94
	v_rcp_f32_e32 v94, v97
	v_add_f32_e32 v97, 1.0, v98
	v_rcp_f32_e32 v98, v97
	v_exp_f32_e32 v97, v88
	v_mul_f32_e32 v88, v89, v184
	v_exp_f32_e32 v89, v88
	v_add_f32_e32 v95, 1.0, v95
	v_mul_f32_e32 v90, v90, v184
	v_rcp_f32_e32 v88, v95
	v_add_f32_e32 v95, 1.0, v97
	v_add_f32_e32 v89, 1.0, v89
	v_mul_f32_e32 v91, v91, v184
	v_add_f32_e32 v96, 1.0, v96
	v_rcp_f32_e32 v97, v95
	v_exp_f32_e32 v90, v90
	v_rcp_f32_e32 v95, v89
	v_rcp_f32_e32 v96, v96
	v_exp_f32_e32 v91, v91
	v_add_f32_e32 v89, 1.0, v90
	v_pk_fma_f32 v[94:95], v[94:95], s[14:15], 0.5 op_sel_hi:[1,0,0]
	v_rcp_f32_e32 v99, v89
	v_add_f32_e32 v89, 1.0, v91
	v_pk_fma_f32 v[90:91], v[96:97], s[14:15], 0.5 op_sel_hi:[1,0,0]
	v_cvt_u32_f32_e32 v95, v95
	v_cvt_u32_f32_e32 v94, v94
	v_rcp_f32_e32 v89, v89
	v_cvt_u32_f32_e32 v91, v91
; __device__ __forceinline__ float sigmoidf_(float z) { return __builtin_amdgcn_rcpf(1.0f + __builtin_amdgcn_exp2f(-1.4426950408889634f * z)); }
;     __device__ __forceinline__ float compute(const Pre& p, f32x4 (&acc)[2][2][4][2], const f32x4 (&cv)[2][2], const pg8::Unit& u, int ai, int m, int wr, int wc, int fr, int fq) const {
;     ...
;             } else if (MODE == EM_GATES) {
;                 const int col = u.pn * 256 + ct; float w[8];
; #pragma unroll
;                 for (int j = 0; j < 8; ++j) w[j] = sigmoidf_(v[j] * rs) * 255.0f + 0.5f;
;                 u32x2 cd; cd.x = (unsigned)w[0] | ((unsigned)w[1] << 8) | ((unsigned)w[2] << 16) | ((unsigned)w[3] << 24); cd.y = (unsigned)w[4] | ((unsigned)w[5] << 8) | ((unsigned)w[6] << 16) | ((unsigned)w[7] << 24);
;                 *(u32x2*)(ws + WS_G8 + (size_t)row * 2048 + col) = cd;
	v_cvt_u32_f32_e32 v90, v90
	v_pk_fma_f32 v[96:97], v[98:99], s[14:15], 0.5 op_sel_hi:[1,0,0]
	v_lshlrev_b32_e32 v95, 8, v95
	v_lshlrev_b32_e32 v94, 8, v94
	v_pk_fma_f32 v[88:89], v[88:89], s[14:15], 0.5 op_sel_hi:[1,0,0]
	v_or_b32_e32 v91, v95, v91
	v_or_b32_e32 v90, v94, v90
	v_cvt_u32_f32_sdwa v94, v97 dst_sel:WORD_1 dst_unused:UNUSED_PAD src0_sel:DWORD
	v_cvt_u32_f32_sdwa v95, v96 dst_sel:WORD_1 dst_unused:UNUSED_PAD src0_sel:DWORD
	v_cvt_u32_f32_sdwa v89, v89 dst_sel:BYTE_3 dst_unused:UNUSED_PAD src0_sel:DWORD
	v_cvt_u32_f32_sdwa v88, v88 dst_sel:BYTE_3 dst_unused:UNUSED_PAD src0_sel:DWORD
	v_lshlrev_b64 v[92:93], 11, v[154:155]
	v_or_b32_e32 v91, v91, v94
	v_or_b32_e32 v90, v90, v95
	v_or_b32_e32 v89, v91, v89
	v_or_b32_e32 v88, v90, v88
	v_lshl_add_u64 v[90:91], s[12:13], 0, v[92:93]
	v_mul_f32_e32 v85, v85, v184
	v_mul_f32_e32 v86, v86, v184
	v_lshl_add_u64 v[90:91], v[90:91], 0, v[142:143]
	v_exp_f32_e32 v85, v85
	global_store_dwordx2 v[90:91], v[88:89], off
	v_exp_f32_e32 v88, v86
	v_mul_f32_e32 v86, v87, v184
	v_exp_f32_e32 v87, v86
	v_add_f32_e32 v85, 1.0, v85
	v_mul_f32_e32 v80, v80, v184
	v_rcp_f32_e32 v86, v85
	v_add_f32_e32 v85, 1.0, v88
	v_mul_f32_e32 v84, v84, v184
	v_rcp_f32_e32 v88, v85
	v_add_f32_e32 v85, 1.0, v87
	v_exp_f32_e32 v87, v80
	v_mul_f32_e32 v80, v81, v184
	v_exp_f32_e32 v84, v84
	v_exp_f32_e32 v81, v80
	v_mul_f32_e32 v82, v82, v184
	v_mul_f32_e32 v83, v83, v184
	v_add_f32_e32 v84, 1.0, v84
	v_rcp_f32_e32 v80, v85
	v_add_f32_e32 v85, 1.0, v87
	v_add_f32_e32 v81, 1.0, v81
	v_exp_f32_e32 v82, v82
	v_rcp_f32_e32 v84, v84
	v_rcp_f32_e32 v85, v85
	v_exp_f32_e32 v83, v83
	v_rcp_f32_e32 v87, v81
	v_add_f32_e32 v81, 1.0, v82
	v_rcp_f32_e32 v89, v81
	v_add_f32_e32 v81, 1.0, v83
	v_pk_fma_f32 v[82:83], v[84:85], s[14:15], 0.5 op_sel_hi:[1,0,0]
	v_pk_fma_f32 v[84:85], v[86:87], s[14:15], 0.5 op_sel_hi:[1,0,0]
	v_rcp_f32_e32 v81, v81
	v_cvt_u32_f32_e32 v85, v85
	v_cvt_u32_f32_e32 v84, v84
	v_cvt_u32_f32_e32 v83, v83
	v_cvt_u32_f32_e32 v82, v82
	v_pk_fma_f32 v[86:87], v[88:89], s[14:15], 0.5 op_sel_hi:[1,0,0]
	v_lshlrev_b32_e32 v85, 8, v85
	v_lshlrev_b32_e32 v84, 8, v84
	v_pk_fma_f32 v[80:81], v[80:81], s[14:15], 0.5 op_sel_hi:[1,0,0]
	v_or_b32_e32 v83, v85, v83
	v_or_b32_e32 v82, v84, v82
	v_cvt_u32_f32_sdwa v84, v87 dst_sel:WORD_1 dst_unused:UNUSED_PAD src0_sel:DWORD
	v_cvt_u32_f32_sdwa v85, v86 dst_sel:WORD_1 dst_unused:UNUSED_PAD src0_sel:DWORD
	v_cvt_u32_f32_sdwa v81, v81 dst_sel:BYTE_3 dst_unused:UNUSED_PAD src0_sel:DWORD
	v_cvt_u32_f32_sdwa v80, v80 dst_sel:BYTE_3 dst_unused:UNUSED_PAD src0_sel:DWORD
	v_or_b32_e32 v83, v83, v84
	v_or_b32_e32 v82, v82, v85
	v_or_b32_e32 v81, v83, v81
	v_or_b32_e32 v80, v82, v80
	v_lshl_add_u64 v[82:83], s[92:93], 0, v[92:93]
	v_lshl_add_u64 v[82:83], v[82:83], 0, v[142:143]
	v_add_co_u32_e32 v82, vcc, s59, v82
	v_mul_f32_e32 v76, v76, v168
	s_nop 0
	v_addc_co_u32_e32 v83, vcc, 0, v83, vcc
	global_store_dwordx2 v[82:83], v[80:81], off offset:128
	v_exp_f32_e32 v80, v76
	v_mul_f32_e32 v76, v77, v168
	v_mul_f32_e32 v78, v78, v168
	v_exp_f32_e32 v81, v76
	v_exp_f32_e32 v82, v78
	v_mul_f32_e32 v78, v79, v168
	v_add_f32_e32 v81, 1.0, v81
	v_mul_f32_e32 v72, v72, v168
	v_exp_f32_e32 v79, v78
	v_rcp_f32_e32 v78, v81
	v_add_f32_e32 v81, 1.0, v82
	v_rcp_f32_e32 v82, v81
	v_exp_f32_e32 v81, v72
	v_mul_f32_e32 v72, v73, v168
	v_exp_f32_e32 v73, v72
	v_add_f32_e32 v79, 1.0, v79
	v_mul_f32_e32 v74, v74, v168
	v_rcp_f32_e32 v72, v79
	v_add_f32_e32 v79, 1.0, v81
	v_add_f32_e32 v73, 1.0, v73
	v_mul_f32_e32 v75, v75, v168
	v_add_f32_e32 v80, 1.0, v80
	v_rcp_f32_e32 v81, v79
	v_exp_f32_e32 v74, v74
	v_rcp_f32_e32 v79, v73
	v_rcp_f32_e32 v80, v80
	v_exp_f32_e32 v75, v75
	v_add_f32_e32 v73, 1.0, v74
	v_pk_fma_f32 v[78:79], v[78:79], s[14:15], 0.5 op_sel_hi:[1,0,0]
	v_rcp_f32_e32 v83, v73
	v_add_f32_e32 v73, 1.0, v75
	v_pk_fma_f32 v[74:75], v[80:81], s[14:15], 0.5 op_sel_hi:[1,0,0]
	v_cvt_u32_f32_e32 v79, v79
	v_cvt_u32_f32_e32 v78, v78
	v_rcp_f32_e32 v73, v73
	v_cvt_u32_f32_e32 v75, v75
	v_cvt_u32_f32_e32 v74, v74
	v_pk_fma_f32 v[80:81], v[82:83], s[14:15], 0.5 op_sel_hi:[1,0,0]
	v_lshlrev_b32_e32 v79, 8, v79
	v_lshlrev_b32_e32 v78, 8, v78
	v_pk_fma_f32 v[72:73], v[72:73], s[14:15], 0.5 op_sel_hi:[1,0,0]
	v_or_b32_e32 v75, v79, v75
	v_or_b32_e32 v74, v78, v74
	v_cvt_u32_f32_sdwa v78, v81 dst_sel:WORD_1 dst_unused:UNUSED_PAD src0_sel:DWORD
	v_cvt_u32_f32_sdwa v79, v80 dst_sel:WORD_1 dst_unused:UNUSED_PAD src0_sel:DWORD
	v_cvt_u32_f32_sdwa v73, v73 dst_sel:BYTE_3 dst_unused:UNUSED_PAD src0_sel:DWORD
	v_cvt_u32_f32_sdwa v72, v72 dst_sel:BYTE_3 dst_unused:UNUSED_PAD src0_sel:DWORD
	v_lshlrev_b64 v[76:77], 11, v[152:153]
	v_or_b32_e32 v75, v75, v78
	v_or_b32_e32 v74, v74, v79
	v_or_b32_e32 v73, v75, v73
	v_or_b32_e32 v72, v74, v72
	v_lshl_add_u64 v[74:75], s[12:13], 0, v[76:77]
	v_mul_f32_e32 v69, v69, v168
	v_mul_f32_e32 v70, v70, v168
	v_lshl_add_u64 v[74:75], v[74:75], 0, v[142:143]
	v_exp_f32_e32 v69, v69
	global_store_dwordx2 v[74:75], v[72:73], off
	v_exp_f32_e32 v72, v70
	v_mul_f32_e32 v70, v71, v168
	v_exp_f32_e32 v71, v70
	v_add_f32_e32 v69, 1.0, v69
	v_mul_f32_e32 v64, v64, v168
	v_rcp_f32_e32 v70, v69
	v_add_f32_e32 v69, 1.0, v72
	v_mul_f32_e32 v68, v68, v168
	v_rcp_f32_e32 v72, v69
	v_add_f32_e32 v69, 1.0, v71
	v_exp_f32_e32 v71, v64
	v_mul_f32_e32 v64, v65, v168
	v_exp_f32_e32 v68, v68
	v_exp_f32_e32 v65, v64
	v_mul_f32_e32 v66, v66, v168
	v_mul_f32_e32 v67, v67, v168
	v_add_f32_e32 v68, 1.0, v68
	v_rcp_f32_e32 v64, v69
	v_add_f32_e32 v69, 1.0, v71
	v_add_f32_e32 v65, 1.0, v65
	v_exp_f32_e32 v66, v66
	v_rcp_f32_e32 v68, v68
	v_rcp_f32_e32 v69, v69
	v_exp_f32_e32 v67, v67
	v_rcp_f32_e32 v71, v65
; __device__ __forceinline__ float sigmoidf_(float z) { return __builtin_amdgcn_rcpf(1.0f + __builtin_amdgcn_exp2f(-1.4426950408889634f * z)); }
;     __device__ __forceinline__ float compute(const Pre& p, f32x4 (&acc)[2][2][4][2], const f32x4 (&cv)[2][2], const pg8::Unit& u, int ai, int m, int wr, int wc, int fr, int fq) const {
;     ...
;             } else if (MODE == EM_GATES) {
;                 const int col = u.pn * 256 + ct; float w[8];
; #pragma unroll
;                 for (int j = 0; j < 8; ++j) w[j] = sigmoidf_(v[j] * rs) * 255.0f + 0.5f;
;                 u32x2 cd; cd.x = (unsigned)w[0] | ((unsigned)w[1] << 8) | ((unsigned)w[2] << 16) | ((unsigned)w[3] << 24); cd.y = (unsigned)w[4] | ((unsigned)w[5] << 8) | ((unsigned)w[6] << 16) | ((unsigned)w[7] << 24);
;                 *(u32x2*)(ws + WS_G8 + (size_t)row * 2048 + col) = cd;
	v_add_f32_e32 v65, 1.0, v66
	v_rcp_f32_e32 v73, v65
	v_add_f32_e32 v65, 1.0, v67
	v_pk_fma_f32 v[66:67], v[68:69], s[14:15], 0.5 op_sel_hi:[1,0,0]
	v_pk_fma_f32 v[68:69], v[70:71], s[14:15], 0.5 op_sel_hi:[1,0,0]
	v_rcp_f32_e32 v65, v65
	v_cvt_u32_f32_e32 v69, v69
	v_cvt_u32_f32_e32 v68, v68
	v_cvt_u32_f32_e32 v67, v67
	v_cvt_u32_f32_e32 v66, v66
	v_pk_fma_f32 v[70:71], v[72:73], s[14:15], 0.5 op_sel_hi:[1,0,0]
	v_lshlrev_b32_e32 v69, 8, v69
	v_lshlrev_b32_e32 v68, 8, v68
	v_pk_fma_f32 v[64:65], v[64:65], s[14:15], 0.5 op_sel_hi:[1,0,0]
	v_or_b32_e32 v67, v69, v67
	v_or_b32_e32 v66, v68, v66
	v_cvt_u32_f32_sdwa v68, v71 dst_sel:WORD_1 dst_unused:UNUSED_PAD src0_sel:DWORD
	v_cvt_u32_f32_sdwa v69, v70 dst_sel:WORD_1 dst_unused:UNUSED_PAD src0_sel:DWORD
	v_cvt_u32_f32_sdwa v65, v65 dst_sel:BYTE_3 dst_unused:UNUSED_PAD src0_sel:DWORD
	v_cvt_u32_f32_sdwa v64, v64 dst_sel:BYTE_3 dst_unused:UNUSED_PAD src0_sel:DWORD
	v_or_b32_e32 v67, v67, v68
	v_or_b32_e32 v66, v66, v69
	v_or_b32_e32 v65, v67, v65
	v_or_b32_e32 v64, v66, v64
	v_lshl_add_u64 v[66:67], s[92:93], 0, v[76:77]
	v_lshl_add_u64 v[66:67], v[66:67], 0, v[142:143]
	v_add_co_u32_e32 v66, vcc, s59, v66
	v_mul_f32_e32 v60, v60, v167
	s_nop 0
	v_addc_co_u32_e32 v67, vcc, 0, v67, vcc
	global_store_dwordx2 v[66:67], v[64:65], off offset:128
	v_exp_f32_e32 v64, v60
	v_mul_f32_e32 v60, v61, v167
	v_mul_f32_e32 v62, v62, v167
	v_exp_f32_e32 v65, v60
	v_exp_f32_e32 v66, v62
	v_mul_f32_e32 v62, v63, v167
	v_add_f32_e32 v65, 1.0, v65
	v_mul_f32_e32 v56, v56, v167
	v_exp_f32_e32 v63, v62
	v_rcp_f32_e32 v62, v65
	v_add_f32_e32 v65, 1.0, v66
	v_rcp_f32_e32 v66, v65
	v_exp_f32_e32 v65, v56
	v_mul_f32_e32 v56, v57, v167
	v_exp_f32_e32 v57, v56
	v_add_f32_e32 v63, 1.0, v63
	v_mul_f32_e32 v58, v58, v167
	v_rcp_f32_e32 v56, v63
	v_add_f32_e32 v63, 1.0, v65
	v_add_f32_e32 v57, 1.0, v57
	v_mul_f32_e32 v59, v59, v167
	v_add_f32_e32 v64, 1.0, v64
	v_rcp_f32_e32 v65, v63
	v_exp_f32_e32 v58, v58
	v_rcp_f32_e32 v63, v57
	v_rcp_f32_e32 v64, v64
	v_exp_f32_e32 v59, v59
	v_add_f32_e32 v57, 1.0, v58
	v_pk_fma_f32 v[62:63], v[62:63], s[14:15], 0.5 op_sel_hi:[1,0,0]
	v_rcp_f32_e32 v67, v57
	v_add_f32_e32 v57, 1.0, v59
	v_pk_fma_f32 v[58:59], v[64:65], s[14:15], 0.5 op_sel_hi:[1,0,0]
	v_cvt_u32_f32_e32 v63, v63
	v_cvt_u32_f32_e32 v62, v62
	v_rcp_f32_e32 v57, v57
	v_cvt_u32_f32_e32 v59, v59
	v_cvt_u32_f32_e32 v58, v58
	v_pk_fma_f32 v[64:65], v[66:67], s[14:15], 0.5 op_sel_hi:[1,0,0]
	v_lshlrev_b32_e32 v63, 8, v63
	v_lshlrev_b32_e32 v62, 8, v62
	v_pk_fma_f32 v[56:57], v[56:57], s[14:15], 0.5 op_sel_hi:[1,0,0]
	v_or_b32_e32 v59, v63, v59
	v_or_b32_e32 v58, v62, v58
	v_cvt_u32_f32_sdwa v62, v65 dst_sel:WORD_1 dst_unused:UNUSED_PAD src0_sel:DWORD
	v_cvt_u32_f32_sdwa v63, v64 dst_sel:WORD_1 dst_unused:UNUSED_PAD src0_sel:DWORD
	v_cvt_u32_f32_sdwa v57, v57 dst_sel:BYTE_3 dst_unused:UNUSED_PAD src0_sel:DWORD
	v_cvt_u32_f32_sdwa v56, v56 dst_sel:BYTE_3 dst_unused:UNUSED_PAD src0_sel:DWORD
	v_lshlrev_b64 v[60:61], 11, v[150:151]
	v_or_b32_e32 v59, v59, v62
	v_or_b32_e32 v58, v58, v63
	v_or_b32_e32 v57, v59, v57
	v_or_b32_e32 v56, v58, v56
	v_lshl_add_u64 v[58:59], s[12:13], 0, v[60:61]
	v_mul_f32_e32 v53, v53, v167
	v_mul_f32_e32 v54, v54, v167
	v_lshl_add_u64 v[58:59], v[58:59], 0, v[142:143]
	v_exp_f32_e32 v53, v53
	global_store_dwordx2 v[58:59], v[56:57], off
	v_exp_f32_e32 v56, v54
	v_mul_f32_e32 v54, v55, v167
	v_exp_f32_e32 v55, v54
	v_add_f32_e32 v53, 1.0, v53
	v_mul_f32_e32 v48, v48, v167
	v_rcp_f32_e32 v54, v53
	v_add_f32_e32 v53, 1.0, v56
	v_mul_f32_e32 v52, v52, v167
	v_rcp_f32_e32 v56, v53
	v_add_f32_e32 v53, 1.0, v55
	v_exp_f32_e32 v55, v48
	v_mul_f32_e32 v48, v49, v167
	v_exp_f32_e32 v52, v52
	v_exp_f32_e32 v49, v48
	v_mul_f32_e32 v50, v50, v167
	v_mul_f32_e32 v51, v51, v167
	v_add_f32_e32 v52, 1.0, v52
	v_rcp_f32_e32 v48, v53
	v_add_f32_e32 v53, 1.0, v55
	v_add_f32_e32 v49, 1.0, v49
	v_exp_f32_e32 v50, v50
	v_rcp_f32_e32 v52, v52
	v_rcp_f32_e32 v53, v53
	v_exp_f32_e32 v51, v51
	v_rcp_f32_e32 v55, v49
	v_add_f32_e32 v49, 1.0, v50
	v_rcp_f32_e32 v57, v49
	v_add_f32_e32 v49, 1.0, v51
	v_pk_fma_f32 v[50:51], v[52:53], s[14:15], 0.5 op_sel_hi:[1,0,0]
	v_pk_fma_f32 v[52:53], v[54:55], s[14:15], 0.5 op_sel_hi:[1,0,0]
	v_rcp_f32_e32 v49, v49
	v_cvt_u32_f32_e32 v53, v53
	v_cvt_u32_f32_e32 v52, v52
	v_cvt_u32_f32_e32 v51, v51
	v_cvt_u32_f32_e32 v50, v50
	v_pk_fma_f32 v[54:55], v[56:57], s[14:15], 0.5 op_sel_hi:[1,0,0]
	v_lshlrev_b32_e32 v53, 8, v53
	v_lshlrev_b32_e32 v52, 8, v52
	v_pk_fma_f32 v[48:49], v[48:49], s[14:15], 0.5 op_sel_hi:[1,0,0]
	v_or_b32_e32 v51, v53, v51
	v_or_b32_e32 v50, v52, v50
	v_cvt_u32_f32_sdwa v52, v55 dst_sel:WORD_1 dst_unused:UNUSED_PAD src0_sel:DWORD
	v_cvt_u32_f32_sdwa v53, v54 dst_sel:WORD_1 dst_unused:UNUSED_PAD src0_sel:DWORD
	v_cvt_u32_f32_sdwa v49, v49 dst_sel:BYTE_3 dst_unused:UNUSED_PAD src0_sel:DWORD
	v_cvt_u32_f32_sdwa v48, v48 dst_sel:BYTE_3 dst_unused:UNUSED_PAD src0_sel:DWORD
	v_or_b32_e32 v51, v51, v52
	v_or_b32_e32 v50, v50, v53
	v_or_b32_e32 v49, v51, v49
	v_or_b32_e32 v48, v50, v48
	v_lshl_add_u64 v[50:51], s[92:93], 0, v[60:61]
	v_lshl_add_u64 v[50:51], v[50:51], 0, v[142:143]
	v_add_co_u32_e32 v50, vcc, s59, v50
	v_mul_f32_e32 v44, v44, v166
	s_nop 0
	v_addc_co_u32_e32 v51, vcc, 0, v51, vcc
	global_store_dwordx2 v[50:51], v[48:49], off offset:128
	v_exp_f32_e32 v48, v44
	v_mul_f32_e32 v44, v45, v166
	v_mul_f32_e32 v46, v46, v166
	v_exp_f32_e32 v49, v44
	v_exp_f32_e32 v50, v46
	v_mul_f32_e32 v46, v47, v166
	v_add_f32_e32 v49, 1.0, v49
	v_mul_f32_e32 v40, v40, v166
	v_exp_f32_e32 v47, v46
	v_rcp_f32_e32 v46, v49
	v_add_f32_e32 v49, 1.0, v50
	v_rcp_f32_e32 v50, v49
; __device__ __forceinline__ float sigmoidf_(float z) { return __builtin_amdgcn_rcpf(1.0f + __builtin_amdgcn_exp2f(-1.4426950408889634f * z)); }
;     __device__ __forceinline__ float compute(const Pre& p, f32x4 (&acc)[2][2][4][2], const f32x4 (&cv)[2][2], const pg8::Unit& u, int ai, int m, int wr, int wc, int fr, int fq) const {
;     ...
;             } else if (MODE == EM_GATES) {
;                 const int col = u.pn * 256 + ct; float w[8];
; #pragma unroll
;                 for (int j = 0; j < 8; ++j) w[j] = sigmoidf_(v[j] * rs) * 255.0f + 0.5f;
;                 u32x2 cd; cd.x = (unsigned)w[0] | ((unsigned)w[1] << 8) | ((unsigned)w[2] << 16) | ((unsigned)w[3] << 24); cd.y = (unsigned)w[4] | ((unsigned)w[5] << 8) | ((unsigned)w[6] << 16) | ((unsigned)w[7] << 24);
;                 *(u32x2*)(ws + WS_G8 + (size_t)row * 2048 + col) = cd;
	v_exp_f32_e32 v49, v40
	v_mul_f32_e32 v40, v41, v166
	v_exp_f32_e32 v41, v40
	v_add_f32_e32 v47, 1.0, v47
	v_mul_f32_e32 v42, v42, v166
	v_rcp_f32_e32 v40, v47
	v_add_f32_e32 v47, 1.0, v49
	v_add_f32_e32 v41, 1.0, v41
	v_mul_f32_e32 v43, v43, v166
	v_add_f32_e32 v48, 1.0, v48
	v_rcp_f32_e32 v49, v47
	v_exp_f32_e32 v42, v42
	v_rcp_f32_e32 v47, v41
	v_rcp_f32_e32 v48, v48
	v_exp_f32_e32 v43, v43
	v_add_f32_e32 v41, 1.0, v42
	v_pk_fma_f32 v[46:47], v[46:47], s[14:15], 0.5 op_sel_hi:[1,0,0]
	v_rcp_f32_e32 v51, v41
	v_add_f32_e32 v41, 1.0, v43
	v_pk_fma_f32 v[42:43], v[48:49], s[14:15], 0.5 op_sel_hi:[1,0,0]
	v_cvt_u32_f32_e32 v47, v47
	v_cvt_u32_f32_e32 v46, v46
	v_rcp_f32_e32 v41, v41
	v_cvt_u32_f32_e32 v43, v43
	v_cvt_u32_f32_e32 v42, v42
	v_pk_fma_f32 v[48:49], v[50:51], s[14:15], 0.5 op_sel_hi:[1,0,0]
	v_lshlrev_b32_e32 v47, 8, v47
	v_lshlrev_b32_e32 v46, 8, v46
	v_pk_fma_f32 v[40:41], v[40:41], s[14:15], 0.5 op_sel_hi:[1,0,0]
	v_or_b32_e32 v43, v47, v43
	v_or_b32_e32 v42, v46, v42
	v_cvt_u32_f32_sdwa v46, v49 dst_sel:WORD_1 dst_unused:UNUSED_PAD src0_sel:DWORD
	v_cvt_u32_f32_sdwa v47, v48 dst_sel:WORD_1 dst_unused:UNUSED_PAD src0_sel:DWORD
	v_cvt_u32_f32_sdwa v41, v41 dst_sel:BYTE_3 dst_unused:UNUSED_PAD src0_sel:DWORD
	v_cvt_u32_f32_sdwa v40, v40 dst_sel:BYTE_3 dst_unused:UNUSED_PAD src0_sel:DWORD
	v_lshlrev_b64 v[44:45], 11, v[148:149]
	v_or_b32_e32 v43, v43, v46
	v_or_b32_e32 v42, v42, v47
	v_or_b32_e32 v41, v43, v41
	v_or_b32_e32 v40, v42, v40
	v_lshl_add_u64 v[42:43], s[12:13], 0, v[44:45]
	v_mul_f32_e32 v37, v37, v166
	v_mul_f32_e32 v38, v38, v166
	v_lshl_add_u64 v[42:43], v[42:43], 0, v[142:143]
	v_exp_f32_e32 v37, v37
	global_store_dwordx2 v[42:43], v[40:41], off
	v_exp_f32_e32 v40, v38
	v_mul_f32_e32 v38, v39, v166
	v_exp_f32_e32 v39, v38
	v_add_f32_e32 v37, 1.0, v37
	v_mul_f32_e32 v32, v32, v166
	v_rcp_f32_e32 v38, v37
	v_add_f32_e32 v37, 1.0, v40
	v_mul_f32_e32 v36, v36, v166
	v_rcp_f32_e32 v40, v37
	v_add_f32_e32 v37, 1.0, v39
	v_exp_f32_e32 v39, v32
	v_mul_f32_e32 v32, v33, v166
	v_exp_f32_e32 v36, v36
	v_exp_f32_e32 v33, v32
	v_mul_f32_e32 v34, v34, v166
	v_mul_f32_e32 v35, v35, v166
	v_add_f32_e32 v36, 1.0, v36
	v_rcp_f32_e32 v32, v37
	v_add_f32_e32 v37, 1.0, v39
	v_add_f32_e32 v33, 1.0, v33
	v_exp_f32_e32 v34, v34
	v_rcp_f32_e32 v36, v36
	v_rcp_f32_e32 v37, v37
	v_exp_f32_e32 v35, v35
	v_rcp_f32_e32 v39, v33
	v_add_f32_e32 v33, 1.0, v34
	v_rcp_f32_e32 v41, v33
	v_add_f32_e32 v33, 1.0, v35
	v_pk_fma_f32 v[34:35], v[36:37], s[14:15], 0.5 op_sel_hi:[1,0,0]
	v_pk_fma_f32 v[36:37], v[38:39], s[14:15], 0.5 op_sel_hi:[1,0,0]
	v_rcp_f32_e32 v33, v33
	v_cvt_u32_f32_e32 v37, v37
	v_cvt_u32_f32_e32 v36, v36
	v_cvt_u32_f32_e32 v35, v35
	v_cvt_u32_f32_e32 v34, v34
	v_pk_fma_f32 v[38:39], v[40:41], s[14:15], 0.5 op_sel_hi:[1,0,0]
	v_lshlrev_b32_e32 v37, 8, v37
	v_lshlrev_b32_e32 v36, 8, v36
	v_pk_fma_f32 v[32:33], v[32:33], s[14:15], 0.5 op_sel_hi:[1,0,0]
	v_or_b32_e32 v35, v37, v35
	v_or_b32_e32 v34, v36, v34
	v_cvt_u32_f32_sdwa v36, v39 dst_sel:WORD_1 dst_unused:UNUSED_PAD src0_sel:DWORD
	v_cvt_u32_f32_sdwa v37, v38 dst_sel:WORD_1 dst_unused:UNUSED_PAD src0_sel:DWORD
	v_cvt_u32_f32_sdwa v33, v33 dst_sel:BYTE_3 dst_unused:UNUSED_PAD src0_sel:DWORD
	v_cvt_u32_f32_sdwa v32, v32 dst_sel:BYTE_3 dst_unused:UNUSED_PAD src0_sel:DWORD
	v_or_b32_e32 v35, v35, v36
	v_or_b32_e32 v34, v34, v37
	v_or_b32_e32 v33, v35, v33
	v_or_b32_e32 v32, v34, v32
	v_lshl_add_u64 v[34:35], s[92:93], 0, v[44:45]
	v_lshl_add_u64 v[34:35], v[34:35], 0, v[142:143]
	v_add_co_u32_e32 v34, vcc, s59, v34
	v_mul_f32_e32 v28, v28, v165
	s_nop 0
	v_addc_co_u32_e32 v35, vcc, 0, v35, vcc
	global_store_dwordx2 v[34:35], v[32:33], off offset:128
	v_exp_f32_e32 v32, v28
	v_mul_f32_e32 v28, v29, v165
	v_mul_f32_e32 v30, v30, v165
	v_exp_f32_e32 v33, v28
	v_exp_f32_e32 v34, v30
	v_mul_f32_e32 v30, v31, v165
	v_add_f32_e32 v33, 1.0, v33
	v_mul_f32_e32 v24, v24, v165
	v_exp_f32_e32 v31, v30
	v_rcp_f32_e32 v30, v33
	v_add_f32_e32 v33, 1.0, v34
	v_rcp_f32_e32 v34, v33
	v_exp_f32_e32 v33, v24
	v_mul_f32_e32 v24, v25, v165
	v_exp_f32_e32 v25, v24
	v_add_f32_e32 v31, 1.0, v31
	v_mul_f32_e32 v26, v26, v165
	v_rcp_f32_e32 v24, v31
	v_add_f32_e32 v31, 1.0, v33
	v_add_f32_e32 v25, 1.0, v25
	v_mul_f32_e32 v27, v27, v165
	v_add_f32_e32 v32, 1.0, v32
	v_rcp_f32_e32 v33, v31
	v_exp_f32_e32 v26, v26
	v_rcp_f32_e32 v31, v25
	v_rcp_f32_e32 v32, v32
	v_exp_f32_e32 v27, v27
	v_add_f32_e32 v25, 1.0, v26
	v_pk_fma_f32 v[30:31], v[30:31], s[14:15], 0.5 op_sel_hi:[1,0,0]
	v_rcp_f32_e32 v35, v25
	v_add_f32_e32 v25, 1.0, v27
	v_pk_fma_f32 v[26:27], v[32:33], s[14:15], 0.5 op_sel_hi:[1,0,0]
	v_cvt_u32_f32_e32 v31, v31
	v_cvt_u32_f32_e32 v30, v30
	v_rcp_f32_e32 v25, v25
	v_cvt_u32_f32_e32 v27, v27
	v_cvt_u32_f32_e32 v26, v26
	v_pk_fma_f32 v[32:33], v[34:35], s[14:15], 0.5 op_sel_hi:[1,0,0]
	v_lshlrev_b32_e32 v31, 8, v31
	v_lshlrev_b32_e32 v30, 8, v30
	v_pk_fma_f32 v[24:25], v[24:25], s[14:15], 0.5 op_sel_hi:[1,0,0]
	v_or_b32_e32 v27, v31, v27
	v_or_b32_e32 v26, v30, v26
	v_cvt_u32_f32_sdwa v30, v33 dst_sel:WORD_1 dst_unused:UNUSED_PAD src0_sel:DWORD
	v_cvt_u32_f32_sdwa v31, v32 dst_sel:WORD_1 dst_unused:UNUSED_PAD src0_sel:DWORD
	v_cvt_u32_f32_sdwa v25, v25 dst_sel:BYTE_3 dst_unused:UNUSED_PAD src0_sel:DWORD
	v_cvt_u32_f32_sdwa v24, v24 dst_sel:BYTE_3 dst_unused:UNUSED_PAD src0_sel:DWORD
	v_lshlrev_b64 v[28:29], 11, v[146:147]
	v_or_b32_e32 v27, v27, v30
	v_or_b32_e32 v26, v26, v31
	v_or_b32_e32 v25, v27, v25
	v_or_b32_e32 v24, v26, v24
	v_lshl_add_u64 v[26:27], s[12:13], 0, v[28:29]
	v_mul_f32_e32 v21, v21, v165
	v_mul_f32_e32 v22, v22, v165
	v_lshl_add_u64 v[26:27], v[26:27], 0, v[142:143]
; __device__ __forceinline__ float sigmoidf_(float z) { return __builtin_amdgcn_rcpf(1.0f + __builtin_amdgcn_exp2f(-1.4426950408889634f * z)); }
; #define PG8_BAR __builtin_amdgcn_s_barrier()
; template <class Epi, class Sched>
; __device__ __forceinline__ void gemm_phase(LAS unsigned char* lds, const Gemm g, const Sched& S, const Epi& E, int wave_id) {
;     ...
;         if (!has_next) break;
; #pragma unroll
;         for (int a = 0; a < 2; ++a)
; #pragma unroll
;             for (int b = 0; b < 2; ++b)
; #pragma unroll
;                 for (int m = 0; m < 4; ++m)
; #pragma unroll
;                     for (int n = 0; n < 2; ++n) acc[a][b][m][n] = (f32x4){0.f, 0.f, 0.f, 0.f};
;         cur = nxt; cA = nA; cB = nB; ++ui;
;         if (wr == 1) PG8_BAR;
;     __device__ __forceinline__ float compute(const Pre& p, f32x4 (&acc)[2][2][4][2], const f32x4 (&cv)[2][2], const pg8::Unit& u, int ai, int m, int wr, int wc, int fr, int fq) const {
;     ...
;             } else if (MODE == EM_GATES) {
;                 const int col = u.pn * 256 + ct; float w[8];
; #pragma unroll
;                 for (int j = 0; j < 8; ++j) w[j] = sigmoidf_(v[j] * rs) * 255.0f + 0.5f;
;                 u32x2 cd; cd.x = (unsigned)w[0] | ((unsigned)w[1] << 8) | ((unsigned)w[2] << 16) | ((unsigned)w[3] << 24); cd.y = (unsigned)w[4] | ((unsigned)w[5] << 8) | ((unsigned)w[6] << 16) | ((unsigned)w[7] << 24);
;                 *(u32x2*)(ws + WS_G8 + (size_t)row * 2048 + col) = cd;
	v_exp_f32_e32 v21, v21
	global_store_dwordx2 v[26:27], v[24:25], off
	v_exp_f32_e32 v24, v22
	v_mul_f32_e32 v22, v23, v165
	v_exp_f32_e32 v23, v22
	v_add_f32_e32 v21, 1.0, v21
	v_mul_f32_e32 v16, v16, v165
	v_rcp_f32_e32 v22, v21
	v_add_f32_e32 v21, 1.0, v24
	v_mul_f32_e32 v20, v20, v165
	v_rcp_f32_e32 v24, v21
	v_add_f32_e32 v21, 1.0, v23
	v_exp_f32_e32 v23, v16
	v_mul_f32_e32 v16, v17, v165
	v_exp_f32_e32 v20, v20
	v_exp_f32_e32 v17, v16
	v_mul_f32_e32 v18, v18, v165
	v_mul_f32_e32 v19, v19, v165
	v_add_f32_e32 v20, 1.0, v20
	v_rcp_f32_e32 v16, v21
	v_add_f32_e32 v21, 1.0, v23
	v_add_f32_e32 v17, 1.0, v17
	v_exp_f32_e32 v18, v18
	v_rcp_f32_e32 v20, v20
	v_rcp_f32_e32 v21, v21
	v_exp_f32_e32 v19, v19
	v_rcp_f32_e32 v23, v17
	v_add_f32_e32 v17, 1.0, v18
	v_rcp_f32_e32 v25, v17
	v_add_f32_e32 v17, 1.0, v19
	v_pk_fma_f32 v[18:19], v[20:21], s[14:15], 0.5 op_sel_hi:[1,0,0]
	v_pk_fma_f32 v[20:21], v[22:23], s[14:15], 0.5 op_sel_hi:[1,0,0]
	v_rcp_f32_e32 v17, v17
	v_cvt_u32_f32_e32 v21, v21
	v_cvt_u32_f32_e32 v20, v20
	v_cvt_u32_f32_e32 v19, v19
	v_cvt_u32_f32_e32 v18, v18
	v_pk_fma_f32 v[22:23], v[24:25], s[14:15], 0.5 op_sel_hi:[1,0,0]
	v_lshlrev_b32_e32 v21, 8, v21
	v_lshlrev_b32_e32 v20, 8, v20
	v_pk_fma_f32 v[16:17], v[16:17], s[14:15], 0.5 op_sel_hi:[1,0,0]
	v_or_b32_e32 v19, v21, v19
	v_or_b32_e32 v18, v20, v18
	v_cvt_u32_f32_sdwa v20, v23 dst_sel:WORD_1 dst_unused:UNUSED_PAD src0_sel:DWORD
	v_cvt_u32_f32_sdwa v21, v22 dst_sel:WORD_1 dst_unused:UNUSED_PAD src0_sel:DWORD
	v_cvt_u32_f32_sdwa v17, v17 dst_sel:BYTE_3 dst_unused:UNUSED_PAD src0_sel:DWORD
	v_cvt_u32_f32_sdwa v16, v16 dst_sel:BYTE_3 dst_unused:UNUSED_PAD src0_sel:DWORD
	v_or_b32_e32 v19, v19, v20
	v_or_b32_e32 v18, v18, v21
	v_or_b32_e32 v17, v19, v17
	v_or_b32_e32 v16, v18, v16
	v_lshl_add_u64 v[18:19], s[92:93], 0, v[28:29]
	v_lshl_add_u64 v[18:19], v[18:19], 0, v[142:143]
	v_add_co_u32_e32 v18, vcc, s59, v18
	v_mul_f32_e32 v12, v12, v164
	s_nop 0
	v_addc_co_u32_e32 v19, vcc, 0, v19, vcc
	global_store_dwordx2 v[18:19], v[16:17], off offset:128
	v_exp_f32_e32 v16, v12
	v_mul_f32_e32 v12, v13, v164
	v_mul_f32_e32 v14, v14, v164
	v_exp_f32_e32 v17, v12
	v_exp_f32_e32 v18, v14
	v_mul_f32_e32 v14, v15, v164
	v_add_f32_e32 v17, 1.0, v17
	v_mul_f32_e32 v8, v8, v164
	v_exp_f32_e32 v15, v14
	v_rcp_f32_e32 v14, v17
	v_add_f32_e32 v17, 1.0, v18
	v_rcp_f32_e32 v18, v17
	v_exp_f32_e32 v17, v8
	v_mul_f32_e32 v8, v9, v164
	v_exp_f32_e32 v9, v8
	v_add_f32_e32 v15, 1.0, v15
	v_mul_f32_e32 v10, v10, v164
	v_rcp_f32_e32 v8, v15
	v_add_f32_e32 v15, 1.0, v17
	v_add_f32_e32 v9, 1.0, v9
	v_mul_f32_e32 v11, v11, v164
	v_add_f32_e32 v16, 1.0, v16
	v_rcp_f32_e32 v17, v15
	v_exp_f32_e32 v10, v10
	v_rcp_f32_e32 v15, v9
	v_rcp_f32_e32 v16, v16
	v_exp_f32_e32 v11, v11
	v_add_f32_e32 v9, 1.0, v10
	v_pk_fma_f32 v[14:15], v[14:15], s[14:15], 0.5 op_sel_hi:[1,0,0]
	v_rcp_f32_e32 v19, v9
	v_add_f32_e32 v9, 1.0, v11
	v_pk_fma_f32 v[10:11], v[16:17], s[14:15], 0.5 op_sel_hi:[1,0,0]
	v_cvt_u32_f32_e32 v15, v15
	v_cvt_u32_f32_e32 v14, v14
	v_rcp_f32_e32 v9, v9
	v_cvt_u32_f32_e32 v11, v11
	v_cvt_u32_f32_e32 v10, v10
	v_pk_fma_f32 v[16:17], v[18:19], s[14:15], 0.5 op_sel_hi:[1,0,0]
	v_lshlrev_b32_e32 v15, 8, v15
	v_lshlrev_b32_e32 v14, 8, v14
	v_pk_fma_f32 v[8:9], v[8:9], s[14:15], 0.5 op_sel_hi:[1,0,0]
	v_or_b32_e32 v11, v15, v11
	v_or_b32_e32 v10, v14, v10
	v_cvt_u32_f32_sdwa v14, v17 dst_sel:WORD_1 dst_unused:UNUSED_PAD src0_sel:DWORD
	v_cvt_u32_f32_sdwa v15, v16 dst_sel:WORD_1 dst_unused:UNUSED_PAD src0_sel:DWORD
	v_cvt_u32_f32_sdwa v9, v9 dst_sel:BYTE_3 dst_unused:UNUSED_PAD src0_sel:DWORD
	v_cvt_u32_f32_sdwa v8, v8 dst_sel:BYTE_3 dst_unused:UNUSED_PAD src0_sel:DWORD
	v_lshlrev_b64 v[12:13], 11, v[144:145]
	v_or_b32_e32 v11, v11, v14
	v_or_b32_e32 v10, v10, v15
	v_or_b32_e32 v9, v11, v9
	v_or_b32_e32 v8, v10, v8
	v_lshl_add_u64 v[10:11], s[12:13], 0, v[12:13]
	v_mul_f32_e32 v5, v5, v164
	v_mul_f32_e32 v6, v6, v164
	v_lshl_add_u64 v[10:11], v[10:11], 0, v[142:143]
	v_exp_f32_e32 v5, v5
	global_store_dwordx2 v[10:11], v[8:9], off
	v_exp_f32_e32 v8, v6
	v_mul_f32_e32 v6, v7, v164
	v_exp_f32_e32 v7, v6
	v_add_f32_e32 v5, 1.0, v5
	v_mul_f32_e32 v0, v0, v164
	v_rcp_f32_e32 v6, v5
	v_add_f32_e32 v5, 1.0, v8
	v_mul_f32_e32 v4, v4, v164
	v_rcp_f32_e32 v8, v5
	v_add_f32_e32 v5, 1.0, v7
	v_exp_f32_e32 v7, v0
	v_mul_f32_e32 v0, v1, v164
	v_exp_f32_e32 v4, v4
	v_exp_f32_e32 v1, v0
	v_mul_f32_e32 v2, v2, v164
	v_mul_f32_e32 v3, v3, v164
	v_add_f32_e32 v4, 1.0, v4
	v_rcp_f32_e32 v0, v5
	v_add_f32_e32 v5, 1.0, v7
	v_add_f32_e32 v1, 1.0, v1
	v_exp_f32_e32 v2, v2
	v_rcp_f32_e32 v4, v4
	v_rcp_f32_e32 v5, v5
	v_exp_f32_e32 v3, v3
	v_rcp_f32_e32 v7, v1
	v_add_f32_e32 v1, 1.0, v2
	v_rcp_f32_e32 v9, v1
	v_add_f32_e32 v1, 1.0, v3
	v_pk_fma_f32 v[2:3], v[4:5], s[14:15], 0.5 op_sel_hi:[1,0,0]
	v_pk_fma_f32 v[4:5], v[6:7], s[14:15], 0.5 op_sel_hi:[1,0,0]
	v_rcp_f32_e32 v1, v1
	v_cvt_u32_f32_e32 v5, v5
	v_cvt_u32_f32_e32 v4, v4
	v_cvt_u32_f32_e32 v3, v3
	v_cvt_u32_f32_e32 v2, v2
	v_pk_fma_f32 v[6:7], v[8:9], s[14:15], 0.5 op_sel_hi:[1,0,0]
	v_lshlrev_b32_e32 v5, 8, v5
	v_lshlrev_b32_e32 v4, 8, v4
	v_pk_fma_f32 v[0:1], v[0:1], s[14:15], 0.5 op_sel_hi:[1,0,0]
	v_or_b32_e32 v3, v5, v3
	v_or_b32_e32 v2, v4, v2
	v_cvt_u32_f32_sdwa v4, v7 dst_sel:WORD_1 dst_unused:UNUSED_PAD src0_sel:DWORD
	v_cvt_u32_f32_sdwa v5, v6 dst_sel:WORD_1 dst_unused:UNUSED_PAD src0_sel:DWORD
	v_cvt_u32_f32_sdwa v1, v1 dst_sel:BYTE_3 dst_unused:UNUSED_PAD src0_sel:DWORD
	v_cvt_u32_f32_sdwa v0, v0 dst_sel:BYTE_3 dst_unused:UNUSED_PAD src0_sel:DWORD
	v_or_b32_e32 v3, v3, v4
	v_or_b32_e32 v2, v2, v5
	v_or_b32_e32 v1, v3, v1
	v_or_b32_e32 v0, v2, v0
	v_lshl_add_u64 v[2:3], s[92:93], 0, v[12:13]
	v_lshl_add_u64 v[2:3], v[2:3], 0, v[142:143]
	v_add_co_u32_e32 v2, vcc, 0xb400000, v2
	s_nop 1
	v_addc_co_u32_e32 v3, vcc, 0, v3, vcc
	s_andn2_b64 vcc, exec, s[24:25]
	s_mov_b64 s[24:25], -1
	global_store_dwordx2 v[2:3], v[0:1], off offset:128
	s_cbranch_vccnz .LBB0_664
	s_andn2_b64 vcc, exec, s[4:5]
	s_cbranch_vccnz .LBB0_663
	s_barrier
	s_branch .LBB0_663

; __device__ __forceinline__ float sigmoidf_(float z) { return __builtin_amdgcn_rcpf(1.0f + __builtin_amdgcn_exp2f(-1.4426950408889634f * z)); }
;     __device__ __forceinline__ void load(Pre& p, const pg8::Unit& u, int ai, int m, int wr, int wc, int fr, int fq) const {
;         const int row = u.pm * 256 + ai * 128 + wr * 64 + m * 16 + fr;
;         if (MODE == EM_PROJ || MODE == EM_GATES) p.rs = ((const float*)(ws + WS_RINV0))[row];
;     __device__ __forceinline__ float compute(const Pre& p, f32x4 (&acc)[2][2][4][2], const f32x4 (&cv)[2][2], const pg8::Unit& u, int ai, int m, int wr, int wc, int fr, int fq) const {
;     ...
;             } else if (MODE == EM_GATES) {
;                 const int col = u.pn * 256 + ct; float w[8];
; #pragma unroll
;                 for (int j = 0; j < 8; ++j) w[j] = sigmoidf_(v[j] * rs) * 255.0f + 0.5f;
;                 u32x2 cd; cd.x = (unsigned)w[0] | ((unsigned)w[1] << 8) | ((unsigned)w[2] << 16) | ((unsigned)w[3] << 24); cd.y = (unsigned)w[4] | ((unsigned)w[5] << 8) | ((unsigned)w[6] << 16) | ((unsigned)w[7] << 24);
;                 *(u32x2*)(ws + WS_G8 + (size_t)row * 2048 + col) = cd;
.LBB0_731:
	v_lshl_add_u32 v164, s28, 8, v158
	v_ashrrev_i32_e32 v165, 31, v164
	v_lshl_add_u64 v[142:143], v[164:165], 2, s[10:11]
	global_load_dword v182, v[142:143], off
	v_or_b32_e32 v156, 16, v164
	v_or_b32_e32 v154, 32, v164
	v_or_b32_e32 v152, 48, v164
	v_add_u32_e32 v150, 0x80, v164
	v_add_u32_e32 v148, 0x90, v164
	v_add_u32_e32 v146, 0xa0, v164
	v_add_u32_e32 v144, 0xb0, v164
	v_ashrrev_i32_e32 v157, 31, v156
	v_ashrrev_i32_e32 v155, 31, v154
	v_ashrrev_i32_e32 v153, 31, v152
	v_ashrrev_i32_e32 v151, 31, v150
	v_ashrrev_i32_e32 v149, 31, v148
	v_ashrrev_i32_e32 v147, 31, v146
	v_ashrrev_i32_e32 v145, 31, v144
	v_lshlrev_b64 v[170:171], 11, v[164:165]
	v_lshl_add_u64 v[164:165], v[156:157], 2, s[10:11]
	v_lshl_add_u64 v[166:167], v[154:155], 2, s[10:11]
	v_lshl_add_u64 v[168:169], v[152:153], 2, s[10:11]
	v_lshl_add_u64 v[172:173], v[150:151], 2, s[10:11]
	v_lshl_add_u64 v[174:175], v[148:149], 2, s[10:11]
	v_lshl_add_u64 v[176:177], v[146:147], 2, s[10:11]
	v_lshl_add_u64 v[178:179], v[144:145], 2, s[10:11]
	global_load_dword v183, v[164:165], off
	global_load_dword v184, v[166:167], off
	s_nop 0
	global_load_dword v168, v[168:169], off
	s_nop 0
	global_load_dword v167, v[172:173], off
	global_load_dword v166, v[174:175], off
	global_load_dword v165, v[176:177], off
	global_load_dword v164, v[178:179], off
	v_lshl_or_b32 v142, s58, 8, v160
	v_ashrrev_i32_e32 v143, 31, v142
	v_lshl_add_u64 v[180:181], s[12:13], 0, v[170:171]
	v_lshl_add_u64 v[172:173], v[180:181], 0, v[142:143]
	v_readlane_b32 s66, v255, 7
	v_readlane_b32 s67, v255, 8
	s_waitcnt vmcnt(0)
	v_mul_f32_e32 v182, 0xbfb8aa3b, v182
	v_mul_f32_e32 v183, 0xbfb8aa3b, v183
	v_mul_f32_e32 v184, 0xbfb8aa3b, v184
	v_mul_f32_e32 v168, 0xbfb8aa3b, v168
	v_mul_f32_e32 v167, 0xbfb8aa3b, v167
	v_mul_f32_e32 v166, 0xbfb8aa3b, v166
	v_mul_f32_e32 v165, 0xbfb8aa3b, v165
	v_mul_f32_e32 v164, 0xbfb8aa3b, v164
	v_mul_f32_e32 v125, v125, v182
	v_mul_f32_e32 v121, v121, v182
	v_mul_f32_e32 v124, v124, v182
	v_mul_f32_e32 v126, v126, v182
	v_mul_f32_e32 v120, v120, v182
	v_exp_f32_e32 v125, v125
	v_exp_f32_e32 v121, v121
	v_mul_f32_e32 v127, v127, v182
	v_mul_f32_e32 v122, v122, v182
	v_exp_f32_e32 v124, v124
	v_exp_f32_e32 v126, v126
	v_exp_f32_e32 v120, v120
	v_mul_f32_e32 v123, v123, v182
	v_mul_f32_e32 v117, v117, v182
	v_mul_f32_e32 v116, v116, v182
	v_exp_f32_e32 v127, v127
	v_exp_f32_e32 v122, v122
	v_exp_f32_e32 v123, v123
	v_exp_f32_e32 v174, v117
	v_add_f32_e32 v117, 1.0, v125
	v_add_f32_e32 v121, 1.0, v121
	v_exp_f32_e32 v169, v116
	v_add_f32_e32 v116, 1.0, v124
	v_add_f32_e32 v124, 1.0, v126
	v_add_f32_e32 v126, 1.0, v120
	v_rcp_f32_e32 v120, v117
	v_rcp_f32_e32 v121, v121
	v_rcp_f32_e32 v116, v116
	v_rcp_f32_e32 v117, v126
	v_add_f32_e32 v125, 1.0, v127
	v_add_f32_e32 v127, 1.0, v122
	v_add_f32_e32 v175, 1.0, v123
	v_rcp_f32_e32 v122, v124
	v_rcp_f32_e32 v123, v127
	v_rcp_f32_e32 v124, v125
	v_rcp_f32_e32 v125, v175
	v_pk_fma_f32 v[120:121], v[120:121], s[14:15], 0.5 op_sel_hi:[1,0,0]
	v_pk_fma_f32 v[116:117], v[116:117], s[14:15], 0.5 op_sel_hi:[1,0,0]
	v_cvt_u32_f32_e32 v120, v120
	v_cvt_u32_f32_e32 v116, v116
	v_cvt_u32_f32_e32 v121, v121
	v_pk_fma_f32 v[122:123], v[122:123], s[14:15], 0.5 op_sel_hi:[1,0,0]
	v_cvt_u32_f32_e32 v117, v117
	v_pk_fma_f32 v[124:125], v[124:125], s[14:15], 0.5 op_sel_hi:[1,0,0]
	v_cvt_u32_f32_sdwa v122, v122 dst_sel:WORD_1 dst_unused:UNUSED_PAD src0_sel:DWORD
	v_cvt_u32_f32_sdwa v123, v123 dst_sel:WORD_1 dst_unused:UNUSED_PAD src0_sel:DWORD
	v_mul_f32_e32 v118, v118, v182
	v_cvt_u32_f32_sdwa v124, v124 dst_sel:BYTE_3 dst_unused:UNUSED_PAD src0_sel:DWORD
	v_cvt_u32_f32_sdwa v125, v125 dst_sel:BYTE_3 dst_unused:UNUSED_PAD src0_sel:DWORD
	v_lshlrev_b32_e32 v120, 8, v120
	v_lshlrev_b32_e32 v121, 8, v121
	v_or_b32_e32 v116, v120, v116
	v_exp_f32_e32 v120, v118
	v_mul_f32_e32 v118, v119, v182
	v_or_b32_e32 v117, v121, v117
	v_or_b32_e32 v117, v117, v123
	v_or_b32_e32 v116, v116, v122
	v_exp_f32_e32 v119, v118
	v_or_b32_e32 v117, v117, v125
	v_or_b32_e32 v116, v116, v124
	global_store_dwordx2 v[172:173], v[116:117], off
	v_add_f32_e32 v117, 1.0, v174
	v_mul_f32_e32 v112, v112, v182
	v_rcp_f32_e32 v118, v117
	v_add_f32_e32 v117, 1.0, v120
	v_rcp_f32_e32 v120, v117
	v_add_f32_e32 v117, 1.0, v119
	v_exp_f32_e32 v119, v112
	v_mul_f32_e32 v112, v113, v182
	v_exp_f32_e32 v113, v112
	v_mul_f32_e32 v114, v114, v182
	v_mul_f32_e32 v115, v115, v182
	v_add_f32_e32 v116, 1.0, v169
	v_rcp_f32_e32 v112, v117
	v_add_f32_e32 v117, 1.0, v119
	v_add_f32_e32 v113, 1.0, v113
	v_exp_f32_e32 v114, v114
	v_rcp_f32_e32 v116, v116
	v_rcp_f32_e32 v117, v117
	v_exp_f32_e32 v115, v115
	v_rcp_f32_e32 v119, v113
	v_add_f32_e32 v113, 1.0, v114
	v_rcp_f32_e32 v121, v113
	v_add_f32_e32 v113, 1.0, v115
	v_pk_fma_f32 v[114:115], v[116:117], s[14:15], 0.5 op_sel_hi:[1,0,0]
	v_pk_fma_f32 v[116:117], v[118:119], s[14:15], 0.5 op_sel_hi:[1,0,0]
	v_rcp_f32_e32 v113, v113
	v_cvt_u32_f32_e32 v117, v117
	v_cvt_u32_f32_e32 v116, v116
	v_cvt_u32_f32_e32 v115, v115
	v_cvt_u32_f32_e32 v114, v114
	v_pk_fma_f32 v[118:119], v[120:121], s[14:15], 0.5 op_sel_hi:[1,0,0]
	v_lshlrev_b32_e32 v117, 8, v117
	v_lshlrev_b32_e32 v116, 8, v116
	v_pk_fma_f32 v[112:113], v[112:113], s[14:15], 0.5 op_sel_hi:[1,0,0]
	v_or_b32_e32 v115, v117, v115
	v_or_b32_e32 v114, v116, v114
	v_cvt_u32_f32_sdwa v116, v119 dst_sel:WORD_1 dst_unused:UNUSED_PAD src0_sel:DWORD
	v_cvt_u32_f32_sdwa v117, v118 dst_sel:WORD_1 dst_unused:UNUSED_PAD src0_sel:DWORD
	v_cvt_u32_f32_sdwa v113, v113 dst_sel:BYTE_3 dst_unused:UNUSED_PAD src0_sel:DWORD
	v_cvt_u32_f32_sdwa v112, v112 dst_sel:BYTE_3 dst_unused:UNUSED_PAD src0_sel:DWORD
; __device__ __forceinline__ float sigmoidf_(float z) { return __builtin_amdgcn_rcpf(1.0f + __builtin_amdgcn_exp2f(-1.4426950408889634f * z)); }
;     __device__ __forceinline__ float compute(const Pre& p, f32x4 (&acc)[2][2][4][2], const f32x4 (&cv)[2][2], const pg8::Unit& u, int ai, int m, int wr, int wc, int fr, int fq) const {
;     ...
;             } else if (MODE == EM_GATES) {
;                 const int col = u.pn * 256 + ct; float w[8];
; #pragma unroll
;                 for (int j = 0; j < 8; ++j) w[j] = sigmoidf_(v[j] * rs) * 255.0f + 0.5f;
;                 u32x2 cd; cd.x = (unsigned)w[0] | ((unsigned)w[1] << 8) | ((unsigned)w[2] << 16) | ((unsigned)w[3] << 24); cd.y = (unsigned)w[4] | ((unsigned)w[5] << 8) | ((unsigned)w[6] << 16) | ((unsigned)w[7] << 24);
;                 *(u32x2*)(ws + WS_G8 + (size_t)row * 2048 + col) = cd;
	v_or_b32_e32 v115, v115, v116
	v_or_b32_e32 v114, v114, v117
	v_or_b32_e32 v113, v115, v113
	v_or_b32_e32 v112, v114, v112
	v_lshl_add_u64 v[114:115], s[92:93], 0, v[170:171]
	v_lshl_add_u64 v[114:115], v[114:115], 0, v[142:143]
	v_add_co_u32_e32 v114, vcc, s55, v114
	v_mul_f32_e32 v108, v108, v183
	s_nop 0
	v_addc_co_u32_e32 v115, vcc, 0, v115, vcc
	global_store_dwordx2 v[114:115], v[112:113], off offset:128
	v_exp_f32_e32 v112, v108
	v_mul_f32_e32 v108, v109, v183
	v_mul_f32_e32 v110, v110, v183
	v_exp_f32_e32 v113, v108
	v_exp_f32_e32 v114, v110
	v_mul_f32_e32 v110, v111, v183
	v_add_f32_e32 v113, 1.0, v113
	v_mul_f32_e32 v104, v104, v183
	v_exp_f32_e32 v111, v110
	v_rcp_f32_e32 v110, v113
	v_add_f32_e32 v113, 1.0, v114
	v_rcp_f32_e32 v114, v113
	v_exp_f32_e32 v113, v104
	v_mul_f32_e32 v104, v105, v183
	v_exp_f32_e32 v105, v104
	v_add_f32_e32 v111, 1.0, v111
	v_mul_f32_e32 v106, v106, v183
	v_rcp_f32_e32 v104, v111
	v_add_f32_e32 v111, 1.0, v113
	v_add_f32_e32 v105, 1.0, v105
	v_mul_f32_e32 v107, v107, v183
	v_add_f32_e32 v112, 1.0, v112
	v_rcp_f32_e32 v113, v111
	v_exp_f32_e32 v106, v106
	v_rcp_f32_e32 v111, v105
	v_rcp_f32_e32 v112, v112
	v_exp_f32_e32 v107, v107
	v_add_f32_e32 v105, 1.0, v106
	v_pk_fma_f32 v[110:111], v[110:111], s[14:15], 0.5 op_sel_hi:[1,0,0]
	v_rcp_f32_e32 v115, v105
	v_add_f32_e32 v105, 1.0, v107
	v_pk_fma_f32 v[106:107], v[112:113], s[14:15], 0.5 op_sel_hi:[1,0,0]
	v_cvt_u32_f32_e32 v111, v111
	v_cvt_u32_f32_e32 v110, v110
	v_rcp_f32_e32 v105, v105
	v_cvt_u32_f32_e32 v107, v107
	v_cvt_u32_f32_e32 v106, v106
	v_pk_fma_f32 v[112:113], v[114:115], s[14:15], 0.5 op_sel_hi:[1,0,0]
	v_lshlrev_b32_e32 v111, 8, v111
	v_lshlrev_b32_e32 v110, 8, v110
	v_pk_fma_f32 v[104:105], v[104:105], s[14:15], 0.5 op_sel_hi:[1,0,0]
	v_or_b32_e32 v107, v111, v107
	v_or_b32_e32 v106, v110, v106
	v_cvt_u32_f32_sdwa v110, v113 dst_sel:WORD_1 dst_unused:UNUSED_PAD src0_sel:DWORD
	v_cvt_u32_f32_sdwa v111, v112 dst_sel:WORD_1 dst_unused:UNUSED_PAD src0_sel:DWORD
	v_cvt_u32_f32_sdwa v105, v105 dst_sel:BYTE_3 dst_unused:UNUSED_PAD src0_sel:DWORD
	v_cvt_u32_f32_sdwa v104, v104 dst_sel:BYTE_3 dst_unused:UNUSED_PAD src0_sel:DWORD
	v_lshlrev_b64 v[108:109], 11, v[156:157]
	v_or_b32_e32 v107, v107, v110
	v_or_b32_e32 v106, v106, v111
	v_or_b32_e32 v105, v107, v105
	v_or_b32_e32 v104, v106, v104
	v_lshl_add_u64 v[106:107], s[12:13], 0, v[108:109]
	v_mul_f32_e32 v101, v101, v183
	v_mul_f32_e32 v102, v102, v183
	v_lshl_add_u64 v[106:107], v[106:107], 0, v[142:143]
	v_exp_f32_e32 v101, v101
	global_store_dwordx2 v[106:107], v[104:105], off
	v_exp_f32_e32 v104, v102
	v_mul_f32_e32 v102, v103, v183
	v_exp_f32_e32 v103, v102
	v_add_f32_e32 v101, 1.0, v101
	v_mul_f32_e32 v96, v96, v183
	v_rcp_f32_e32 v102, v101
	v_add_f32_e32 v101, 1.0, v104
	v_mul_f32_e32 v100, v100, v183
	v_rcp_f32_e32 v104, v101
	v_add_f32_e32 v101, 1.0, v103
	v_exp_f32_e32 v103, v96
	v_mul_f32_e32 v96, v97, v183
	v_exp_f32_e32 v100, v100
	v_exp_f32_e32 v97, v96
	v_mul_f32_e32 v98, v98, v183
	v_mul_f32_e32 v99, v99, v183
	v_add_f32_e32 v100, 1.0, v100
	v_rcp_f32_e32 v96, v101
	v_add_f32_e32 v101, 1.0, v103
	v_add_f32_e32 v97, 1.0, v97
	v_exp_f32_e32 v98, v98
	v_rcp_f32_e32 v100, v100
	v_rcp_f32_e32 v101, v101
	v_exp_f32_e32 v99, v99
	v_rcp_f32_e32 v103, v97
	v_add_f32_e32 v97, 1.0, v98
	v_rcp_f32_e32 v105, v97
	v_add_f32_e32 v97, 1.0, v99
	v_pk_fma_f32 v[98:99], v[100:101], s[14:15], 0.5 op_sel_hi:[1,0,0]
	v_pk_fma_f32 v[100:101], v[102:103], s[14:15], 0.5 op_sel_hi:[1,0,0]
	v_rcp_f32_e32 v97, v97
	v_cvt_u32_f32_e32 v101, v101
	v_cvt_u32_f32_e32 v100, v100
	v_cvt_u32_f32_e32 v99, v99
	v_cvt_u32_f32_e32 v98, v98
	v_pk_fma_f32 v[102:103], v[104:105], s[14:15], 0.5 op_sel_hi:[1,0,0]
	v_lshlrev_b32_e32 v101, 8, v101
	v_lshlrev_b32_e32 v100, 8, v100
	v_pk_fma_f32 v[96:97], v[96:97], s[14:15], 0.5 op_sel_hi:[1,0,0]
	v_or_b32_e32 v99, v101, v99
	v_or_b32_e32 v98, v100, v98
	v_cvt_u32_f32_sdwa v100, v103 dst_sel:WORD_1 dst_unused:UNUSED_PAD src0_sel:DWORD
	v_cvt_u32_f32_sdwa v101, v102 dst_sel:WORD_1 dst_unused:UNUSED_PAD src0_sel:DWORD
	v_cvt_u32_f32_sdwa v97, v97 dst_sel:BYTE_3 dst_unused:UNUSED_PAD src0_sel:DWORD
	v_cvt_u32_f32_sdwa v96, v96 dst_sel:BYTE_3 dst_unused:UNUSED_PAD src0_sel:DWORD
	v_or_b32_e32 v99, v99, v100
	v_or_b32_e32 v98, v98, v101
	v_or_b32_e32 v97, v99, v97
	v_or_b32_e32 v96, v98, v96
	v_lshl_add_u64 v[98:99], s[92:93], 0, v[108:109]
	v_lshl_add_u64 v[98:99], v[98:99], 0, v[142:143]
	v_add_co_u32_e32 v98, vcc, s55, v98
	v_mul_f32_e32 v92, v92, v184
	s_nop 0
	v_addc_co_u32_e32 v99, vcc, 0, v99, vcc
	global_store_dwordx2 v[98:99], v[96:97], off offset:128
	v_exp_f32_e32 v96, v92
	v_mul_f32_e32 v92, v93, v184
	v_mul_f32_e32 v94, v94, v184
	v_exp_f32_e32 v97, v92
	v_exp_f32_e32 v98, v94
	v_mul_f32_e32 v94, v95, v184
	v_add_f32_e32 v97, 1.0, v97
	v_mul_f32_e32 v88, v88, v184
	v_exp_f32_e32 v95, v94
	v_rcp_f32_e32 v94, v97
	v_add_f32_e32 v97, 1.0, v98
	v_rcp_f32_e32 v98, v97
	v_exp_f32_e32 v97, v88
	v_mul_f32_e32 v88, v89, v184
	v_exp_f32_e32 v89, v88
	v_add_f32_e32 v95, 1.0, v95
	v_mul_f32_e32 v90, v90, v184
	v_rcp_f32_e32 v88, v95
	v_add_f32_e32 v95, 1.0, v97
	v_add_f32_e32 v89, 1.0, v89
	v_mul_f32_e32 v91, v91, v184
	v_add_f32_e32 v96, 1.0, v96
	v_rcp_f32_e32 v97, v95
	v_exp_f32_e32 v90, v90
	v_rcp_f32_e32 v95, v89
	v_rcp_f32_e32 v96, v96
	v_exp_f32_e32 v91, v91
	v_add_f32_e32 v89, 1.0, v90
	v_pk_fma_f32 v[94:95], v[94:95], s[14:15], 0.5 op_sel_hi:[1,0,0]
	v_rcp_f32_e32 v99, v89
	v_add_f32_e32 v89, 1.0, v91
	v_pk_fma_f32 v[90:91], v[96:97], s[14:15], 0.5 op_sel_hi:[1,0,0]
	v_cvt_u32_f32_e32 v95, v95
	v_cvt_u32_f32_e32 v94, v94
	v_rcp_f32_e32 v89, v89
	v_cvt_u32_f32_e32 v91, v91
; __device__ __forceinline__ float sigmoidf_(float z) { return __builtin_amdgcn_rcpf(1.0f + __builtin_amdgcn_exp2f(-1.4426950408889634f * z)); }
;     __device__ __forceinline__ float compute(const Pre& p, f32x4 (&acc)[2][2][4][2], const f32x4 (&cv)[2][2], const pg8::Unit& u, int ai, int m, int wr, int wc, int fr, int fq) const {
;     ...
;             } else if (MODE == EM_GATES) {
;                 const int col = u.pn * 256 + ct; float w[8];
; #pragma unroll
;                 for (int j = 0; j < 8; ++j) w[j] = sigmoidf_(v[j] * rs) * 255.0f + 0.5f;
;                 u32x2 cd; cd.x = (unsigned)w[0] | ((unsigned)w[1] << 8) | ((unsigned)w[2] << 16) | ((unsigned)w[3] << 24); cd.y = (unsigned)w[4] | ((unsigned)w[5] << 8) | ((unsigned)w[6] << 16) | ((unsigned)w[7] << 24);
;                 *(u32x2*)(ws + WS_G8 + (size_t)row * 2048 + col) = cd;
	v_cvt_u32_f32_e32 v90, v90
	v_pk_fma_f32 v[96:97], v[98:99], s[14:15], 0.5 op_sel_hi:[1,0,0]
	v_lshlrev_b32_e32 v95, 8, v95
	v_lshlrev_b32_e32 v94, 8, v94
	v_pk_fma_f32 v[88:89], v[88:89], s[14:15], 0.5 op_sel_hi:[1,0,0]
	v_or_b32_e32 v91, v95, v91
	v_or_b32_e32 v90, v94, v90
	v_cvt_u32_f32_sdwa v94, v97 dst_sel:WORD_1 dst_unused:UNUSED_PAD src0_sel:DWORD
	v_cvt_u32_f32_sdwa v95, v96 dst_sel:WORD_1 dst_unused:UNUSED_PAD src0_sel:DWORD
	v_cvt_u32_f32_sdwa v89, v89 dst_sel:BYTE_3 dst_unused:UNUSED_PAD src0_sel:DWORD
	v_cvt_u32_f32_sdwa v88, v88 dst_sel:BYTE_3 dst_unused:UNUSED_PAD src0_sel:DWORD
	v_lshlrev_b64 v[92:93], 11, v[154:155]
	v_or_b32_e32 v91, v91, v94
	v_or_b32_e32 v90, v90, v95
	v_or_b32_e32 v89, v91, v89
	v_or_b32_e32 v88, v90, v88
	v_lshl_add_u64 v[90:91], s[12:13], 0, v[92:93]
	v_mul_f32_e32 v85, v85, v184
	v_mul_f32_e32 v86, v86, v184
	v_lshl_add_u64 v[90:91], v[90:91], 0, v[142:143]
	v_exp_f32_e32 v85, v85
	global_store_dwordx2 v[90:91], v[88:89], off
	v_exp_f32_e32 v88, v86
	v_mul_f32_e32 v86, v87, v184
	v_exp_f32_e32 v87, v86
	v_add_f32_e32 v85, 1.0, v85
	v_mul_f32_e32 v80, v80, v184
	v_rcp_f32_e32 v86, v85
	v_add_f32_e32 v85, 1.0, v88
	v_mul_f32_e32 v84, v84, v184
	v_rcp_f32_e32 v88, v85
	v_add_f32_e32 v85, 1.0, v87
	v_exp_f32_e32 v87, v80
	v_mul_f32_e32 v80, v81, v184
	v_exp_f32_e32 v84, v84
	v_exp_f32_e32 v81, v80
	v_mul_f32_e32 v82, v82, v184
	v_mul_f32_e32 v83, v83, v184
	v_add_f32_e32 v84, 1.0, v84
	v_rcp_f32_e32 v80, v85
	v_add_f32_e32 v85, 1.0, v87
	v_add_f32_e32 v81, 1.0, v81
	v_exp_f32_e32 v82, v82
	v_rcp_f32_e32 v84, v84
	v_rcp_f32_e32 v85, v85
	v_exp_f32_e32 v83, v83
	v_rcp_f32_e32 v87, v81
	v_add_f32_e32 v81, 1.0, v82
	v_rcp_f32_e32 v89, v81
	v_add_f32_e32 v81, 1.0, v83
	v_pk_fma_f32 v[82:83], v[84:85], s[14:15], 0.5 op_sel_hi:[1,0,0]
	v_pk_fma_f32 v[84:85], v[86:87], s[14:15], 0.5 op_sel_hi:[1,0,0]
	v_rcp_f32_e32 v81, v81
	v_cvt_u32_f32_e32 v85, v85
	v_cvt_u32_f32_e32 v84, v84
	v_cvt_u32_f32_e32 v83, v83
	v_cvt_u32_f32_e32 v82, v82
	v_pk_fma_f32 v[86:87], v[88:89], s[14:15], 0.5 op_sel_hi:[1,0,0]
	v_lshlrev_b32_e32 v85, 8, v85
	v_lshlrev_b32_e32 v84, 8, v84
	v_pk_fma_f32 v[80:81], v[80:81], s[14:15], 0.5 op_sel_hi:[1,0,0]
	v_or_b32_e32 v83, v85, v83
	v_or_b32_e32 v82, v84, v82
	v_cvt_u32_f32_sdwa v84, v87 dst_sel:WORD_1 dst_unused:UNUSED_PAD src0_sel:DWORD
	v_cvt_u32_f32_sdwa v85, v86 dst_sel:WORD_1 dst_unused:UNUSED_PAD src0_sel:DWORD
	v_cvt_u32_f32_sdwa v81, v81 dst_sel:BYTE_3 dst_unused:UNUSED_PAD src0_sel:DWORD
	v_cvt_u32_f32_sdwa v80, v80 dst_sel:BYTE_3 dst_unused:UNUSED_PAD src0_sel:DWORD
	v_or_b32_e32 v83, v83, v84
	v_or_b32_e32 v82, v82, v85
	v_or_b32_e32 v81, v83, v81
	v_or_b32_e32 v80, v82, v80
	v_lshl_add_u64 v[82:83], s[92:93], 0, v[92:93]
	v_lshl_add_u64 v[82:83], v[82:83], 0, v[142:143]
	v_add_co_u32_e32 v82, vcc, s55, v82
	v_mul_f32_e32 v76, v76, v168
	s_nop 0
	v_addc_co_u32_e32 v83, vcc, 0, v83, vcc
	global_store_dwordx2 v[82:83], v[80:81], off offset:128
	v_exp_f32_e32 v80, v76
	v_mul_f32_e32 v76, v77, v168
	v_mul_f32_e32 v78, v78, v168
	v_exp_f32_e32 v81, v76
	v_exp_f32_e32 v82, v78
	v_mul_f32_e32 v78, v79, v168
	v_add_f32_e32 v81, 1.0, v81
	v_mul_f32_e32 v72, v72, v168
	v_exp_f32_e32 v79, v78
	v_rcp_f32_e32 v78, v81
	v_add_f32_e32 v81, 1.0, v82
	v_rcp_f32_e32 v82, v81
	v_exp_f32_e32 v81, v72
	v_mul_f32_e32 v72, v73, v168
	v_exp_f32_e32 v73, v72
	v_add_f32_e32 v79, 1.0, v79
	v_mul_f32_e32 v74, v74, v168
	v_rcp_f32_e32 v72, v79
	v_add_f32_e32 v79, 1.0, v81
	v_add_f32_e32 v73, 1.0, v73
	v_mul_f32_e32 v75, v75, v168
	v_add_f32_e32 v80, 1.0, v80
	v_rcp_f32_e32 v81, v79
	v_exp_f32_e32 v74, v74
	v_rcp_f32_e32 v79, v73
	v_rcp_f32_e32 v80, v80
	v_exp_f32_e32 v75, v75
	v_add_f32_e32 v73, 1.0, v74
	v_pk_fma_f32 v[78:79], v[78:79], s[14:15], 0.5 op_sel_hi:[1,0,0]
	v_rcp_f32_e32 v83, v73
	v_add_f32_e32 v73, 1.0, v75
	v_pk_fma_f32 v[74:75], v[80:81], s[14:15], 0.5 op_sel_hi:[1,0,0]
	v_cvt_u32_f32_e32 v79, v79
	v_cvt_u32_f32_e32 v78, v78
	v_rcp_f32_e32 v73, v73
	v_cvt_u32_f32_e32 v75, v75
	v_cvt_u32_f32_e32 v74, v74
	v_pk_fma_f32 v[80:81], v[82:83], s[14:15], 0.5 op_sel_hi:[1,0,0]
	v_lshlrev_b32_e32 v79, 8, v79
	v_lshlrev_b32_e32 v78, 8, v78
	v_pk_fma_f32 v[72:73], v[72:73], s[14:15], 0.5 op_sel_hi:[1,0,0]
	v_or_b32_e32 v75, v79, v75
	v_or_b32_e32 v74, v78, v74
	v_cvt_u32_f32_sdwa v78, v81 dst_sel:WORD_1 dst_unused:UNUSED_PAD src0_sel:DWORD
	v_cvt_u32_f32_sdwa v79, v80 dst_sel:WORD_1 dst_unused:UNUSED_PAD src0_sel:DWORD
	v_cvt_u32_f32_sdwa v73, v73 dst_sel:BYTE_3 dst_unused:UNUSED_PAD src0_sel:DWORD
	v_cvt_u32_f32_sdwa v72, v72 dst_sel:BYTE_3 dst_unused:UNUSED_PAD src0_sel:DWORD
	v_lshlrev_b64 v[76:77], 11, v[152:153]
	v_or_b32_e32 v75, v75, v78
	v_or_b32_e32 v74, v74, v79
	v_or_b32_e32 v73, v75, v73
	v_or_b32_e32 v72, v74, v72
	v_lshl_add_u64 v[74:75], s[12:13], 0, v[76:77]
	v_mul_f32_e32 v69, v69, v168
	v_mul_f32_e32 v70, v70, v168
	v_lshl_add_u64 v[74:75], v[74:75], 0, v[142:143]
	v_exp_f32_e32 v69, v69
	global_store_dwordx2 v[74:75], v[72:73], off
	v_exp_f32_e32 v72, v70
	v_mul_f32_e32 v70, v71, v168
	v_exp_f32_e32 v71, v70
	v_add_f32_e32 v69, 1.0, v69
	v_mul_f32_e32 v64, v64, v168
	v_rcp_f32_e32 v70, v69
	v_add_f32_e32 v69, 1.0, v72
	v_mul_f32_e32 v68, v68, v168
	v_rcp_f32_e32 v72, v69
	v_add_f32_e32 v69, 1.0, v71
	v_exp_f32_e32 v71, v64
	v_mul_f32_e32 v64, v65, v168
	v_exp_f32_e32 v68, v68
	v_exp_f32_e32 v65, v64
	v_mul_f32_e32 v66, v66, v168
	v_mul_f32_e32 v67, v67, v168
	v_add_f32_e32 v68, 1.0, v68
	v_rcp_f32_e32 v64, v69
	v_add_f32_e32 v69, 1.0, v71
	v_add_f32_e32 v65, 1.0, v65
	v_exp_f32_e32 v66, v66
	v_rcp_f32_e32 v68, v68
	v_rcp_f32_e32 v69, v69
	v_exp_f32_e32 v67, v67
	v_rcp_f32_e32 v71, v65
; __device__ __forceinline__ float sigmoidf_(float z) { return __builtin_amdgcn_rcpf(1.0f + __builtin_amdgcn_exp2f(-1.4426950408889634f * z)); }
;     __device__ __forceinline__ float compute(const Pre& p, f32x4 (&acc)[2][2][4][2], const f32x4 (&cv)[2][2], const pg8::Unit& u, int ai, int m, int wr, int wc, int fr, int fq) const {
;     ...
;             } else if (MODE == EM_GATES) {
;                 const int col = u.pn * 256 + ct; float w[8];
; #pragma unroll
;                 for (int j = 0; j < 8; ++j) w[j] = sigmoidf_(v[j] * rs) * 255.0f + 0.5f;
;                 u32x2 cd; cd.x = (unsigned)w[0] | ((unsigned)w[1] << 8) | ((unsigned)w[2] << 16) | ((unsigned)w[3] << 24); cd.y = (unsigned)w[4] | ((unsigned)w[5] << 8) | ((unsigned)w[6] << 16) | ((unsigned)w[7] << 24);
;                 *(u32x2*)(ws + WS_G8 + (size_t)row * 2048 + col) = cd;
	v_add_f32_e32 v65, 1.0, v66
	v_rcp_f32_e32 v73, v65
	v_add_f32_e32 v65, 1.0, v67
	v_pk_fma_f32 v[66:67], v[68:69], s[14:15], 0.5 op_sel_hi:[1,0,0]
	v_pk_fma_f32 v[68:69], v[70:71], s[14:15], 0.5 op_sel_hi:[1,0,0]
	v_rcp_f32_e32 v65, v65
	v_cvt_u32_f32_e32 v69, v69
	v_cvt_u32_f32_e32 v68, v68
	v_cvt_u32_f32_e32 v67, v67
	v_cvt_u32_f32_e32 v66, v66
	v_pk_fma_f32 v[70:71], v[72:73], s[14:15], 0.5 op_sel_hi:[1,0,0]
	v_lshlrev_b32_e32 v69, 8, v69
	v_lshlrev_b32_e32 v68, 8, v68
	v_pk_fma_f32 v[64:65], v[64:65], s[14:15], 0.5 op_sel_hi:[1,0,0]
	v_or_b32_e32 v67, v69, v67
	v_or_b32_e32 v66, v68, v66
	v_cvt_u32_f32_sdwa v68, v71 dst_sel:WORD_1 dst_unused:UNUSED_PAD src0_sel:DWORD
	v_cvt_u32_f32_sdwa v69, v70 dst_sel:WORD_1 dst_unused:UNUSED_PAD src0_sel:DWORD
	v_cvt_u32_f32_sdwa v65, v65 dst_sel:BYTE_3 dst_unused:UNUSED_PAD src0_sel:DWORD
	v_cvt_u32_f32_sdwa v64, v64 dst_sel:BYTE_3 dst_unused:UNUSED_PAD src0_sel:DWORD
	v_or_b32_e32 v67, v67, v68
	v_or_b32_e32 v66, v66, v69
	v_or_b32_e32 v65, v67, v65
	v_or_b32_e32 v64, v66, v64
	v_lshl_add_u64 v[66:67], s[92:93], 0, v[76:77]
	v_lshl_add_u64 v[66:67], v[66:67], 0, v[142:143]
	v_add_co_u32_e32 v66, vcc, s55, v66
	v_mul_f32_e32 v60, v60, v167
	s_nop 0
	v_addc_co_u32_e32 v67, vcc, 0, v67, vcc
	global_store_dwordx2 v[66:67], v[64:65], off offset:128
	v_exp_f32_e32 v64, v60
	v_mul_f32_e32 v60, v61, v167
	v_mul_f32_e32 v62, v62, v167
	v_exp_f32_e32 v65, v60
	v_exp_f32_e32 v66, v62
	v_mul_f32_e32 v62, v63, v167
	v_add_f32_e32 v65, 1.0, v65
	v_mul_f32_e32 v56, v56, v167
	v_exp_f32_e32 v63, v62
	v_rcp_f32_e32 v62, v65
	v_add_f32_e32 v65, 1.0, v66
	v_rcp_f32_e32 v66, v65
	v_exp_f32_e32 v65, v56
	v_mul_f32_e32 v56, v57, v167
	v_exp_f32_e32 v57, v56
	v_add_f32_e32 v63, 1.0, v63
	v_mul_f32_e32 v58, v58, v167
	v_rcp_f32_e32 v56, v63
	v_add_f32_e32 v63, 1.0, v65
	v_add_f32_e32 v57, 1.0, v57
	v_mul_f32_e32 v59, v59, v167
	v_add_f32_e32 v64, 1.0, v64
	v_rcp_f32_e32 v65, v63
	v_exp_f32_e32 v58, v58
	v_rcp_f32_e32 v63, v57
	v_rcp_f32_e32 v64, v64
	v_exp_f32_e32 v59, v59
	v_add_f32_e32 v57, 1.0, v58
	v_pk_fma_f32 v[62:63], v[62:63], s[14:15], 0.5 op_sel_hi:[1,0,0]
	v_rcp_f32_e32 v67, v57
	v_add_f32_e32 v57, 1.0, v59
	v_pk_fma_f32 v[58:59], v[64:65], s[14:15], 0.5 op_sel_hi:[1,0,0]
	v_cvt_u32_f32_e32 v63, v63
	v_cvt_u32_f32_e32 v62, v62
	v_rcp_f32_e32 v57, v57
	v_cvt_u32_f32_e32 v59, v59
	v_cvt_u32_f32_e32 v58, v58
	v_pk_fma_f32 v[64:65], v[66:67], s[14:15], 0.5 op_sel_hi:[1,0,0]
	v_lshlrev_b32_e32 v63, 8, v63
	v_lshlrev_b32_e32 v62, 8, v62
	v_pk_fma_f32 v[56:57], v[56:57], s[14:15], 0.5 op_sel_hi:[1,0,0]
	v_or_b32_e32 v59, v63, v59
	v_or_b32_e32 v58, v62, v58
	v_cvt_u32_f32_sdwa v62, v65 dst_sel:WORD_1 dst_unused:UNUSED_PAD src0_sel:DWORD
	v_cvt_u32_f32_sdwa v63, v64 dst_sel:WORD_1 dst_unused:UNUSED_PAD src0_sel:DWORD
	v_cvt_u32_f32_sdwa v57, v57 dst_sel:BYTE_3 dst_unused:UNUSED_PAD src0_sel:DWORD
	v_cvt_u32_f32_sdwa v56, v56 dst_sel:BYTE_3 dst_unused:UNUSED_PAD src0_sel:DWORD
	v_lshlrev_b64 v[60:61], 11, v[150:151]
	v_or_b32_e32 v59, v59, v62
	v_or_b32_e32 v58, v58, v63
	v_or_b32_e32 v57, v59, v57
	v_or_b32_e32 v56, v58, v56
	v_lshl_add_u64 v[58:59], s[12:13], 0, v[60:61]
	v_mul_f32_e32 v53, v53, v167
	v_mul_f32_e32 v54, v54, v167
	v_lshl_add_u64 v[58:59], v[58:59], 0, v[142:143]
	v_exp_f32_e32 v53, v53
	global_store_dwordx2 v[58:59], v[56:57], off
	v_exp_f32_e32 v56, v54
	v_mul_f32_e32 v54, v55, v167
	v_exp_f32_e32 v55, v54
	v_add_f32_e32 v53, 1.0, v53
	v_mul_f32_e32 v48, v48, v167
	v_rcp_f32_e32 v54, v53
	v_add_f32_e32 v53, 1.0, v56
	v_mul_f32_e32 v52, v52, v167
	v_rcp_f32_e32 v56, v53
	v_add_f32_e32 v53, 1.0, v55
	v_exp_f32_e32 v55, v48
	v_mul_f32_e32 v48, v49, v167
	v_exp_f32_e32 v52, v52
	v_exp_f32_e32 v49, v48
	v_mul_f32_e32 v50, v50, v167
	v_mul_f32_e32 v51, v51, v167
	v_add_f32_e32 v52, 1.0, v52
	v_rcp_f32_e32 v48, v53
	v_add_f32_e32 v53, 1.0, v55
	v_add_f32_e32 v49, 1.0, v49
	v_exp_f32_e32 v50, v50
	v_rcp_f32_e32 v52, v52
	v_rcp_f32_e32 v53, v53
	v_exp_f32_e32 v51, v51
	v_rcp_f32_e32 v55, v49
	v_add_f32_e32 v49, 1.0, v50
	v_rcp_f32_e32 v57, v49
	v_add_f32_e32 v49, 1.0, v51
	v_pk_fma_f32 v[50:51], v[52:53], s[14:15], 0.5 op_sel_hi:[1,0,0]
	v_pk_fma_f32 v[52:53], v[54:55], s[14:15], 0.5 op_sel_hi:[1,0,0]
	v_rcp_f32_e32 v49, v49
	v_cvt_u32_f32_e32 v53, v53
	v_cvt_u32_f32_e32 v52, v52
	v_cvt_u32_f32_e32 v51, v51
	v_cvt_u32_f32_e32 v50, v50
	v_pk_fma_f32 v[54:55], v[56:57], s[14:15], 0.5 op_sel_hi:[1,0,0]
	v_lshlrev_b32_e32 v53, 8, v53
	v_lshlrev_b32_e32 v52, 8, v52
	v_pk_fma_f32 v[48:49], v[48:49], s[14:15], 0.5 op_sel_hi:[1,0,0]
	v_or_b32_e32 v51, v53, v51
	v_or_b32_e32 v50, v52, v50
	v_cvt_u32_f32_sdwa v52, v55 dst_sel:WORD_1 dst_unused:UNUSED_PAD src0_sel:DWORD
	v_cvt_u32_f32_sdwa v53, v54 dst_sel:WORD_1 dst_unused:UNUSED_PAD src0_sel:DWORD
	v_cvt_u32_f32_sdwa v49, v49 dst_sel:BYTE_3 dst_unused:UNUSED_PAD src0_sel:DWORD
	v_cvt_u32_f32_sdwa v48, v48 dst_sel:BYTE_3 dst_unused:UNUSED_PAD src0_sel:DWORD
	v_or_b32_e32 v51, v51, v52
	v_or_b32_e32 v50, v50, v53
	v_or_b32_e32 v49, v51, v49
	v_or_b32_e32 v48, v50, v48
	v_lshl_add_u64 v[50:51], s[92:93], 0, v[60:61]
	v_lshl_add_u64 v[50:51], v[50:51], 0, v[142:143]
	v_add_co_u32_e32 v50, vcc, s55, v50
	v_mul_f32_e32 v44, v44, v166
	s_nop 0
	v_addc_co_u32_e32 v51, vcc, 0, v51, vcc
	global_store_dwordx2 v[50:51], v[48:49], off offset:128
	v_exp_f32_e32 v48, v44
	v_mul_f32_e32 v44, v45, v166
	v_mul_f32_e32 v46, v46, v166
	v_exp_f32_e32 v49, v44
	v_exp_f32_e32 v50, v46
	v_mul_f32_e32 v46, v47, v166
	v_add_f32_e32 v49, 1.0, v49
	v_mul_f32_e32 v40, v40, v166
	v_exp_f32_e32 v47, v46
	v_rcp_f32_e32 v46, v49
	v_add_f32_e32 v49, 1.0, v50
	v_rcp_f32_e32 v50, v49
; __device__ __forceinline__ float sigmoidf_(float z) { return __builtin_amdgcn_rcpf(1.0f + __builtin_amdgcn_exp2f(-1.4426950408889634f * z)); }
;     __device__ __forceinline__ float compute(const Pre& p, f32x4 (&acc)[2][2][4][2], const f32x4 (&cv)[2][2], const pg8::Unit& u, int ai, int m, int wr, int wc, int fr, int fq) const {
;     ...
;             } else if (MODE == EM_GATES) {
;                 const int col = u.pn * 256 + ct; float w[8];
; #pragma unroll
;                 for (int j = 0; j < 8; ++j) w[j] = sigmoidf_(v[j] * rs) * 255.0f + 0.5f;
;                 u32x2 cd; cd.x = (unsigned)w[0] | ((unsigned)w[1] << 8) | ((unsigned)w[2] << 16) | ((unsigned)w[3] << 24); cd.y = (unsigned)w[4] | ((unsigned)w[5] << 8) | ((unsigned)w[6] << 16) | ((unsigned)w[7] << 24);
;                 *(u32x2*)(ws + WS_G8 + (size_t)row * 2048 + col) = cd;
	v_exp_f32_e32 v49, v40
	v_mul_f32_e32 v40, v41, v166
	v_exp_f32_e32 v41, v40
	v_add_f32_e32 v47, 1.0, v47
	v_mul_f32_e32 v42, v42, v166
	v_rcp_f32_e32 v40, v47
	v_add_f32_e32 v47, 1.0, v49
	v_add_f32_e32 v41, 1.0, v41
	v_mul_f32_e32 v43, v43, v166
	v_add_f32_e32 v48, 1.0, v48
	v_rcp_f32_e32 v49, v47
	v_exp_f32_e32 v42, v42
	v_rcp_f32_e32 v47, v41
	v_rcp_f32_e32 v48, v48
	v_exp_f32_e32 v43, v43
	v_add_f32_e32 v41, 1.0, v42
	v_pk_fma_f32 v[46:47], v[46:47], s[14:15], 0.5 op_sel_hi:[1,0,0]
	v_rcp_f32_e32 v51, v41
	v_add_f32_e32 v41, 1.0, v43
	v_pk_fma_f32 v[42:43], v[48:49], s[14:15], 0.5 op_sel_hi:[1,0,0]
	v_cvt_u32_f32_e32 v47, v47
	v_cvt_u32_f32_e32 v46, v46
	v_rcp_f32_e32 v41, v41
	v_cvt_u32_f32_e32 v43, v43
	v_cvt_u32_f32_e32 v42, v42
	v_pk_fma_f32 v[48:49], v[50:51], s[14:15], 0.5 op_sel_hi:[1,0,0]
	v_lshlrev_b32_e32 v47, 8, v47
	v_lshlrev_b32_e32 v46, 8, v46
	v_pk_fma_f32 v[40:41], v[40:41], s[14:15], 0.5 op_sel_hi:[1,0,0]
	v_or_b32_e32 v43, v47, v43
	v_or_b32_e32 v42, v46, v42
	v_cvt_u32_f32_sdwa v46, v49 dst_sel:WORD_1 dst_unused:UNUSED_PAD src0_sel:DWORD
	v_cvt_u32_f32_sdwa v47, v48 dst_sel:WORD_1 dst_unused:UNUSED_PAD src0_sel:DWORD
	v_cvt_u32_f32_sdwa v41, v41 dst_sel:BYTE_3 dst_unused:UNUSED_PAD src0_sel:DWORD
	v_cvt_u32_f32_sdwa v40, v40 dst_sel:BYTE_3 dst_unused:UNUSED_PAD src0_sel:DWORD
	v_lshlrev_b64 v[44:45], 11, v[148:149]
	v_or_b32_e32 v43, v43, v46
	v_or_b32_e32 v42, v42, v47
	v_or_b32_e32 v41, v43, v41
	v_or_b32_e32 v40, v42, v40
	v_lshl_add_u64 v[42:43], s[12:13], 0, v[44:45]
	v_mul_f32_e32 v37, v37, v166
	v_mul_f32_e32 v38, v38, v166
	v_lshl_add_u64 v[42:43], v[42:43], 0, v[142:143]
	v_exp_f32_e32 v37, v37
	global_store_dwordx2 v[42:43], v[40:41], off
	v_exp_f32_e32 v40, v38
	v_mul_f32_e32 v38, v39, v166
	v_exp_f32_e32 v39, v38
	v_add_f32_e32 v37, 1.0, v37
	v_mul_f32_e32 v32, v32, v166
	v_rcp_f32_e32 v38, v37
	v_add_f32_e32 v37, 1.0, v40
	v_mul_f32_e32 v36, v36, v166
	v_rcp_f32_e32 v40, v37
	v_add_f32_e32 v37, 1.0, v39
	v_exp_f32_e32 v39, v32
	v_mul_f32_e32 v32, v33, v166
	v_exp_f32_e32 v36, v36
	v_exp_f32_e32 v33, v32
	v_mul_f32_e32 v34, v34, v166
	v_mul_f32_e32 v35, v35, v166
	v_add_f32_e32 v36, 1.0, v36
	v_rcp_f32_e32 v32, v37
	v_add_f32_e32 v37, 1.0, v39
	v_add_f32_e32 v33, 1.0, v33
	v_exp_f32_e32 v34, v34
	v_rcp_f32_e32 v36, v36
	v_rcp_f32_e32 v37, v37
	v_exp_f32_e32 v35, v35
	v_rcp_f32_e32 v39, v33
	v_add_f32_e32 v33, 1.0, v34
	v_rcp_f32_e32 v41, v33
	v_add_f32_e32 v33, 1.0, v35
	v_pk_fma_f32 v[34:35], v[36:37], s[14:15], 0.5 op_sel_hi:[1,0,0]
	v_pk_fma_f32 v[36:37], v[38:39], s[14:15], 0.5 op_sel_hi:[1,0,0]
	v_rcp_f32_e32 v33, v33
	v_cvt_u32_f32_e32 v37, v37
	v_cvt_u32_f32_e32 v36, v36
	v_cvt_u32_f32_e32 v35, v35
	v_cvt_u32_f32_e32 v34, v34
	v_pk_fma_f32 v[38:39], v[40:41], s[14:15], 0.5 op_sel_hi:[1,0,0]
	v_lshlrev_b32_e32 v37, 8, v37
	v_lshlrev_b32_e32 v36, 8, v36
	v_pk_fma_f32 v[32:33], v[32:33], s[14:15], 0.5 op_sel_hi:[1,0,0]
	v_or_b32_e32 v35, v37, v35
	v_or_b32_e32 v34, v36, v34
	v_cvt_u32_f32_sdwa v36, v39 dst_sel:WORD_1 dst_unused:UNUSED_PAD src0_sel:DWORD
	v_cvt_u32_f32_sdwa v37, v38 dst_sel:WORD_1 dst_unused:UNUSED_PAD src0_sel:DWORD
	v_cvt_u32_f32_sdwa v33, v33 dst_sel:BYTE_3 dst_unused:UNUSED_PAD src0_sel:DWORD
	v_cvt_u32_f32_sdwa v32, v32 dst_sel:BYTE_3 dst_unused:UNUSED_PAD src0_sel:DWORD
	v_or_b32_e32 v35, v35, v36
	v_or_b32_e32 v34, v34, v37
	v_or_b32_e32 v33, v35, v33
	v_or_b32_e32 v32, v34, v32
	v_lshl_add_u64 v[34:35], s[92:93], 0, v[44:45]
	v_lshl_add_u64 v[34:35], v[34:35], 0, v[142:143]
	v_add_co_u32_e32 v34, vcc, s55, v34
	v_mul_f32_e32 v28, v28, v165
	s_nop 0
	v_addc_co_u32_e32 v35, vcc, 0, v35, vcc
	global_store_dwordx2 v[34:35], v[32:33], off offset:128
	v_exp_f32_e32 v32, v28
	v_mul_f32_e32 v28, v29, v165
	v_mul_f32_e32 v30, v30, v165
	v_exp_f32_e32 v33, v28
	v_exp_f32_e32 v34, v30
	v_mul_f32_e32 v30, v31, v165
	v_add_f32_e32 v33, 1.0, v33
	v_mul_f32_e32 v24, v24, v165
	v_exp_f32_e32 v31, v30
	v_rcp_f32_e32 v30, v33
	v_add_f32_e32 v33, 1.0, v34
	v_rcp_f32_e32 v34, v33
	v_exp_f32_e32 v33, v24
	v_mul_f32_e32 v24, v25, v165
	v_exp_f32_e32 v25, v24
	v_add_f32_e32 v31, 1.0, v31
	v_mul_f32_e32 v26, v26, v165
	v_rcp_f32_e32 v24, v31
	v_add_f32_e32 v31, 1.0, v33
	v_add_f32_e32 v25, 1.0, v25
	v_mul_f32_e32 v27, v27, v165
	v_add_f32_e32 v32, 1.0, v32
	v_rcp_f32_e32 v33, v31
	v_exp_f32_e32 v26, v26
	v_rcp_f32_e32 v31, v25
	v_rcp_f32_e32 v32, v32
	v_exp_f32_e32 v27, v27
	v_add_f32_e32 v25, 1.0, v26
	v_pk_fma_f32 v[30:31], v[30:31], s[14:15], 0.5 op_sel_hi:[1,0,0]
	v_rcp_f32_e32 v35, v25
	v_add_f32_e32 v25, 1.0, v27
	v_pk_fma_f32 v[26:27], v[32:33], s[14:15], 0.5 op_sel_hi:[1,0,0]
	v_cvt_u32_f32_e32 v31, v31
	v_cvt_u32_f32_e32 v30, v30
	v_rcp_f32_e32 v25, v25
	v_cvt_u32_f32_e32 v27, v27
	v_cvt_u32_f32_e32 v26, v26
	v_pk_fma_f32 v[32:33], v[34:35], s[14:15], 0.5 op_sel_hi:[1,0,0]
	v_lshlrev_b32_e32 v31, 8, v31
	v_lshlrev_b32_e32 v30, 8, v30
	v_pk_fma_f32 v[24:25], v[24:25], s[14:15], 0.5 op_sel_hi:[1,0,0]
	v_or_b32_e32 v27, v31, v27
	v_or_b32_e32 v26, v30, v26
	v_cvt_u32_f32_sdwa v30, v33 dst_sel:WORD_1 dst_unused:UNUSED_PAD src0_sel:DWORD
	v_cvt_u32_f32_sdwa v31, v32 dst_sel:WORD_1 dst_unused:UNUSED_PAD src0_sel:DWORD
	v_cvt_u32_f32_sdwa v25, v25 dst_sel:BYTE_3 dst_unused:UNUSED_PAD src0_sel:DWORD
	v_cvt_u32_f32_sdwa v24, v24 dst_sel:BYTE_3 dst_unused:UNUSED_PAD src0_sel:DWORD
	v_lshlrev_b64 v[28:29], 11, v[146:147]
	v_or_b32_e32 v27, v27, v30
	v_or_b32_e32 v26, v26, v31
	v_or_b32_e32 v25, v27, v25
	v_or_b32_e32 v24, v26, v24
	v_lshl_add_u64 v[26:27], s[12:13], 0, v[28:29]
	v_mul_f32_e32 v21, v21, v165
	v_mul_f32_e32 v22, v22, v165
	v_lshl_add_u64 v[26:27], v[26:27], 0, v[142:143]
; __device__ __forceinline__ float sigmoidf_(float z) { return __builtin_amdgcn_rcpf(1.0f + __builtin_amdgcn_exp2f(-1.4426950408889634f * z)); }
; #define PG8_BAR __builtin_amdgcn_s_barrier()
; template <class Epi, class Sched>
; __device__ __forceinline__ void gemm_phase(LAS unsigned char* lds, const Gemm g, const Sched& S, const Epi& E, int wave_id) {
;     ...
;         if (!has_next) break;
; #pragma unroll
;         for (int a = 0; a < 2; ++a)
; #pragma unroll
;             for (int b = 0; b < 2; ++b)
; #pragma unroll
;                 for (int m = 0; m < 4; ++m)
; #pragma unroll
;                     for (int n = 0; n < 2; ++n) acc[a][b][m][n] = (f32x4){0.f, 0.f, 0.f, 0.f};
;         cur = nxt; cA = nA; cB = nB; ++ui;
;         if (wr == 1) PG8_BAR;
;     __device__ __forceinline__ float compute(const Pre& p, f32x4 (&acc)[2][2][4][2], const f32x4 (&cv)[2][2], const pg8::Unit& u, int ai, int m, int wr, int wc, int fr, int fq) const {
;     ...
;             } else if (MODE == EM_GATES) {
;                 const int col = u.pn * 256 + ct; float w[8];
; #pragma unroll
;                 for (int j = 0; j < 8; ++j) w[j] = sigmoidf_(v[j] * rs) * 255.0f + 0.5f;
;                 u32x2 cd; cd.x = (unsigned)w[0] | ((unsigned)w[1] << 8) | ((unsigned)w[2] << 16) | ((unsigned)w[3] << 24); cd.y = (unsigned)w[4] | ((unsigned)w[5] << 8) | ((unsigned)w[6] << 16) | ((unsigned)w[7] << 24);
;                 *(u32x2*)(ws + WS_G8 + (size_t)row * 2048 + col) = cd;
	v_exp_f32_e32 v21, v21
	global_store_dwordx2 v[26:27], v[24:25], off
	v_exp_f32_e32 v24, v22
	v_mul_f32_e32 v22, v23, v165
	v_exp_f32_e32 v23, v22
	v_add_f32_e32 v21, 1.0, v21
	v_mul_f32_e32 v16, v16, v165
	v_rcp_f32_e32 v22, v21
	v_add_f32_e32 v21, 1.0, v24
	v_mul_f32_e32 v20, v20, v165
	v_rcp_f32_e32 v24, v21
	v_add_f32_e32 v21, 1.0, v23
	v_exp_f32_e32 v23, v16
	v_mul_f32_e32 v16, v17, v165
	v_exp_f32_e32 v20, v20
	v_exp_f32_e32 v17, v16
	v_mul_f32_e32 v18, v18, v165
	v_mul_f32_e32 v19, v19, v165
	v_add_f32_e32 v20, 1.0, v20
	v_rcp_f32_e32 v16, v21
	v_add_f32_e32 v21, 1.0, v23
	v_add_f32_e32 v17, 1.0, v17
	v_exp_f32_e32 v18, v18
	v_rcp_f32_e32 v20, v20
	v_rcp_f32_e32 v21, v21
	v_exp_f32_e32 v19, v19
	v_rcp_f32_e32 v23, v17
	v_add_f32_e32 v17, 1.0, v18
	v_rcp_f32_e32 v25, v17
	v_add_f32_e32 v17, 1.0, v19
	v_pk_fma_f32 v[18:19], v[20:21], s[14:15], 0.5 op_sel_hi:[1,0,0]
	v_pk_fma_f32 v[20:21], v[22:23], s[14:15], 0.5 op_sel_hi:[1,0,0]
	v_rcp_f32_e32 v17, v17
	v_cvt_u32_f32_e32 v21, v21
	v_cvt_u32_f32_e32 v20, v20
	v_cvt_u32_f32_e32 v19, v19
	v_cvt_u32_f32_e32 v18, v18
	v_pk_fma_f32 v[22:23], v[24:25], s[14:15], 0.5 op_sel_hi:[1,0,0]
	v_lshlrev_b32_e32 v21, 8, v21
	v_lshlrev_b32_e32 v20, 8, v20
	v_pk_fma_f32 v[16:17], v[16:17], s[14:15], 0.5 op_sel_hi:[1,0,0]
	v_or_b32_e32 v19, v21, v19
	v_or_b32_e32 v18, v20, v18
	v_cvt_u32_f32_sdwa v20, v23 dst_sel:WORD_1 dst_unused:UNUSED_PAD src0_sel:DWORD
	v_cvt_u32_f32_sdwa v21, v22 dst_sel:WORD_1 dst_unused:UNUSED_PAD src0_sel:DWORD
	v_cvt_u32_f32_sdwa v17, v17 dst_sel:BYTE_3 dst_unused:UNUSED_PAD src0_sel:DWORD
	v_cvt_u32_f32_sdwa v16, v16 dst_sel:BYTE_3 dst_unused:UNUSED_PAD src0_sel:DWORD
	v_or_b32_e32 v19, v19, v20
	v_or_b32_e32 v18, v18, v21
	v_or_b32_e32 v17, v19, v17
	v_or_b32_e32 v16, v18, v16
	v_lshl_add_u64 v[18:19], s[92:93], 0, v[28:29]
	v_lshl_add_u64 v[18:19], v[18:19], 0, v[142:143]
	v_add_co_u32_e32 v18, vcc, s55, v18
	v_mul_f32_e32 v12, v12, v164
	s_nop 0
	v_addc_co_u32_e32 v19, vcc, 0, v19, vcc
	global_store_dwordx2 v[18:19], v[16:17], off offset:128
	v_exp_f32_e32 v16, v12
	v_mul_f32_e32 v12, v13, v164
	v_mul_f32_e32 v14, v14, v164
	v_exp_f32_e32 v17, v12
	v_exp_f32_e32 v18, v14
	v_mul_f32_e32 v14, v15, v164
	v_add_f32_e32 v17, 1.0, v17
	v_mul_f32_e32 v8, v8, v164
	v_exp_f32_e32 v15, v14
	v_rcp_f32_e32 v14, v17
	v_add_f32_e32 v17, 1.0, v18
	v_rcp_f32_e32 v18, v17
	v_exp_f32_e32 v17, v8
	v_mul_f32_e32 v8, v9, v164
	v_exp_f32_e32 v9, v8
	v_add_f32_e32 v15, 1.0, v15
	v_mul_f32_e32 v10, v10, v164
	v_rcp_f32_e32 v8, v15
	v_add_f32_e32 v15, 1.0, v17
	v_add_f32_e32 v9, 1.0, v9
	v_mul_f32_e32 v11, v11, v164
	v_add_f32_e32 v16, 1.0, v16
	v_rcp_f32_e32 v17, v15
	v_exp_f32_e32 v10, v10
	v_rcp_f32_e32 v15, v9
	v_rcp_f32_e32 v16, v16
	v_exp_f32_e32 v11, v11
	v_add_f32_e32 v9, 1.0, v10
	v_pk_fma_f32 v[14:15], v[14:15], s[14:15], 0.5 op_sel_hi:[1,0,0]
	v_rcp_f32_e32 v19, v9
	v_add_f32_e32 v9, 1.0, v11
	v_pk_fma_f32 v[10:11], v[16:17], s[14:15], 0.5 op_sel_hi:[1,0,0]
	v_cvt_u32_f32_e32 v15, v15
	v_cvt_u32_f32_e32 v14, v14
	v_rcp_f32_e32 v9, v9
	v_cvt_u32_f32_e32 v11, v11
	v_cvt_u32_f32_e32 v10, v10
	v_pk_fma_f32 v[16:17], v[18:19], s[14:15], 0.5 op_sel_hi:[1,0,0]
	v_lshlrev_b32_e32 v15, 8, v15
	v_lshlrev_b32_e32 v14, 8, v14
	v_pk_fma_f32 v[8:9], v[8:9], s[14:15], 0.5 op_sel_hi:[1,0,0]
	v_or_b32_e32 v11, v15, v11
	v_or_b32_e32 v10, v14, v10
	v_cvt_u32_f32_sdwa v14, v17 dst_sel:WORD_1 dst_unused:UNUSED_PAD src0_sel:DWORD
	v_cvt_u32_f32_sdwa v15, v16 dst_sel:WORD_1 dst_unused:UNUSED_PAD src0_sel:DWORD
	v_cvt_u32_f32_sdwa v9, v9 dst_sel:BYTE_3 dst_unused:UNUSED_PAD src0_sel:DWORD
	v_cvt_u32_f32_sdwa v8, v8 dst_sel:BYTE_3 dst_unused:UNUSED_PAD src0_sel:DWORD
	v_lshlrev_b64 v[12:13], 11, v[144:145]
	v_or_b32_e32 v11, v11, v14
	v_or_b32_e32 v10, v10, v15
	v_or_b32_e32 v9, v11, v9
	v_or_b32_e32 v8, v10, v8
	v_lshl_add_u64 v[10:11], s[12:13], 0, v[12:13]
	v_mul_f32_e32 v5, v5, v164
	v_mul_f32_e32 v6, v6, v164
	v_lshl_add_u64 v[10:11], v[10:11], 0, v[142:143]
	v_exp_f32_e32 v5, v5
	global_store_dwordx2 v[10:11], v[8:9], off
	v_exp_f32_e32 v8, v6
	v_mul_f32_e32 v6, v7, v164
	v_exp_f32_e32 v7, v6
	v_add_f32_e32 v5, 1.0, v5
	v_mul_f32_e32 v0, v0, v164
	v_rcp_f32_e32 v6, v5
	v_add_f32_e32 v5, 1.0, v8
	v_mul_f32_e32 v4, v4, v164
	v_rcp_f32_e32 v8, v5
	v_add_f32_e32 v5, 1.0, v7
	v_exp_f32_e32 v7, v0
	v_mul_f32_e32 v0, v1, v164
	v_exp_f32_e32 v4, v4
	v_exp_f32_e32 v1, v0
	v_mul_f32_e32 v2, v2, v164
	v_mul_f32_e32 v3, v3, v164
	v_add_f32_e32 v4, 1.0, v4
	v_rcp_f32_e32 v0, v5
	v_add_f32_e32 v5, 1.0, v7
	v_add_f32_e32 v1, 1.0, v1
	v_exp_f32_e32 v2, v2
	v_rcp_f32_e32 v4, v4
	v_rcp_f32_e32 v5, v5
	v_exp_f32_e32 v3, v3
	v_rcp_f32_e32 v7, v1
	v_add_f32_e32 v1, 1.0, v2
	v_rcp_f32_e32 v9, v1
	v_add_f32_e32 v1, 1.0, v3
	v_pk_fma_f32 v[2:3], v[4:5], s[14:15], 0.5 op_sel_hi:[1,0,0]
	v_pk_fma_f32 v[4:5], v[6:7], s[14:15], 0.5 op_sel_hi:[1,0,0]
	v_rcp_f32_e32 v1, v1
	v_cvt_u32_f32_e32 v5, v5
	v_cvt_u32_f32_e32 v4, v4
	v_cvt_u32_f32_e32 v3, v3
	v_cvt_u32_f32_e32 v2, v2
	v_pk_fma_f32 v[6:7], v[8:9], s[14:15], 0.5 op_sel_hi:[1,0,0]
	v_lshlrev_b32_e32 v5, 8, v5
	v_lshlrev_b32_e32 v4, 8, v4
	v_pk_fma_f32 v[0:1], v[0:1], s[14:15], 0.5 op_sel_hi:[1,0,0]
	v_or_b32_e32 v3, v5, v3
	v_or_b32_e32 v2, v4, v2
	v_cvt_u32_f32_sdwa v4, v7 dst_sel:WORD_1 dst_unused:UNUSED_PAD src0_sel:DWORD
	v_cvt_u32_f32_sdwa v5, v6 dst_sel:WORD_1 dst_unused:UNUSED_PAD src0_sel:DWORD
	v_cvt_u32_f32_sdwa v1, v1 dst_sel:BYTE_3 dst_unused:UNUSED_PAD src0_sel:DWORD
	v_cvt_u32_f32_sdwa v0, v0 dst_sel:BYTE_3 dst_unused:UNUSED_PAD src0_sel:DWORD
	v_or_b32_e32 v3, v3, v4
	v_or_b32_e32 v2, v2, v5
	v_or_b32_e32 v1, v3, v1
	v_or_b32_e32 v0, v2, v0
	v_lshl_add_u64 v[2:3], s[92:93], 0, v[12:13]
	v_lshl_add_u64 v[2:3], v[2:3], 0, v[142:143]
	v_add_co_u32_e32 v2, vcc, 0xb400000, v2
	s_nop 1
	v_addc_co_u32_e32 v3, vcc, 0, v3, vcc
	s_andn2_b64 vcc, exec, s[22:23]
	s_mov_b64 s[22:23], -1
	global_store_dwordx2 v[2:3], v[0:1], off offset:128
	s_cbranch_vccnz .LBB0_719
	s_andn2_b64 vcc, exec, s[4:5]
	s_cbranch_vccnz .LBB0_718
	s_barrier
	s_branch .LBB0_718

; __device__ __forceinline__ float sigmoidf_(float z) { return __builtin_amdgcn_rcpf(1.0f + __builtin_amdgcn_exp2f(-1.4426950408889634f * z)); }
;     __device__ __forceinline__ void load(Pre& p, const pg8::Unit& u, int ai, int m, int wr, int wc, int fr, int fq) const {
;         const int row = u.pm * 256 + ai * 128 + wr * 64 + m * 16 + fr;
;         if (MODE == EM_PROJ || MODE == EM_GATES) p.rs = ((const float*)(ws + WS_RINV0))[row];
;     __device__ __forceinline__ float compute(const Pre& p, f32x4 (&acc)[2][2][4][2], const f32x4 (&cv)[2][2], const pg8::Unit& u, int ai, int m, int wr, int wc, int fr, int fq) const {
;     ...
;             } else if (MODE == EM_GATES) {
;                 const int col = u.pn * 256 + ct; float w[8];
; #pragma unroll
;                 for (int j = 0; j < 8; ++j) w[j] = sigmoidf_(v[j] * rs) * 255.0f + 0.5f;
;                 u32x2 cd; cd.x = (unsigned)w[0] | ((unsigned)w[1] << 8) | ((unsigned)w[2] << 16) | ((unsigned)w[3] << 24); cd.y = (unsigned)w[4] | ((unsigned)w[5] << 8) | ((unsigned)w[6] << 16) | ((unsigned)w[7] << 24);
;                 *(u32x2*)(ws + WS_G8 + (size_t)row * 2048 + col) = cd;
.LBB0_807:
	v_lshl_add_u32 v162, s28, 8, v156
	v_ashrrev_i32_e32 v163, 31, v162
	v_lshl_add_u64 v[140:141], v[162:163], 2, s[12:13]
	global_load_dword v180, v[140:141], off
	v_or_b32_e32 v154, 16, v162
	v_or_b32_e32 v152, 32, v162
	v_or_b32_e32 v150, 48, v162
	v_add_u32_e32 v148, 0x80, v162
	v_add_u32_e32 v146, 0x90, v162
	v_add_u32_e32 v144, 0xa0, v162
	v_add_u32_e32 v142, 0xb0, v162
	v_ashrrev_i32_e32 v155, 31, v154
	v_ashrrev_i32_e32 v153, 31, v152
	v_ashrrev_i32_e32 v151, 31, v150
	v_ashrrev_i32_e32 v149, 31, v148
	v_ashrrev_i32_e32 v147, 31, v146
	v_ashrrev_i32_e32 v145, 31, v144
	v_ashrrev_i32_e32 v143, 31, v142
	v_lshlrev_b64 v[168:169], 11, v[162:163]
	v_lshl_add_u64 v[162:163], v[154:155], 2, s[12:13]
	v_lshl_add_u64 v[164:165], v[152:153], 2, s[12:13]
	v_lshl_add_u64 v[166:167], v[150:151], 2, s[12:13]
	v_lshl_add_u64 v[170:171], v[148:149], 2, s[12:13]
	v_lshl_add_u64 v[172:173], v[146:147], 2, s[12:13]
	v_lshl_add_u64 v[174:175], v[144:145], 2, s[12:13]
	v_lshl_add_u64 v[176:177], v[142:143], 2, s[12:13]
	global_load_dword v181, v[162:163], off
	global_load_dword v182, v[164:165], off
	s_nop 0
	global_load_dword v166, v[166:167], off
	s_nop 0
	global_load_dword v165, v[170:171], off
	global_load_dword v164, v[172:173], off
	global_load_dword v163, v[174:175], off
	global_load_dword v162, v[176:177], off
	v_lshl_or_b32 v140, s26, 8, v158
	v_ashrrev_i32_e32 v141, 31, v140
	v_lshl_add_u64 v[178:179], s[14:15], 0, v[168:169]
	v_lshl_add_u64 v[170:171], v[178:179], 0, v[140:141]
	s_waitcnt vmcnt(0)
	v_mul_f32_e32 v180, 0xbfb8aa3b, v180
	v_mul_f32_e32 v181, 0xbfb8aa3b, v181
	v_mul_f32_e32 v182, 0xbfb8aa3b, v182
	v_mul_f32_e32 v166, 0xbfb8aa3b, v166
	v_mul_f32_e32 v165, 0xbfb8aa3b, v165
	v_mul_f32_e32 v164, 0xbfb8aa3b, v164
	v_mul_f32_e32 v163, 0xbfb8aa3b, v163
	v_mul_f32_e32 v162, 0xbfb8aa3b, v162
	v_mul_f32_e32 v125, v125, v180
	v_mul_f32_e32 v121, v121, v180
	v_mul_f32_e32 v124, v124, v180
	v_mul_f32_e32 v126, v126, v180
	v_mul_f32_e32 v120, v120, v180
	v_exp_f32_e32 v125, v125
	v_exp_f32_e32 v121, v121
	v_mul_f32_e32 v127, v127, v180
	v_mul_f32_e32 v122, v122, v180
	v_exp_f32_e32 v124, v124
	v_exp_f32_e32 v126, v126
	v_exp_f32_e32 v120, v120
	v_mul_f32_e32 v123, v123, v180
	v_mul_f32_e32 v117, v117, v180
	v_mul_f32_e32 v116, v116, v180
	v_exp_f32_e32 v127, v127
	v_exp_f32_e32 v122, v122
	v_exp_f32_e32 v123, v123
	v_exp_f32_e32 v172, v117
	v_add_f32_e32 v117, 1.0, v125
	v_add_f32_e32 v121, 1.0, v121
	v_exp_f32_e32 v167, v116
	v_add_f32_e32 v116, 1.0, v124
	v_add_f32_e32 v124, 1.0, v126
	v_add_f32_e32 v126, 1.0, v120
	v_rcp_f32_e32 v120, v117
	v_rcp_f32_e32 v121, v121
	v_rcp_f32_e32 v116, v116
	v_rcp_f32_e32 v117, v126
	v_add_f32_e32 v125, 1.0, v127
	v_add_f32_e32 v127, 1.0, v122
	v_add_f32_e32 v173, 1.0, v123
	v_rcp_f32_e32 v122, v124
	v_rcp_f32_e32 v123, v127
	v_rcp_f32_e32 v124, v125
	v_rcp_f32_e32 v125, v173
	v_pk_fma_f32 v[120:121], v[120:121], s[20:21], 0.5 op_sel_hi:[1,0,0]
	v_pk_fma_f32 v[116:117], v[116:117], s[20:21], 0.5 op_sel_hi:[1,0,0]
	v_cvt_u32_f32_e32 v120, v120
	v_cvt_u32_f32_e32 v116, v116
	v_cvt_u32_f32_e32 v121, v121
	v_pk_fma_f32 v[122:123], v[122:123], s[20:21], 0.5 op_sel_hi:[1,0,0]
	v_cvt_u32_f32_e32 v117, v117
	v_pk_fma_f32 v[124:125], v[124:125], s[20:21], 0.5 op_sel_hi:[1,0,0]
	v_cvt_u32_f32_sdwa v122, v122 dst_sel:WORD_1 dst_unused:UNUSED_PAD src0_sel:DWORD
	v_cvt_u32_f32_sdwa v123, v123 dst_sel:WORD_1 dst_unused:UNUSED_PAD src0_sel:DWORD
	v_mul_f32_e32 v118, v118, v180
	v_cvt_u32_f32_sdwa v124, v124 dst_sel:BYTE_3 dst_unused:UNUSED_PAD src0_sel:DWORD
	v_cvt_u32_f32_sdwa v125, v125 dst_sel:BYTE_3 dst_unused:UNUSED_PAD src0_sel:DWORD
	v_lshlrev_b32_e32 v120, 8, v120
	v_lshlrev_b32_e32 v121, 8, v121
	v_or_b32_e32 v116, v120, v116
	v_exp_f32_e32 v120, v118
	v_mul_f32_e32 v118, v119, v180
	v_or_b32_e32 v117, v121, v117
	v_or_b32_e32 v117, v117, v123
	v_or_b32_e32 v116, v116, v122
	v_exp_f32_e32 v119, v118
	v_or_b32_e32 v117, v117, v125
	v_or_b32_e32 v116, v116, v124
	global_store_dwordx2 v[170:171], v[116:117], off
	v_add_f32_e32 v117, 1.0, v172
	v_mul_f32_e32 v112, v112, v180
	v_rcp_f32_e32 v118, v117
	v_add_f32_e32 v117, 1.0, v120
	v_rcp_f32_e32 v120, v117
	v_add_f32_e32 v117, 1.0, v119
	v_exp_f32_e32 v119, v112
	v_mul_f32_e32 v112, v113, v180
	v_exp_f32_e32 v113, v112
	v_mul_f32_e32 v114, v114, v180
	v_mul_f32_e32 v115, v115, v180
	v_add_f32_e32 v116, 1.0, v167
	v_rcp_f32_e32 v112, v117
	v_add_f32_e32 v117, 1.0, v119
	v_add_f32_e32 v113, 1.0, v113
	v_exp_f32_e32 v114, v114
	v_rcp_f32_e32 v116, v116
	v_rcp_f32_e32 v117, v117
	v_exp_f32_e32 v115, v115
	v_rcp_f32_e32 v119, v113
	v_add_f32_e32 v113, 1.0, v114
	v_rcp_f32_e32 v121, v113
	v_add_f32_e32 v113, 1.0, v115
	v_pk_fma_f32 v[114:115], v[116:117], s[20:21], 0.5 op_sel_hi:[1,0,0]
	v_pk_fma_f32 v[116:117], v[118:119], s[20:21], 0.5 op_sel_hi:[1,0,0]
	v_rcp_f32_e32 v113, v113
	v_cvt_u32_f32_e32 v117, v117
	v_cvt_u32_f32_e32 v116, v116
	v_cvt_u32_f32_e32 v115, v115
	v_cvt_u32_f32_e32 v114, v114
	v_pk_fma_f32 v[118:119], v[120:121], s[20:21], 0.5 op_sel_hi:[1,0,0]
	v_lshlrev_b32_e32 v117, 8, v117
	v_lshlrev_b32_e32 v116, 8, v116
	v_pk_fma_f32 v[112:113], v[112:113], s[20:21], 0.5 op_sel_hi:[1,0,0]
	v_or_b32_e32 v115, v117, v115
	v_or_b32_e32 v114, v116, v114
	v_cvt_u32_f32_sdwa v116, v119 dst_sel:WORD_1 dst_unused:UNUSED_PAD src0_sel:DWORD
	v_cvt_u32_f32_sdwa v117, v118 dst_sel:WORD_1 dst_unused:UNUSED_PAD src0_sel:DWORD
	v_cvt_u32_f32_sdwa v113, v113 dst_sel:BYTE_3 dst_unused:UNUSED_PAD src0_sel:DWORD
	v_cvt_u32_f32_sdwa v112, v112 dst_sel:BYTE_3 dst_unused:UNUSED_PAD src0_sel:DWORD
	v_or_b32_e32 v115, v115, v116
	v_or_b32_e32 v114, v114, v117
; __device__ __forceinline__ float sigmoidf_(float z) { return __builtin_amdgcn_rcpf(1.0f + __builtin_amdgcn_exp2f(-1.4426950408889634f * z)); }
;     __device__ __forceinline__ float compute(const Pre& p, f32x4 (&acc)[2][2][4][2], const f32x4 (&cv)[2][2], const pg8::Unit& u, int ai, int m, int wr, int wc, int fr, int fq) const {
;     ...
;             } else if (MODE == EM_GATES) {
;                 const int col = u.pn * 256 + ct; float w[8];
; #pragma unroll
;                 for (int j = 0; j < 8; ++j) w[j] = sigmoidf_(v[j] * rs) * 255.0f + 0.5f;
;                 u32x2 cd; cd.x = (unsigned)w[0] | ((unsigned)w[1] << 8) | ((unsigned)w[2] << 16) | ((unsigned)w[3] << 24); cd.y = (unsigned)w[4] | ((unsigned)w[5] << 8) | ((unsigned)w[6] << 16) | ((unsigned)w[7] << 24);
;                 *(u32x2*)(ws + WS_G8 + (size_t)row * 2048 + col) = cd;
	v_or_b32_e32 v113, v115, v113
	v_or_b32_e32 v112, v114, v112
	v_lshl_add_u64 v[114:115], s[92:93], 0, v[168:169]
	v_lshl_add_u64 v[114:115], v[114:115], 0, v[140:141]
	v_add_co_u32_e32 v114, vcc, s50, v114
	v_mul_f32_e32 v108, v108, v181
	s_nop 0
	v_addc_co_u32_e32 v115, vcc, 0, v115, vcc
	global_store_dwordx2 v[114:115], v[112:113], off offset:128
	v_exp_f32_e32 v112, v108
	v_mul_f32_e32 v108, v109, v181
	v_mul_f32_e32 v110, v110, v181
	v_exp_f32_e32 v113, v108
	v_exp_f32_e32 v114, v110
	v_mul_f32_e32 v110, v111, v181
	v_add_f32_e32 v113, 1.0, v113
	v_mul_f32_e32 v104, v104, v181
	v_exp_f32_e32 v111, v110
	v_rcp_f32_e32 v110, v113
	v_add_f32_e32 v113, 1.0, v114
	v_rcp_f32_e32 v114, v113
	v_exp_f32_e32 v113, v104
	v_mul_f32_e32 v104, v105, v181
	v_exp_f32_e32 v105, v104
	v_add_f32_e32 v111, 1.0, v111
	v_mul_f32_e32 v106, v106, v181
	v_rcp_f32_e32 v104, v111
	v_add_f32_e32 v111, 1.0, v113
	v_add_f32_e32 v105, 1.0, v105
	v_mul_f32_e32 v107, v107, v181
	v_add_f32_e32 v112, 1.0, v112
	v_rcp_f32_e32 v113, v111
	v_exp_f32_e32 v106, v106
	v_rcp_f32_e32 v111, v105
	v_rcp_f32_e32 v112, v112
	v_exp_f32_e32 v107, v107
	v_add_f32_e32 v105, 1.0, v106
	v_pk_fma_f32 v[110:111], v[110:111], s[20:21], 0.5 op_sel_hi:[1,0,0]
	v_rcp_f32_e32 v115, v105
	v_add_f32_e32 v105, 1.0, v107
	v_pk_fma_f32 v[106:107], v[112:113], s[20:21], 0.5 op_sel_hi:[1,0,0]
	v_cvt_u32_f32_e32 v111, v111
	v_cvt_u32_f32_e32 v110, v110
	v_rcp_f32_e32 v105, v105
	v_cvt_u32_f32_e32 v107, v107
	v_cvt_u32_f32_e32 v106, v106
	v_pk_fma_f32 v[112:113], v[114:115], s[20:21], 0.5 op_sel_hi:[1,0,0]
	v_lshlrev_b32_e32 v111, 8, v111
	v_lshlrev_b32_e32 v110, 8, v110
	v_pk_fma_f32 v[104:105], v[104:105], s[20:21], 0.5 op_sel_hi:[1,0,0]
	v_or_b32_e32 v107, v111, v107
	v_or_b32_e32 v106, v110, v106
	v_cvt_u32_f32_sdwa v110, v113 dst_sel:WORD_1 dst_unused:UNUSED_PAD src0_sel:DWORD
	v_cvt_u32_f32_sdwa v111, v112 dst_sel:WORD_1 dst_unused:UNUSED_PAD src0_sel:DWORD
	v_cvt_u32_f32_sdwa v105, v105 dst_sel:BYTE_3 dst_unused:UNUSED_PAD src0_sel:DWORD
	v_cvt_u32_f32_sdwa v104, v104 dst_sel:BYTE_3 dst_unused:UNUSED_PAD src0_sel:DWORD
	v_lshlrev_b64 v[108:109], 11, v[154:155]
	v_or_b32_e32 v107, v107, v110
	v_or_b32_e32 v106, v106, v111
	v_or_b32_e32 v105, v107, v105
	v_or_b32_e32 v104, v106, v104
	v_lshl_add_u64 v[106:107], s[14:15], 0, v[108:109]
	v_mul_f32_e32 v101, v101, v181
	v_mul_f32_e32 v102, v102, v181
	v_lshl_add_u64 v[106:107], v[106:107], 0, v[140:141]
	v_exp_f32_e32 v101, v101
	global_store_dwordx2 v[106:107], v[104:105], off
	v_exp_f32_e32 v104, v102
	v_mul_f32_e32 v102, v103, v181
	v_exp_f32_e32 v103, v102
	v_add_f32_e32 v101, 1.0, v101
	v_mul_f32_e32 v96, v96, v181
	v_rcp_f32_e32 v102, v101
	v_add_f32_e32 v101, 1.0, v104
	v_mul_f32_e32 v100, v100, v181
	v_rcp_f32_e32 v104, v101
	v_add_f32_e32 v101, 1.0, v103
	v_exp_f32_e32 v103, v96
	v_mul_f32_e32 v96, v97, v181
	v_exp_f32_e32 v100, v100
	v_exp_f32_e32 v97, v96
	v_mul_f32_e32 v98, v98, v181
	v_mul_f32_e32 v99, v99, v181
	v_add_f32_e32 v100, 1.0, v100
	v_rcp_f32_e32 v96, v101
	v_add_f32_e32 v101, 1.0, v103
	v_add_f32_e32 v97, 1.0, v97
	v_exp_f32_e32 v98, v98
	v_rcp_f32_e32 v100, v100
	v_rcp_f32_e32 v101, v101
	v_exp_f32_e32 v99, v99
	v_rcp_f32_e32 v103, v97
	v_add_f32_e32 v97, 1.0, v98
	v_rcp_f32_e32 v105, v97
	v_add_f32_e32 v97, 1.0, v99
	v_pk_fma_f32 v[98:99], v[100:101], s[20:21], 0.5 op_sel_hi:[1,0,0]
	v_pk_fma_f32 v[100:101], v[102:103], s[20:21], 0.5 op_sel_hi:[1,0,0]
	v_rcp_f32_e32 v97, v97
	v_cvt_u32_f32_e32 v101, v101
	v_cvt_u32_f32_e32 v100, v100
	v_cvt_u32_f32_e32 v99, v99
	v_cvt_u32_f32_e32 v98, v98
	v_pk_fma_f32 v[102:103], v[104:105], s[20:21], 0.5 op_sel_hi:[1,0,0]
	v_lshlrev_b32_e32 v101, 8, v101
	v_lshlrev_b32_e32 v100, 8, v100
	v_pk_fma_f32 v[96:97], v[96:97], s[20:21], 0.5 op_sel_hi:[1,0,0]
	v_or_b32_e32 v99, v101, v99
	v_or_b32_e32 v98, v100, v98
	v_cvt_u32_f32_sdwa v100, v103 dst_sel:WORD_1 dst_unused:UNUSED_PAD src0_sel:DWORD
	v_cvt_u32_f32_sdwa v101, v102 dst_sel:WORD_1 dst_unused:UNUSED_PAD src0_sel:DWORD
	v_cvt_u32_f32_sdwa v97, v97 dst_sel:BYTE_3 dst_unused:UNUSED_PAD src0_sel:DWORD
	v_cvt_u32_f32_sdwa v96, v96 dst_sel:BYTE_3 dst_unused:UNUSED_PAD src0_sel:DWORD
	v_or_b32_e32 v99, v99, v100
	v_or_b32_e32 v98, v98, v101
	v_or_b32_e32 v97, v99, v97
	v_or_b32_e32 v96, v98, v96
	v_lshl_add_u64 v[98:99], s[92:93], 0, v[108:109]
	v_lshl_add_u64 v[98:99], v[98:99], 0, v[140:141]
	v_add_co_u32_e32 v98, vcc, s50, v98
	v_mul_f32_e32 v92, v92, v182
	s_nop 0
	v_addc_co_u32_e32 v99, vcc, 0, v99, vcc
	global_store_dwordx2 v[98:99], v[96:97], off offset:128
	v_exp_f32_e32 v96, v92
	v_mul_f32_e32 v92, v93, v182
	v_mul_f32_e32 v94, v94, v182
	v_exp_f32_e32 v97, v92
	v_exp_f32_e32 v98, v94
	v_mul_f32_e32 v94, v95, v182
	v_add_f32_e32 v97, 1.0, v97
	v_mul_f32_e32 v88, v88, v182
	v_exp_f32_e32 v95, v94
	v_rcp_f32_e32 v94, v97
	v_add_f32_e32 v97, 1.0, v98
	v_rcp_f32_e32 v98, v97
	v_exp_f32_e32 v97, v88
	v_mul_f32_e32 v88, v89, v182
	v_exp_f32_e32 v89, v88
	v_add_f32_e32 v95, 1.0, v95
	v_mul_f32_e32 v90, v90, v182
	v_rcp_f32_e32 v88, v95
	v_add_f32_e32 v95, 1.0, v97
	v_add_f32_e32 v89, 1.0, v89
	v_mul_f32_e32 v91, v91, v182
	v_add_f32_e32 v96, 1.0, v96
	v_rcp_f32_e32 v97, v95
	v_exp_f32_e32 v90, v90
	v_rcp_f32_e32 v95, v89
	v_rcp_f32_e32 v96, v96
	v_exp_f32_e32 v91, v91
	v_add_f32_e32 v89, 1.0, v90
	v_pk_fma_f32 v[94:95], v[94:95], s[20:21], 0.5 op_sel_hi:[1,0,0]
	v_rcp_f32_e32 v99, v89
	v_add_f32_e32 v89, 1.0, v91
	v_pk_fma_f32 v[90:91], v[96:97], s[20:21], 0.5 op_sel_hi:[1,0,0]
	v_cvt_u32_f32_e32 v95, v95
	v_cvt_u32_f32_e32 v94, v94
	v_rcp_f32_e32 v89, v89
	v_cvt_u32_f32_e32 v91, v91
	v_cvt_u32_f32_e32 v90, v90
; __device__ __forceinline__ float sigmoidf_(float z) { return __builtin_amdgcn_rcpf(1.0f + __builtin_amdgcn_exp2f(-1.4426950408889634f * z)); }
;     __device__ __forceinline__ float compute(const Pre& p, f32x4 (&acc)[2][2][4][2], const f32x4 (&cv)[2][2], const pg8::Unit& u, int ai, int m, int wr, int wc, int fr, int fq) const {
;     ...
;             } else if (MODE == EM_GATES) {
;                 const int col = u.pn * 256 + ct; float w[8];
; #pragma unroll
;                 for (int j = 0; j < 8; ++j) w[j] = sigmoidf_(v[j] * rs) * 255.0f + 0.5f;
;                 u32x2 cd; cd.x = (unsigned)w[0] | ((unsigned)w[1] << 8) | ((unsigned)w[2] << 16) | ((unsigned)w[3] << 24); cd.y = (unsigned)w[4] | ((unsigned)w[5] << 8) | ((unsigned)w[6] << 16) | ((unsigned)w[7] << 24);
;                 *(u32x2*)(ws + WS_G8 + (size_t)row * 2048 + col) = cd;
	v_pk_fma_f32 v[96:97], v[98:99], s[20:21], 0.5 op_sel_hi:[1,0,0]
	v_lshlrev_b32_e32 v95, 8, v95
	v_lshlrev_b32_e32 v94, 8, v94
	v_pk_fma_f32 v[88:89], v[88:89], s[20:21], 0.5 op_sel_hi:[1,0,0]
	v_or_b32_e32 v91, v95, v91
	v_or_b32_e32 v90, v94, v90
	v_cvt_u32_f32_sdwa v94, v97 dst_sel:WORD_1 dst_unused:UNUSED_PAD src0_sel:DWORD
	v_cvt_u32_f32_sdwa v95, v96 dst_sel:WORD_1 dst_unused:UNUSED_PAD src0_sel:DWORD
	v_cvt_u32_f32_sdwa v89, v89 dst_sel:BYTE_3 dst_unused:UNUSED_PAD src0_sel:DWORD
	v_cvt_u32_f32_sdwa v88, v88 dst_sel:BYTE_3 dst_unused:UNUSED_PAD src0_sel:DWORD
	v_lshlrev_b64 v[92:93], 11, v[152:153]
	v_or_b32_e32 v91, v91, v94
	v_or_b32_e32 v90, v90, v95
	v_or_b32_e32 v89, v91, v89
	v_or_b32_e32 v88, v90, v88
	v_lshl_add_u64 v[90:91], s[14:15], 0, v[92:93]
	v_mul_f32_e32 v85, v85, v182
	v_mul_f32_e32 v86, v86, v182
	v_lshl_add_u64 v[90:91], v[90:91], 0, v[140:141]
	v_exp_f32_e32 v85, v85
	global_store_dwordx2 v[90:91], v[88:89], off
	v_exp_f32_e32 v88, v86
	v_mul_f32_e32 v86, v87, v182
	v_exp_f32_e32 v87, v86
	v_add_f32_e32 v85, 1.0, v85
	v_mul_f32_e32 v80, v80, v182
	v_rcp_f32_e32 v86, v85
	v_add_f32_e32 v85, 1.0, v88
	v_mul_f32_e32 v84, v84, v182
	v_rcp_f32_e32 v88, v85
	v_add_f32_e32 v85, 1.0, v87
	v_exp_f32_e32 v87, v80
	v_mul_f32_e32 v80, v81, v182
	v_exp_f32_e32 v84, v84
	v_exp_f32_e32 v81, v80
	v_mul_f32_e32 v82, v82, v182
	v_mul_f32_e32 v83, v83, v182
	v_add_f32_e32 v84, 1.0, v84
	v_rcp_f32_e32 v80, v85
	v_add_f32_e32 v85, 1.0, v87
	v_add_f32_e32 v81, 1.0, v81
	v_exp_f32_e32 v82, v82
	v_rcp_f32_e32 v84, v84
	v_rcp_f32_e32 v85, v85
	v_exp_f32_e32 v83, v83
	v_rcp_f32_e32 v87, v81
	v_add_f32_e32 v81, 1.0, v82
	v_rcp_f32_e32 v89, v81
	v_add_f32_e32 v81, 1.0, v83
	v_pk_fma_f32 v[82:83], v[84:85], s[20:21], 0.5 op_sel_hi:[1,0,0]
	v_pk_fma_f32 v[84:85], v[86:87], s[20:21], 0.5 op_sel_hi:[1,0,0]
	v_rcp_f32_e32 v81, v81
	v_cvt_u32_f32_e32 v85, v85
	v_cvt_u32_f32_e32 v84, v84
	v_cvt_u32_f32_e32 v83, v83
	v_cvt_u32_f32_e32 v82, v82
	v_pk_fma_f32 v[86:87], v[88:89], s[20:21], 0.5 op_sel_hi:[1,0,0]
	v_lshlrev_b32_e32 v85, 8, v85
	v_lshlrev_b32_e32 v84, 8, v84
	v_pk_fma_f32 v[80:81], v[80:81], s[20:21], 0.5 op_sel_hi:[1,0,0]
	v_or_b32_e32 v83, v85, v83
	v_or_b32_e32 v82, v84, v82
	v_cvt_u32_f32_sdwa v84, v87 dst_sel:WORD_1 dst_unused:UNUSED_PAD src0_sel:DWORD
	v_cvt_u32_f32_sdwa v85, v86 dst_sel:WORD_1 dst_unused:UNUSED_PAD src0_sel:DWORD
	v_cvt_u32_f32_sdwa v81, v81 dst_sel:BYTE_3 dst_unused:UNUSED_PAD src0_sel:DWORD
	v_cvt_u32_f32_sdwa v80, v80 dst_sel:BYTE_3 dst_unused:UNUSED_PAD src0_sel:DWORD
	v_or_b32_e32 v83, v83, v84
	v_or_b32_e32 v82, v82, v85
	v_or_b32_e32 v81, v83, v81
	v_or_b32_e32 v80, v82, v80
	v_lshl_add_u64 v[82:83], s[92:93], 0, v[92:93]
	v_lshl_add_u64 v[82:83], v[82:83], 0, v[140:141]
	v_add_co_u32_e32 v82, vcc, s50, v82
	v_mul_f32_e32 v76, v76, v166
	s_nop 0
	v_addc_co_u32_e32 v83, vcc, 0, v83, vcc
	global_store_dwordx2 v[82:83], v[80:81], off offset:128
	v_exp_f32_e32 v80, v76
	v_mul_f32_e32 v76, v77, v166
	v_mul_f32_e32 v78, v78, v166
	v_exp_f32_e32 v81, v76
	v_exp_f32_e32 v82, v78
	v_mul_f32_e32 v78, v79, v166
	v_add_f32_e32 v81, 1.0, v81
	v_mul_f32_e32 v72, v72, v166
	v_exp_f32_e32 v79, v78
	v_rcp_f32_e32 v78, v81
	v_add_f32_e32 v81, 1.0, v82
	v_rcp_f32_e32 v82, v81
	v_exp_f32_e32 v81, v72
	v_mul_f32_e32 v72, v73, v166
	v_exp_f32_e32 v73, v72
	v_add_f32_e32 v79, 1.0, v79
	v_mul_f32_e32 v74, v74, v166
	v_rcp_f32_e32 v72, v79
	v_add_f32_e32 v79, 1.0, v81
	v_add_f32_e32 v73, 1.0, v73
	v_mul_f32_e32 v75, v75, v166
	v_add_f32_e32 v80, 1.0, v80
	v_rcp_f32_e32 v81, v79
	v_exp_f32_e32 v74, v74
	v_rcp_f32_e32 v79, v73
	v_rcp_f32_e32 v80, v80
	v_exp_f32_e32 v75, v75
	v_add_f32_e32 v73, 1.0, v74
	v_pk_fma_f32 v[78:79], v[78:79], s[20:21], 0.5 op_sel_hi:[1,0,0]
	v_rcp_f32_e32 v83, v73
	v_add_f32_e32 v73, 1.0, v75
	v_pk_fma_f32 v[74:75], v[80:81], s[20:21], 0.5 op_sel_hi:[1,0,0]
	v_cvt_u32_f32_e32 v79, v79
	v_cvt_u32_f32_e32 v78, v78
	v_rcp_f32_e32 v73, v73
	v_cvt_u32_f32_e32 v75, v75
	v_cvt_u32_f32_e32 v74, v74
	v_pk_fma_f32 v[80:81], v[82:83], s[20:21], 0.5 op_sel_hi:[1,0,0]
	v_lshlrev_b32_e32 v79, 8, v79
	v_lshlrev_b32_e32 v78, 8, v78
	v_pk_fma_f32 v[72:73], v[72:73], s[20:21], 0.5 op_sel_hi:[1,0,0]
	v_or_b32_e32 v75, v79, v75
	v_or_b32_e32 v74, v78, v74
	v_cvt_u32_f32_sdwa v78, v81 dst_sel:WORD_1 dst_unused:UNUSED_PAD src0_sel:DWORD
	v_cvt_u32_f32_sdwa v79, v80 dst_sel:WORD_1 dst_unused:UNUSED_PAD src0_sel:DWORD
	v_cvt_u32_f32_sdwa v73, v73 dst_sel:BYTE_3 dst_unused:UNUSED_PAD src0_sel:DWORD
	v_cvt_u32_f32_sdwa v72, v72 dst_sel:BYTE_3 dst_unused:UNUSED_PAD src0_sel:DWORD
	v_lshlrev_b64 v[76:77], 11, v[150:151]
	v_or_b32_e32 v75, v75, v78
	v_or_b32_e32 v74, v74, v79
	v_or_b32_e32 v73, v75, v73
	v_or_b32_e32 v72, v74, v72
	v_lshl_add_u64 v[74:75], s[14:15], 0, v[76:77]
	v_mul_f32_e32 v69, v69, v166
	v_mul_f32_e32 v70, v70, v166
	v_lshl_add_u64 v[74:75], v[74:75], 0, v[140:141]
	v_exp_f32_e32 v69, v69
	global_store_dwordx2 v[74:75], v[72:73], off
	v_exp_f32_e32 v72, v70
	v_mul_f32_e32 v70, v71, v166
	v_exp_f32_e32 v71, v70
	v_add_f32_e32 v69, 1.0, v69
	v_mul_f32_e32 v64, v64, v166
	v_rcp_f32_e32 v70, v69
	v_add_f32_e32 v69, 1.0, v72
	v_mul_f32_e32 v68, v68, v166
	v_rcp_f32_e32 v72, v69
	v_add_f32_e32 v69, 1.0, v71
	v_exp_f32_e32 v71, v64
	v_mul_f32_e32 v64, v65, v166
	v_exp_f32_e32 v68, v68
	v_exp_f32_e32 v65, v64
	v_mul_f32_e32 v66, v66, v166
	v_mul_f32_e32 v67, v67, v166
	v_add_f32_e32 v68, 1.0, v68
	v_rcp_f32_e32 v64, v69
	v_add_f32_e32 v69, 1.0, v71
	v_add_f32_e32 v65, 1.0, v65
	v_exp_f32_e32 v66, v66
	v_rcp_f32_e32 v68, v68
	v_rcp_f32_e32 v69, v69
	v_exp_f32_e32 v67, v67
	v_rcp_f32_e32 v71, v65
	v_add_f32_e32 v65, 1.0, v66
; __device__ __forceinline__ float sigmoidf_(float z) { return __builtin_amdgcn_rcpf(1.0f + __builtin_amdgcn_exp2f(-1.4426950408889634f * z)); }
;     __device__ __forceinline__ float compute(const Pre& p, f32x4 (&acc)[2][2][4][2], const f32x4 (&cv)[2][2], const pg8::Unit& u, int ai, int m, int wr, int wc, int fr, int fq) const {
;     ...
;                 const int col = u.pn * 256 + ct; float w[8];
; #pragma unroll
;                 for (int j = 0; j < 8; ++j) w[j] = sigmoidf_(v[j] * rs) * 255.0f + 0.5f;
;                 u32x2 cd; cd.x = (unsigned)w[0] | ((unsigned)w[1] << 8) | ((unsigned)w[2] << 16) | ((unsigned)w[3] << 24); cd.y = (unsigned)w[4] | ((unsigned)w[5] << 8) | ((unsigned)w[6] << 16) | ((unsigned)w[7] << 24);
;                 *(u32x2*)(ws + WS_G8 + (size_t)row * 2048 + col) = cd;
	v_rcp_f32_e32 v73, v65
	v_add_f32_e32 v65, 1.0, v67
	v_pk_fma_f32 v[66:67], v[68:69], s[20:21], 0.5 op_sel_hi:[1,0,0]
	v_pk_fma_f32 v[68:69], v[70:71], s[20:21], 0.5 op_sel_hi:[1,0,0]
	v_rcp_f32_e32 v65, v65
	v_cvt_u32_f32_e32 v69, v69
	v_cvt_u32_f32_e32 v68, v68
	v_cvt_u32_f32_e32 v67, v67
	v_cvt_u32_f32_e32 v66, v66
	v_pk_fma_f32 v[70:71], v[72:73], s[20:21], 0.5 op_sel_hi:[1,0,0]
	v_lshlrev_b32_e32 v69, 8, v69
	v_lshlrev_b32_e32 v68, 8, v68
	v_pk_fma_f32 v[64:65], v[64:65], s[20:21], 0.5 op_sel_hi:[1,0,0]
	v_or_b32_e32 v67, v69, v67
	v_or_b32_e32 v66, v68, v66
	v_cvt_u32_f32_sdwa v68, v71 dst_sel:WORD_1 dst_unused:UNUSED_PAD src0_sel:DWORD
	v_cvt_u32_f32_sdwa v69, v70 dst_sel:WORD_1 dst_unused:UNUSED_PAD src0_sel:DWORD
	v_cvt_u32_f32_sdwa v65, v65 dst_sel:BYTE_3 dst_unused:UNUSED_PAD src0_sel:DWORD
	v_cvt_u32_f32_sdwa v64, v64 dst_sel:BYTE_3 dst_unused:UNUSED_PAD src0_sel:DWORD
	v_or_b32_e32 v67, v67, v68
	v_or_b32_e32 v66, v66, v69
	v_or_b32_e32 v65, v67, v65
	v_or_b32_e32 v64, v66, v64
	v_lshl_add_u64 v[66:67], s[92:93], 0, v[76:77]
	v_lshl_add_u64 v[66:67], v[66:67], 0, v[140:141]
	v_add_co_u32_e32 v66, vcc, s50, v66
	v_mul_f32_e32 v60, v60, v165
	s_nop 0
	v_addc_co_u32_e32 v67, vcc, 0, v67, vcc
	global_store_dwordx2 v[66:67], v[64:65], off offset:128
	v_exp_f32_e32 v64, v60
	v_mul_f32_e32 v60, v61, v165
	v_mul_f32_e32 v62, v62, v165
	v_exp_f32_e32 v65, v60
	v_exp_f32_e32 v66, v62
	v_mul_f32_e32 v62, v63, v165
	v_add_f32_e32 v65, 1.0, v65
	v_mul_f32_e32 v56, v56, v165
	v_exp_f32_e32 v63, v62
	v_rcp_f32_e32 v62, v65
	v_add_f32_e32 v65, 1.0, v66
	v_rcp_f32_e32 v66, v65
	v_exp_f32_e32 v65, v56
	v_mul_f32_e32 v56, v57, v165
	v_exp_f32_e32 v57, v56
	v_add_f32_e32 v63, 1.0, v63
	v_mul_f32_e32 v58, v58, v165
	v_rcp_f32_e32 v56, v63
	v_add_f32_e32 v63, 1.0, v65
	v_add_f32_e32 v57, 1.0, v57
	v_mul_f32_e32 v59, v59, v165
	v_add_f32_e32 v64, 1.0, v64
	v_rcp_f32_e32 v65, v63
	v_exp_f32_e32 v58, v58
	v_rcp_f32_e32 v63, v57
	v_rcp_f32_e32 v64, v64
	v_exp_f32_e32 v59, v59
	v_add_f32_e32 v57, 1.0, v58
	v_pk_fma_f32 v[62:63], v[62:63], s[20:21], 0.5 op_sel_hi:[1,0,0]
	v_rcp_f32_e32 v67, v57
	v_add_f32_e32 v57, 1.0, v59
	v_pk_fma_f32 v[58:59], v[64:65], s[20:21], 0.5 op_sel_hi:[1,0,0]
	v_cvt_u32_f32_e32 v63, v63
	v_cvt_u32_f32_e32 v62, v62
	v_rcp_f32_e32 v57, v57
	v_cvt_u32_f32_e32 v59, v59
	v_cvt_u32_f32_e32 v58, v58
	v_pk_fma_f32 v[64:65], v[66:67], s[20:21], 0.5 op_sel_hi:[1,0,0]
	v_lshlrev_b32_e32 v63, 8, v63
	v_lshlrev_b32_e32 v62, 8, v62
	v_pk_fma_f32 v[56:57], v[56:57], s[20:21], 0.5 op_sel_hi:[1,0,0]
	v_or_b32_e32 v59, v63, v59
	v_or_b32_e32 v58, v62, v58
	v_cvt_u32_f32_sdwa v62, v65 dst_sel:WORD_1 dst_unused:UNUSED_PAD src0_sel:DWORD
	v_cvt_u32_f32_sdwa v63, v64 dst_sel:WORD_1 dst_unused:UNUSED_PAD src0_sel:DWORD
	v_cvt_u32_f32_sdwa v57, v57 dst_sel:BYTE_3 dst_unused:UNUSED_PAD src0_sel:DWORD
	v_cvt_u32_f32_sdwa v56, v56 dst_sel:BYTE_3 dst_unused:UNUSED_PAD src0_sel:DWORD
	v_lshlrev_b64 v[60:61], 11, v[148:149]
	v_or_b32_e32 v59, v59, v62
	v_or_b32_e32 v58, v58, v63
	v_or_b32_e32 v57, v59, v57
	v_or_b32_e32 v56, v58, v56
	v_lshl_add_u64 v[58:59], s[14:15], 0, v[60:61]
	v_mul_f32_e32 v53, v53, v165
	v_mul_f32_e32 v54, v54, v165
	v_lshl_add_u64 v[58:59], v[58:59], 0, v[140:141]
	v_exp_f32_e32 v53, v53
	global_store_dwordx2 v[58:59], v[56:57], off
	v_exp_f32_e32 v56, v54
	v_mul_f32_e32 v54, v55, v165
	v_exp_f32_e32 v55, v54
	v_add_f32_e32 v53, 1.0, v53
	v_mul_f32_e32 v48, v48, v165
	v_rcp_f32_e32 v54, v53
	v_add_f32_e32 v53, 1.0, v56
	v_mul_f32_e32 v52, v52, v165
	v_rcp_f32_e32 v56, v53
	v_add_f32_e32 v53, 1.0, v55
	v_exp_f32_e32 v55, v48
	v_mul_f32_e32 v48, v49, v165
	v_exp_f32_e32 v52, v52
	v_exp_f32_e32 v49, v48
	v_mul_f32_e32 v50, v50, v165
	v_mul_f32_e32 v51, v51, v165
	v_add_f32_e32 v52, 1.0, v52
	v_rcp_f32_e32 v48, v53
	v_add_f32_e32 v53, 1.0, v55
	v_add_f32_e32 v49, 1.0, v49
	v_exp_f32_e32 v50, v50
	v_rcp_f32_e32 v52, v52
	v_rcp_f32_e32 v53, v53
	v_exp_f32_e32 v51, v51
	v_rcp_f32_e32 v55, v49
	v_add_f32_e32 v49, 1.0, v50
	v_rcp_f32_e32 v57, v49
	v_add_f32_e32 v49, 1.0, v51
	v_pk_fma_f32 v[50:51], v[52:53], s[20:21], 0.5 op_sel_hi:[1,0,0]
	v_pk_fma_f32 v[52:53], v[54:55], s[20:21], 0.5 op_sel_hi:[1,0,0]
	v_rcp_f32_e32 v49, v49
	v_cvt_u32_f32_e32 v53, v53
	v_cvt_u32_f32_e32 v52, v52
	v_cvt_u32_f32_e32 v51, v51
	v_cvt_u32_f32_e32 v50, v50
	v_pk_fma_f32 v[54:55], v[56:57], s[20:21], 0.5 op_sel_hi:[1,0,0]
	v_lshlrev_b32_e32 v53, 8, v53
	v_lshlrev_b32_e32 v52, 8, v52
	v_pk_fma_f32 v[48:49], v[48:49], s[20:21], 0.5 op_sel_hi:[1,0,0]
	v_or_b32_e32 v51, v53, v51
	v_or_b32_e32 v50, v52, v50
	v_cvt_u32_f32_sdwa v52, v55 dst_sel:WORD_1 dst_unused:UNUSED_PAD src0_sel:DWORD
	v_cvt_u32_f32_sdwa v53, v54 dst_sel:WORD_1 dst_unused:UNUSED_PAD src0_sel:DWORD
	v_cvt_u32_f32_sdwa v49, v49 dst_sel:BYTE_3 dst_unused:UNUSED_PAD src0_sel:DWORD
	v_cvt_u32_f32_sdwa v48, v48 dst_sel:BYTE_3 dst_unused:UNUSED_PAD src0_sel:DWORD
	v_or_b32_e32 v51, v51, v52
	v_or_b32_e32 v50, v50, v53
	v_or_b32_e32 v49, v51, v49
	v_or_b32_e32 v48, v50, v48
	v_lshl_add_u64 v[50:51], s[92:93], 0, v[60:61]
	v_lshl_add_u64 v[50:51], v[50:51], 0, v[140:141]
	v_add_co_u32_e32 v50, vcc, s50, v50
	v_mul_f32_e32 v44, v44, v164
	s_nop 0
	v_addc_co_u32_e32 v51, vcc, 0, v51, vcc
	global_store_dwordx2 v[50:51], v[48:49], off offset:128
	v_exp_f32_e32 v48, v44
	v_mul_f32_e32 v44, v45, v164
	v_mul_f32_e32 v46, v46, v164
	v_exp_f32_e32 v49, v44
	v_exp_f32_e32 v50, v46
	v_mul_f32_e32 v46, v47, v164
	v_add_f32_e32 v49, 1.0, v49
	v_mul_f32_e32 v40, v40, v164
	v_exp_f32_e32 v47, v46
	v_rcp_f32_e32 v46, v49
	v_add_f32_e32 v49, 1.0, v50
	v_rcp_f32_e32 v50, v49
	v_exp_f32_e32 v49, v40
	v_mul_f32_e32 v40, v41, v164
; __device__ __forceinline__ float sigmoidf_(float z) { return __builtin_amdgcn_rcpf(1.0f + __builtin_amdgcn_exp2f(-1.4426950408889634f * z)); }
;     __device__ __forceinline__ float compute(const Pre& p, f32x4 (&acc)[2][2][4][2], const f32x4 (&cv)[2][2], const pg8::Unit& u, int ai, int m, int wr, int wc, int fr, int fq) const {
;     ...
;                 const int col = u.pn * 256 + ct; float w[8];
; #pragma unroll
;                 for (int j = 0; j < 8; ++j) w[j] = sigmoidf_(v[j] * rs) * 255.0f + 0.5f;
;                 u32x2 cd; cd.x = (unsigned)w[0] | ((unsigned)w[1] << 8) | ((unsigned)w[2] << 16) | ((unsigned)w[3] << 24); cd.y = (unsigned)w[4] | ((unsigned)w[5] << 8) | ((unsigned)w[6] << 16) | ((unsigned)w[7] << 24);
;                 *(u32x2*)(ws + WS_G8 + (size_t)row * 2048 + col) = cd;
	v_exp_f32_e32 v41, v40
	v_add_f32_e32 v47, 1.0, v47
	v_mul_f32_e32 v42, v42, v164
	v_rcp_f32_e32 v40, v47
	v_add_f32_e32 v47, 1.0, v49
	v_add_f32_e32 v41, 1.0, v41
	v_mul_f32_e32 v43, v43, v164
	v_add_f32_e32 v48, 1.0, v48
	v_rcp_f32_e32 v49, v47
	v_exp_f32_e32 v42, v42
	v_rcp_f32_e32 v47, v41
	v_rcp_f32_e32 v48, v48
	v_exp_f32_e32 v43, v43
	v_add_f32_e32 v41, 1.0, v42
	v_pk_fma_f32 v[46:47], v[46:47], s[20:21], 0.5 op_sel_hi:[1,0,0]
	v_rcp_f32_e32 v51, v41
	v_add_f32_e32 v41, 1.0, v43
	v_pk_fma_f32 v[42:43], v[48:49], s[20:21], 0.5 op_sel_hi:[1,0,0]
	v_cvt_u32_f32_e32 v47, v47
	v_cvt_u32_f32_e32 v46, v46
	v_rcp_f32_e32 v41, v41
	v_cvt_u32_f32_e32 v43, v43
	v_cvt_u32_f32_e32 v42, v42
	v_pk_fma_f32 v[48:49], v[50:51], s[20:21], 0.5 op_sel_hi:[1,0,0]
	v_lshlrev_b32_e32 v47, 8, v47
	v_lshlrev_b32_e32 v46, 8, v46
	v_pk_fma_f32 v[40:41], v[40:41], s[20:21], 0.5 op_sel_hi:[1,0,0]
	v_or_b32_e32 v43, v47, v43
	v_or_b32_e32 v42, v46, v42
	v_cvt_u32_f32_sdwa v46, v49 dst_sel:WORD_1 dst_unused:UNUSED_PAD src0_sel:DWORD
	v_cvt_u32_f32_sdwa v47, v48 dst_sel:WORD_1 dst_unused:UNUSED_PAD src0_sel:DWORD
	v_cvt_u32_f32_sdwa v41, v41 dst_sel:BYTE_3 dst_unused:UNUSED_PAD src0_sel:DWORD
	v_cvt_u32_f32_sdwa v40, v40 dst_sel:BYTE_3 dst_unused:UNUSED_PAD src0_sel:DWORD
	v_lshlrev_b64 v[44:45], 11, v[146:147]
	v_or_b32_e32 v43, v43, v46
	v_or_b32_e32 v42, v42, v47
	v_or_b32_e32 v41, v43, v41
	v_or_b32_e32 v40, v42, v40
	v_lshl_add_u64 v[42:43], s[14:15], 0, v[44:45]
	v_mul_f32_e32 v37, v37, v164
	v_mul_f32_e32 v38, v38, v164
	v_lshl_add_u64 v[42:43], v[42:43], 0, v[140:141]
	v_exp_f32_e32 v37, v37
	global_store_dwordx2 v[42:43], v[40:41], off
	v_exp_f32_e32 v40, v38
	v_mul_f32_e32 v38, v39, v164
	v_exp_f32_e32 v39, v38
	v_add_f32_e32 v37, 1.0, v37
	v_mul_f32_e32 v32, v32, v164
	v_rcp_f32_e32 v38, v37
	v_add_f32_e32 v37, 1.0, v40
	v_mul_f32_e32 v36, v36, v164
	v_rcp_f32_e32 v40, v37
	v_add_f32_e32 v37, 1.0, v39
	v_exp_f32_e32 v39, v32
	v_mul_f32_e32 v32, v33, v164
	v_exp_f32_e32 v36, v36
	v_exp_f32_e32 v33, v32
	v_mul_f32_e32 v34, v34, v164
	v_mul_f32_e32 v35, v35, v164
	v_add_f32_e32 v36, 1.0, v36
	v_rcp_f32_e32 v32, v37
	v_add_f32_e32 v37, 1.0, v39
	v_add_f32_e32 v33, 1.0, v33
	v_exp_f32_e32 v34, v34
	v_rcp_f32_e32 v36, v36
	v_rcp_f32_e32 v37, v37
	v_exp_f32_e32 v35, v35
	v_rcp_f32_e32 v39, v33
	v_add_f32_e32 v33, 1.0, v34
	v_rcp_f32_e32 v41, v33
	v_add_f32_e32 v33, 1.0, v35
	v_pk_fma_f32 v[34:35], v[36:37], s[20:21], 0.5 op_sel_hi:[1,0,0]
	v_pk_fma_f32 v[36:37], v[38:39], s[20:21], 0.5 op_sel_hi:[1,0,0]
	v_rcp_f32_e32 v33, v33
	v_cvt_u32_f32_e32 v37, v37
	v_cvt_u32_f32_e32 v36, v36
	v_cvt_u32_f32_e32 v35, v35
	v_cvt_u32_f32_e32 v34, v34
	v_pk_fma_f32 v[38:39], v[40:41], s[20:21], 0.5 op_sel_hi:[1,0,0]
	v_lshlrev_b32_e32 v37, 8, v37
	v_lshlrev_b32_e32 v36, 8, v36
	v_pk_fma_f32 v[32:33], v[32:33], s[20:21], 0.5 op_sel_hi:[1,0,0]
	v_or_b32_e32 v35, v37, v35
	v_or_b32_e32 v34, v36, v34
	v_cvt_u32_f32_sdwa v36, v39 dst_sel:WORD_1 dst_unused:UNUSED_PAD src0_sel:DWORD
	v_cvt_u32_f32_sdwa v37, v38 dst_sel:WORD_1 dst_unused:UNUSED_PAD src0_sel:DWORD
	v_cvt_u32_f32_sdwa v33, v33 dst_sel:BYTE_3 dst_unused:UNUSED_PAD src0_sel:DWORD
	v_cvt_u32_f32_sdwa v32, v32 dst_sel:BYTE_3 dst_unused:UNUSED_PAD src0_sel:DWORD
	v_or_b32_e32 v35, v35, v36
	v_or_b32_e32 v34, v34, v37
	v_or_b32_e32 v33, v35, v33
	v_or_b32_e32 v32, v34, v32
	v_lshl_add_u64 v[34:35], s[92:93], 0, v[44:45]
	v_lshl_add_u64 v[34:35], v[34:35], 0, v[140:141]
	v_add_co_u32_e32 v34, vcc, s50, v34
	v_mul_f32_e32 v28, v28, v163
	s_nop 0
	v_addc_co_u32_e32 v35, vcc, 0, v35, vcc
	global_store_dwordx2 v[34:35], v[32:33], off offset:128
	v_exp_f32_e32 v32, v28
	v_mul_f32_e32 v28, v29, v163
	v_mul_f32_e32 v30, v30, v163
	v_exp_f32_e32 v33, v28
	v_exp_f32_e32 v34, v30
	v_mul_f32_e32 v30, v31, v163
	v_add_f32_e32 v33, 1.0, v33
	v_mul_f32_e32 v24, v24, v163
	v_exp_f32_e32 v31, v30
	v_rcp_f32_e32 v30, v33
	v_add_f32_e32 v33, 1.0, v34
	v_rcp_f32_e32 v34, v33
	v_exp_f32_e32 v33, v24
	v_mul_f32_e32 v24, v25, v163
	v_exp_f32_e32 v25, v24
	v_add_f32_e32 v31, 1.0, v31
	v_mul_f32_e32 v26, v26, v163
	v_rcp_f32_e32 v24, v31
	v_add_f32_e32 v31, 1.0, v33
	v_add_f32_e32 v25, 1.0, v25
	v_mul_f32_e32 v27, v27, v163
	v_add_f32_e32 v32, 1.0, v32
	v_rcp_f32_e32 v33, v31
	v_exp_f32_e32 v26, v26
	v_rcp_f32_e32 v31, v25
	v_rcp_f32_e32 v32, v32
	v_exp_f32_e32 v27, v27
	v_add_f32_e32 v25, 1.0, v26
	v_pk_fma_f32 v[30:31], v[30:31], s[20:21], 0.5 op_sel_hi:[1,0,0]
	v_rcp_f32_e32 v35, v25
	v_add_f32_e32 v25, 1.0, v27
	v_pk_fma_f32 v[26:27], v[32:33], s[20:21], 0.5 op_sel_hi:[1,0,0]
	v_cvt_u32_f32_e32 v31, v31
	v_cvt_u32_f32_e32 v30, v30
	v_rcp_f32_e32 v25, v25
	v_cvt_u32_f32_e32 v27, v27
	v_cvt_u32_f32_e32 v26, v26
	v_pk_fma_f32 v[32:33], v[34:35], s[20:21], 0.5 op_sel_hi:[1,0,0]
	v_lshlrev_b32_e32 v31, 8, v31
	v_lshlrev_b32_e32 v30, 8, v30
	v_pk_fma_f32 v[24:25], v[24:25], s[20:21], 0.5 op_sel_hi:[1,0,0]
	v_or_b32_e32 v27, v31, v27
	v_or_b32_e32 v26, v30, v26
	v_cvt_u32_f32_sdwa v30, v33 dst_sel:WORD_1 dst_unused:UNUSED_PAD src0_sel:DWORD
	v_cvt_u32_f32_sdwa v31, v32 dst_sel:WORD_1 dst_unused:UNUSED_PAD src0_sel:DWORD
	v_cvt_u32_f32_sdwa v25, v25 dst_sel:BYTE_3 dst_unused:UNUSED_PAD src0_sel:DWORD
	v_cvt_u32_f32_sdwa v24, v24 dst_sel:BYTE_3 dst_unused:UNUSED_PAD src0_sel:DWORD
	v_lshlrev_b64 v[28:29], 11, v[144:145]
	v_or_b32_e32 v27, v27, v30
	v_or_b32_e32 v26, v26, v31
	v_or_b32_e32 v25, v27, v25
	v_or_b32_e32 v24, v26, v24
	v_lshl_add_u64 v[26:27], s[14:15], 0, v[28:29]
	v_mul_f32_e32 v21, v21, v163
	v_mul_f32_e32 v22, v22, v163
	v_lshl_add_u64 v[26:27], v[26:27], 0, v[140:141]
	v_exp_f32_e32 v21, v21
	global_store_dwordx2 v[26:27], v[24:25], off
; __device__ __forceinline__ float sigmoidf_(float z) { return __builtin_amdgcn_rcpf(1.0f + __builtin_amdgcn_exp2f(-1.4426950408889634f * z)); }
;     __device__ __forceinline__ float compute(const Pre& p, f32x4 (&acc)[2][2][4][2], const f32x4 (&cv)[2][2], const pg8::Unit& u, int ai, int m, int wr, int wc, int fr, int fq) const {
;     ...
;                 const int col = u.pn * 256 + ct; float w[8];
; #pragma unroll
;                 for (int j = 0; j < 8; ++j) w[j] = sigmoidf_(v[j] * rs) * 255.0f + 0.5f;
;                 u32x2 cd; cd.x = (unsigned)w[0] | ((unsigned)w[1] << 8) | ((unsigned)w[2] << 16) | ((unsigned)w[3] << 24); cd.y = (unsigned)w[4] | ((unsigned)w[5] << 8) | ((unsigned)w[6] << 16) | ((unsigned)w[7] << 24);
;                 *(u32x2*)(ws + WS_G8 + (size_t)row * 2048 + col) = cd;
	v_exp_f32_e32 v24, v22
	v_mul_f32_e32 v22, v23, v163
	v_exp_f32_e32 v23, v22
	v_add_f32_e32 v21, 1.0, v21
	v_mul_f32_e32 v16, v16, v163
	v_rcp_f32_e32 v22, v21
	v_add_f32_e32 v21, 1.0, v24
	v_mul_f32_e32 v20, v20, v163
	v_rcp_f32_e32 v24, v21
	v_add_f32_e32 v21, 1.0, v23
	v_exp_f32_e32 v23, v16
	v_mul_f32_e32 v16, v17, v163
	v_exp_f32_e32 v20, v20
	v_exp_f32_e32 v17, v16
	v_mul_f32_e32 v18, v18, v163
	v_mul_f32_e32 v19, v19, v163
	v_add_f32_e32 v20, 1.0, v20
	v_rcp_f32_e32 v16, v21
	v_add_f32_e32 v21, 1.0, v23
	v_add_f32_e32 v17, 1.0, v17
	v_exp_f32_e32 v18, v18
	v_rcp_f32_e32 v20, v20
	v_rcp_f32_e32 v21, v21
	v_exp_f32_e32 v19, v19
	v_rcp_f32_e32 v23, v17
	v_add_f32_e32 v17, 1.0, v18
	v_rcp_f32_e32 v25, v17
	v_add_f32_e32 v17, 1.0, v19
	v_pk_fma_f32 v[18:19], v[20:21], s[20:21], 0.5 op_sel_hi:[1,0,0]
	v_pk_fma_f32 v[20:21], v[22:23], s[20:21], 0.5 op_sel_hi:[1,0,0]
	v_rcp_f32_e32 v17, v17
	v_cvt_u32_f32_e32 v21, v21
	v_cvt_u32_f32_e32 v20, v20
	v_cvt_u32_f32_e32 v19, v19
	v_cvt_u32_f32_e32 v18, v18
	v_pk_fma_f32 v[22:23], v[24:25], s[20:21], 0.5 op_sel_hi:[1,0,0]
	v_lshlrev_b32_e32 v21, 8, v21
	v_lshlrev_b32_e32 v20, 8, v20
	v_pk_fma_f32 v[16:17], v[16:17], s[20:21], 0.5 op_sel_hi:[1,0,0]
	v_or_b32_e32 v19, v21, v19
	v_or_b32_e32 v18, v20, v18
	v_cvt_u32_f32_sdwa v20, v23 dst_sel:WORD_1 dst_unused:UNUSED_PAD src0_sel:DWORD
	v_cvt_u32_f32_sdwa v21, v22 dst_sel:WORD_1 dst_unused:UNUSED_PAD src0_sel:DWORD
	v_cvt_u32_f32_sdwa v17, v17 dst_sel:BYTE_3 dst_unused:UNUSED_PAD src0_sel:DWORD
	v_cvt_u32_f32_sdwa v16, v16 dst_sel:BYTE_3 dst_unused:UNUSED_PAD src0_sel:DWORD
	v_or_b32_e32 v19, v19, v20
	v_or_b32_e32 v18, v18, v21
	v_or_b32_e32 v17, v19, v17
	v_or_b32_e32 v16, v18, v16
	v_lshl_add_u64 v[18:19], s[92:93], 0, v[28:29]
	v_lshl_add_u64 v[18:19], v[18:19], 0, v[140:141]
	v_add_co_u32_e32 v18, vcc, s50, v18
	v_mul_f32_e32 v12, v12, v162
	s_nop 0
	v_addc_co_u32_e32 v19, vcc, 0, v19, vcc
	global_store_dwordx2 v[18:19], v[16:17], off offset:128
	v_exp_f32_e32 v16, v12
	v_mul_f32_e32 v12, v13, v162
	v_mul_f32_e32 v14, v14, v162
	v_exp_f32_e32 v17, v12
	v_exp_f32_e32 v18, v14
	v_mul_f32_e32 v14, v15, v162
	v_add_f32_e32 v17, 1.0, v17
	v_mul_f32_e32 v8, v8, v162
	v_exp_f32_e32 v15, v14
	v_rcp_f32_e32 v14, v17
	v_add_f32_e32 v17, 1.0, v18
	v_rcp_f32_e32 v18, v17
	v_exp_f32_e32 v17, v8
	v_mul_f32_e32 v8, v9, v162
	v_exp_f32_e32 v9, v8
	v_add_f32_e32 v15, 1.0, v15
	v_mul_f32_e32 v10, v10, v162
	v_rcp_f32_e32 v8, v15
	v_add_f32_e32 v15, 1.0, v17
	v_add_f32_e32 v9, 1.0, v9
	v_mul_f32_e32 v11, v11, v162
	v_add_f32_e32 v16, 1.0, v16
	v_rcp_f32_e32 v17, v15
	v_exp_f32_e32 v10, v10
	v_rcp_f32_e32 v15, v9
	v_rcp_f32_e32 v16, v16
	v_exp_f32_e32 v11, v11
	v_add_f32_e32 v9, 1.0, v10
	v_pk_fma_f32 v[14:15], v[14:15], s[20:21], 0.5 op_sel_hi:[1,0,0]
	v_rcp_f32_e32 v19, v9
	v_add_f32_e32 v9, 1.0, v11
	v_pk_fma_f32 v[10:11], v[16:17], s[20:21], 0.5 op_sel_hi:[1,0,0]
	v_cvt_u32_f32_e32 v15, v15
	v_cvt_u32_f32_e32 v14, v14
	v_rcp_f32_e32 v9, v9
	v_cvt_u32_f32_e32 v11, v11
	v_cvt_u32_f32_e32 v10, v10
	v_pk_fma_f32 v[16:17], v[18:19], s[20:21], 0.5 op_sel_hi:[1,0,0]
	v_lshlrev_b32_e32 v15, 8, v15
	v_lshlrev_b32_e32 v14, 8, v14
	v_pk_fma_f32 v[8:9], v[8:9], s[20:21], 0.5 op_sel_hi:[1,0,0]
	v_or_b32_e32 v11, v15, v11
	v_or_b32_e32 v10, v14, v10
	v_cvt_u32_f32_sdwa v14, v17 dst_sel:WORD_1 dst_unused:UNUSED_PAD src0_sel:DWORD
	v_cvt_u32_f32_sdwa v15, v16 dst_sel:WORD_1 dst_unused:UNUSED_PAD src0_sel:DWORD
	v_cvt_u32_f32_sdwa v9, v9 dst_sel:BYTE_3 dst_unused:UNUSED_PAD src0_sel:DWORD
	v_cvt_u32_f32_sdwa v8, v8 dst_sel:BYTE_3 dst_unused:UNUSED_PAD src0_sel:DWORD
	v_lshlrev_b64 v[12:13], 11, v[142:143]
	v_or_b32_e32 v11, v11, v14
	v_or_b32_e32 v10, v10, v15
	v_or_b32_e32 v9, v11, v9
	v_or_b32_e32 v8, v10, v8
	v_lshl_add_u64 v[10:11], s[14:15], 0, v[12:13]
	v_mul_f32_e32 v5, v5, v162
	v_mul_f32_e32 v6, v6, v162
	v_lshl_add_u64 v[10:11], v[10:11], 0, v[140:141]
	v_exp_f32_e32 v5, v5
	global_store_dwordx2 v[10:11], v[8:9], off
	v_exp_f32_e32 v8, v6
	v_mul_f32_e32 v6, v7, v162
	v_exp_f32_e32 v7, v6
	v_add_f32_e32 v5, 1.0, v5
	v_mul_f32_e32 v0, v0, v162
	v_rcp_f32_e32 v6, v5
	v_add_f32_e32 v5, 1.0, v8
	v_mul_f32_e32 v4, v4, v162
	v_rcp_f32_e32 v8, v5
	v_add_f32_e32 v5, 1.0, v7
	v_exp_f32_e32 v7, v0
	v_mul_f32_e32 v0, v1, v162
	v_exp_f32_e32 v4, v4
	v_exp_f32_e32 v1, v0
	v_mul_f32_e32 v2, v2, v162
	v_mul_f32_e32 v3, v3, v162
	v_add_f32_e32 v4, 1.0, v4
	v_rcp_f32_e32 v0, v5
	v_add_f32_e32 v5, 1.0, v7
	v_add_f32_e32 v1, 1.0, v1
	v_exp_f32_e32 v2, v2
	v_rcp_f32_e32 v4, v4
	v_rcp_f32_e32 v5, v5
	v_exp_f32_e32 v3, v3
	v_rcp_f32_e32 v7, v1
	v_add_f32_e32 v1, 1.0, v2
	v_rcp_f32_e32 v9, v1
	v_add_f32_e32 v1, 1.0, v3
	v_pk_fma_f32 v[2:3], v[4:5], s[20:21], 0.5 op_sel_hi:[1,0,0]
	v_pk_fma_f32 v[4:5], v[6:7], s[20:21], 0.5 op_sel_hi:[1,0,0]
	v_rcp_f32_e32 v1, v1
	v_cvt_u32_f32_e32 v5, v5
	v_cvt_u32_f32_e32 v4, v4
	v_cvt_u32_f32_e32 v3, v3
	v_cvt_u32_f32_e32 v2, v2
	v_pk_fma_f32 v[6:7], v[8:9], s[20:21], 0.5 op_sel_hi:[1,0,0]
	v_lshlrev_b32_e32 v5, 8, v5
	v_lshlrev_b32_e32 v4, 8, v4
	v_pk_fma_f32 v[0:1], v[0:1], s[20:21], 0.5 op_sel_hi:[1,0,0]
	v_or_b32_e32 v3, v5, v3
	v_or_b32_e32 v2, v4, v2
	v_cvt_u32_f32_sdwa v4, v7 dst_sel:WORD_1 dst_unused:UNUSED_PAD src0_sel:DWORD
	v_cvt_u32_f32_sdwa v5, v6 dst_sel:WORD_1 dst_unused:UNUSED_PAD src0_sel:DWORD
	v_cvt_u32_f32_sdwa v1, v1 dst_sel:BYTE_3 dst_unused:UNUSED_PAD src0_sel:DWORD
	v_cvt_u32_f32_sdwa v0, v0 dst_sel:BYTE_3 dst_unused:UNUSED_PAD src0_sel:DWORD
	v_or_b32_e32 v3, v3, v4
	v_or_b32_e32 v2, v2, v5
	v_or_b32_e32 v1, v3, v1
	v_or_b32_e32 v0, v2, v0
	v_lshl_add_u64 v[2:3], s[92:93], 0, v[12:13]
	v_lshl_add_u64 v[2:3], v[2:3], 0, v[140:141]
	v_add_co_u32_e32 v2, vcc, 0xb400000, v2
	s_nop 1
	v_addc_co_u32_e32 v3, vcc, 0, v3, vcc
	s_and_b64 vcc, exec, s[4:5]
	s_mov_b64 s[4:5], -1
	global_store_dwordx2 v[2:3], v[0:1], off offset:128
	s_cbranch_vccnz .LBB0_802
	s_andn2_b64 vcc, exec, s[6:7]
	s_cbranch_vccnz .LBB0_801
	s_barrier
	s_branch .LBB0_801

; __device__ __forceinline__ float sigmoidf_(float z) { return __builtin_amdgcn_rcpf(1.0f + __builtin_amdgcn_exp2f(-1.4426950408889634f * z)); }
;     __device__ __forceinline__ void load(Pre& p, const pg8::Unit& u, int ai, int m, int wr, int wc, int fr, int fq) const {
;         const int row = u.pm * 256 + ai * 128 + wr * 64 + m * 16 + fr;
;         if (MODE == EM_PROJ || MODE == EM_GATES) p.rs = ((const float*)(ws + WS_RINV0))[row];
;     __device__ __forceinline__ float compute(const Pre& p, f32x4 (&acc)[2][2][4][2], const f32x4 (&cv)[2][2], const pg8::Unit& u, int ai, int m, int wr, int wc, int fr, int fq) const {
;     ...
;                 const int col = u.pn * 256 + ct; float w[8];
; #pragma unroll
;                 for (int j = 0; j < 8; ++j) w[j] = sigmoidf_(v[j] * rs) * 255.0f + 0.5f;
;                 u32x2 cd; cd.x = (unsigned)w[0] | ((unsigned)w[1] << 8) | ((unsigned)w[2] << 16) | ((unsigned)w[3] << 24); cd.y = (unsigned)w[4] | ((unsigned)w[5] << 8) | ((unsigned)w[6] << 16) | ((unsigned)w[7] << 24);
;                 *(u32x2*)(ws + WS_G8 + (size_t)row * 2048 + col) = cd;
.LBB0_866:
	v_lshl_add_u32 v162, s28, 8, v156
	v_ashrrev_i32_e32 v163, 31, v162
	v_lshl_add_u64 v[140:141], v[162:163], 2, s[12:13]
	global_load_dword v180, v[140:141], off
	v_or_b32_e32 v154, 16, v162
	v_or_b32_e32 v152, 32, v162
	v_or_b32_e32 v150, 48, v162
	v_add_u32_e32 v148, 0x80, v162
	v_add_u32_e32 v146, 0x90, v162
	v_add_u32_e32 v144, 0xa0, v162
	v_add_u32_e32 v142, 0xb0, v162
	v_ashrrev_i32_e32 v155, 31, v154
	v_ashrrev_i32_e32 v153, 31, v152
	v_ashrrev_i32_e32 v151, 31, v150
	v_ashrrev_i32_e32 v149, 31, v148
	v_ashrrev_i32_e32 v147, 31, v146
	v_ashrrev_i32_e32 v145, 31, v144
	v_ashrrev_i32_e32 v143, 31, v142
	v_lshlrev_b64 v[168:169], 11, v[162:163]
	v_lshl_add_u64 v[162:163], v[154:155], 2, s[12:13]
	v_lshl_add_u64 v[164:165], v[152:153], 2, s[12:13]
	v_lshl_add_u64 v[166:167], v[150:151], 2, s[12:13]
	v_lshl_add_u64 v[170:171], v[148:149], 2, s[12:13]
	v_lshl_add_u64 v[172:173], v[146:147], 2, s[12:13]
	v_lshl_add_u64 v[174:175], v[144:145], 2, s[12:13]
	v_lshl_add_u64 v[176:177], v[142:143], 2, s[12:13]
	global_load_dword v181, v[162:163], off
	global_load_dword v182, v[164:165], off
	s_nop 0
	global_load_dword v166, v[166:167], off
	s_nop 0
	global_load_dword v165, v[170:171], off
	global_load_dword v164, v[172:173], off
	global_load_dword v163, v[174:175], off
	global_load_dword v162, v[176:177], off
	v_lshl_or_b32 v140, s26, 8, v158
	v_ashrrev_i32_e32 v141, 31, v140
	v_lshl_add_u64 v[178:179], s[14:15], 0, v[168:169]
	v_lshl_add_u64 v[170:171], v[178:179], 0, v[140:141]
	s_waitcnt vmcnt(0)
	v_mul_f32_e32 v180, 0xbfb8aa3b, v180
	v_mul_f32_e32 v181, 0xbfb8aa3b, v181
	v_mul_f32_e32 v182, 0xbfb8aa3b, v182
	v_mul_f32_e32 v166, 0xbfb8aa3b, v166
	v_mul_f32_e32 v165, 0xbfb8aa3b, v165
	v_mul_f32_e32 v164, 0xbfb8aa3b, v164
	v_mul_f32_e32 v163, 0xbfb8aa3b, v163
	v_mul_f32_e32 v162, 0xbfb8aa3b, v162
	v_mul_f32_e32 v125, v125, v180
	v_mul_f32_e32 v121, v121, v180
	v_mul_f32_e32 v124, v124, v180
	v_mul_f32_e32 v126, v126, v180
	v_mul_f32_e32 v120, v120, v180
	v_exp_f32_e32 v125, v125
	v_exp_f32_e32 v121, v121
	v_mul_f32_e32 v127, v127, v180
	v_mul_f32_e32 v122, v122, v180
	v_exp_f32_e32 v124, v124
	v_exp_f32_e32 v126, v126
	v_exp_f32_e32 v120, v120
	v_mul_f32_e32 v123, v123, v180
	v_mul_f32_e32 v117, v117, v180
	v_mul_f32_e32 v116, v116, v180
	v_exp_f32_e32 v127, v127
	v_exp_f32_e32 v122, v122
	v_exp_f32_e32 v123, v123
	v_exp_f32_e32 v172, v117
	v_add_f32_e32 v117, 1.0, v125
	v_add_f32_e32 v121, 1.0, v121
	v_exp_f32_e32 v167, v116
	v_add_f32_e32 v116, 1.0, v124
	v_add_f32_e32 v124, 1.0, v126
	v_add_f32_e32 v126, 1.0, v120
	v_rcp_f32_e32 v120, v117
	v_rcp_f32_e32 v121, v121
	v_rcp_f32_e32 v116, v116
	v_rcp_f32_e32 v117, v126
	v_add_f32_e32 v125, 1.0, v127
	v_add_f32_e32 v127, 1.0, v122
	v_add_f32_e32 v173, 1.0, v123
	v_rcp_f32_e32 v122, v124
	v_rcp_f32_e32 v123, v127
	v_rcp_f32_e32 v124, v125
	v_rcp_f32_e32 v125, v173
	v_pk_fma_f32 v[120:121], v[120:121], s[20:21], 0.5 op_sel_hi:[1,0,0]
	v_pk_fma_f32 v[116:117], v[116:117], s[20:21], 0.5 op_sel_hi:[1,0,0]
	v_cvt_u32_f32_e32 v120, v120
	v_cvt_u32_f32_e32 v116, v116
	v_cvt_u32_f32_e32 v121, v121
	v_pk_fma_f32 v[122:123], v[122:123], s[20:21], 0.5 op_sel_hi:[1,0,0]
	v_cvt_u32_f32_e32 v117, v117
	v_pk_fma_f32 v[124:125], v[124:125], s[20:21], 0.5 op_sel_hi:[1,0,0]
	v_cvt_u32_f32_sdwa v122, v122 dst_sel:WORD_1 dst_unused:UNUSED_PAD src0_sel:DWORD
	v_cvt_u32_f32_sdwa v123, v123 dst_sel:WORD_1 dst_unused:UNUSED_PAD src0_sel:DWORD
	v_mul_f32_e32 v118, v118, v180
	v_cvt_u32_f32_sdwa v124, v124 dst_sel:BYTE_3 dst_unused:UNUSED_PAD src0_sel:DWORD
	v_cvt_u32_f32_sdwa v125, v125 dst_sel:BYTE_3 dst_unused:UNUSED_PAD src0_sel:DWORD
	v_lshlrev_b32_e32 v120, 8, v120
	v_lshlrev_b32_e32 v121, 8, v121
	v_or_b32_e32 v116, v120, v116
	v_exp_f32_e32 v120, v118
	v_mul_f32_e32 v118, v119, v180
	v_or_b32_e32 v117, v121, v117
	v_or_b32_e32 v117, v117, v123
	v_or_b32_e32 v116, v116, v122
	v_exp_f32_e32 v119, v118
	v_or_b32_e32 v117, v117, v125
	v_or_b32_e32 v116, v116, v124
	global_store_dwordx2 v[170:171], v[116:117], off
	v_add_f32_e32 v117, 1.0, v172
	v_mul_f32_e32 v112, v112, v180
	v_rcp_f32_e32 v118, v117
	v_add_f32_e32 v117, 1.0, v120
	v_rcp_f32_e32 v120, v117
	v_add_f32_e32 v117, 1.0, v119
	v_exp_f32_e32 v119, v112
	v_mul_f32_e32 v112, v113, v180
	v_exp_f32_e32 v113, v112
	v_mul_f32_e32 v114, v114, v180
	v_mul_f32_e32 v115, v115, v180
	v_add_f32_e32 v116, 1.0, v167
	v_rcp_f32_e32 v112, v117
	v_add_f32_e32 v117, 1.0, v119
	v_add_f32_e32 v113, 1.0, v113
	v_exp_f32_e32 v114, v114
	v_rcp_f32_e32 v116, v116
	v_rcp_f32_e32 v117, v117
	v_exp_f32_e32 v115, v115
	v_rcp_f32_e32 v119, v113
	v_add_f32_e32 v113, 1.0, v114
	v_rcp_f32_e32 v121, v113
	v_add_f32_e32 v113, 1.0, v115
	v_pk_fma_f32 v[114:115], v[116:117], s[20:21], 0.5 op_sel_hi:[1,0,0]
	v_pk_fma_f32 v[116:117], v[118:119], s[20:21], 0.5 op_sel_hi:[1,0,0]
	v_rcp_f32_e32 v113, v113
	v_cvt_u32_f32_e32 v117, v117
	v_cvt_u32_f32_e32 v116, v116
	v_cvt_u32_f32_e32 v115, v115
	v_cvt_u32_f32_e32 v114, v114
	v_pk_fma_f32 v[118:119], v[120:121], s[20:21], 0.5 op_sel_hi:[1,0,0]
	v_lshlrev_b32_e32 v117, 8, v117
	v_lshlrev_b32_e32 v116, 8, v116
	v_pk_fma_f32 v[112:113], v[112:113], s[20:21], 0.5 op_sel_hi:[1,0,0]
	v_or_b32_e32 v115, v117, v115
	v_or_b32_e32 v114, v116, v114
	v_cvt_u32_f32_sdwa v116, v119 dst_sel:WORD_1 dst_unused:UNUSED_PAD src0_sel:DWORD
	v_cvt_u32_f32_sdwa v117, v118 dst_sel:WORD_1 dst_unused:UNUSED_PAD src0_sel:DWORD
	v_cvt_u32_f32_sdwa v113, v113 dst_sel:BYTE_3 dst_unused:UNUSED_PAD src0_sel:DWORD
	v_cvt_u32_f32_sdwa v112, v112 dst_sel:BYTE_3 dst_unused:UNUSED_PAD src0_sel:DWORD
	v_or_b32_e32 v115, v115, v116
	v_or_b32_e32 v114, v114, v117
; __device__ __forceinline__ float sigmoidf_(float z) { return __builtin_amdgcn_rcpf(1.0f + __builtin_amdgcn_exp2f(-1.4426950408889634f * z)); }
;     __device__ __forceinline__ float compute(const Pre& p, f32x4 (&acc)[2][2][4][2], const f32x4 (&cv)[2][2], const pg8::Unit& u, int ai, int m, int wr, int wc, int fr, int fq) const {
;     ...
;                 const int col = u.pn * 256 + ct; float w[8];
; #pragma unroll
;                 for (int j = 0; j < 8; ++j) w[j] = sigmoidf_(v[j] * rs) * 255.0f + 0.5f;
;                 u32x2 cd; cd.x = (unsigned)w[0] | ((unsigned)w[1] << 8) | ((unsigned)w[2] << 16) | ((unsigned)w[3] << 24); cd.y = (unsigned)w[4] | ((unsigned)w[5] << 8) | ((unsigned)w[6] << 16) | ((unsigned)w[7] << 24);
;                 *(u32x2*)(ws + WS_G8 + (size_t)row * 2048 + col) = cd;
	v_or_b32_e32 v113, v115, v113
	v_or_b32_e32 v112, v114, v112
	v_lshl_add_u64 v[114:115], s[92:93], 0, v[168:169]
	v_lshl_add_u64 v[114:115], v[114:115], 0, v[140:141]
	v_add_co_u32_e32 v114, vcc, s45, v114
	v_mul_f32_e32 v108, v108, v181
	s_nop 0
	v_addc_co_u32_e32 v115, vcc, 0, v115, vcc
	global_store_dwordx2 v[114:115], v[112:113], off offset:128
	v_exp_f32_e32 v112, v108
	v_mul_f32_e32 v108, v109, v181
	v_mul_f32_e32 v110, v110, v181
	v_exp_f32_e32 v113, v108
	v_exp_f32_e32 v114, v110
	v_mul_f32_e32 v110, v111, v181
	v_add_f32_e32 v113, 1.0, v113
	v_mul_f32_e32 v104, v104, v181
	v_exp_f32_e32 v111, v110
	v_rcp_f32_e32 v110, v113
	v_add_f32_e32 v113, 1.0, v114
	v_rcp_f32_e32 v114, v113
	v_exp_f32_e32 v113, v104
	v_mul_f32_e32 v104, v105, v181
	v_exp_f32_e32 v105, v104
	v_add_f32_e32 v111, 1.0, v111
	v_mul_f32_e32 v106, v106, v181
	v_rcp_f32_e32 v104, v111
	v_add_f32_e32 v111, 1.0, v113
	v_add_f32_e32 v105, 1.0, v105
	v_mul_f32_e32 v107, v107, v181
	v_add_f32_e32 v112, 1.0, v112
	v_rcp_f32_e32 v113, v111
	v_exp_f32_e32 v106, v106
	v_rcp_f32_e32 v111, v105
	v_rcp_f32_e32 v112, v112
	v_exp_f32_e32 v107, v107
	v_add_f32_e32 v105, 1.0, v106
	v_pk_fma_f32 v[110:111], v[110:111], s[20:21], 0.5 op_sel_hi:[1,0,0]
	v_rcp_f32_e32 v115, v105
	v_add_f32_e32 v105, 1.0, v107
	v_pk_fma_f32 v[106:107], v[112:113], s[20:21], 0.5 op_sel_hi:[1,0,0]
	v_cvt_u32_f32_e32 v111, v111
	v_cvt_u32_f32_e32 v110, v110
	v_rcp_f32_e32 v105, v105
	v_cvt_u32_f32_e32 v107, v107
	v_cvt_u32_f32_e32 v106, v106
	v_pk_fma_f32 v[112:113], v[114:115], s[20:21], 0.5 op_sel_hi:[1,0,0]
	v_lshlrev_b32_e32 v111, 8, v111
	v_lshlrev_b32_e32 v110, 8, v110
	v_pk_fma_f32 v[104:105], v[104:105], s[20:21], 0.5 op_sel_hi:[1,0,0]
	v_or_b32_e32 v107, v111, v107
	v_or_b32_e32 v106, v110, v106
	v_cvt_u32_f32_sdwa v110, v113 dst_sel:WORD_1 dst_unused:UNUSED_PAD src0_sel:DWORD
	v_cvt_u32_f32_sdwa v111, v112 dst_sel:WORD_1 dst_unused:UNUSED_PAD src0_sel:DWORD
	v_cvt_u32_f32_sdwa v105, v105 dst_sel:BYTE_3 dst_unused:UNUSED_PAD src0_sel:DWORD
	v_cvt_u32_f32_sdwa v104, v104 dst_sel:BYTE_3 dst_unused:UNUSED_PAD src0_sel:DWORD
	v_lshlrev_b64 v[108:109], 11, v[154:155]
	v_or_b32_e32 v107, v107, v110
	v_or_b32_e32 v106, v106, v111
	v_or_b32_e32 v105, v107, v105
	v_or_b32_e32 v104, v106, v104
	v_lshl_add_u64 v[106:107], s[14:15], 0, v[108:109]
	v_mul_f32_e32 v101, v101, v181
	v_mul_f32_e32 v102, v102, v181
	v_lshl_add_u64 v[106:107], v[106:107], 0, v[140:141]
	v_exp_f32_e32 v101, v101
	global_store_dwordx2 v[106:107], v[104:105], off
	v_exp_f32_e32 v104, v102
	v_mul_f32_e32 v102, v103, v181
	v_exp_f32_e32 v103, v102
	v_add_f32_e32 v101, 1.0, v101
	v_mul_f32_e32 v96, v96, v181
	v_rcp_f32_e32 v102, v101
	v_add_f32_e32 v101, 1.0, v104
	v_mul_f32_e32 v100, v100, v181
	v_rcp_f32_e32 v104, v101
	v_add_f32_e32 v101, 1.0, v103
	v_exp_f32_e32 v103, v96
	v_mul_f32_e32 v96, v97, v181
	v_exp_f32_e32 v100, v100
	v_exp_f32_e32 v97, v96
	v_mul_f32_e32 v98, v98, v181
	v_mul_f32_e32 v99, v99, v181
	v_add_f32_e32 v100, 1.0, v100
	v_rcp_f32_e32 v96, v101
	v_add_f32_e32 v101, 1.0, v103
	v_add_f32_e32 v97, 1.0, v97
	v_exp_f32_e32 v98, v98
	v_rcp_f32_e32 v100, v100
	v_rcp_f32_e32 v101, v101
	v_exp_f32_e32 v99, v99
	v_rcp_f32_e32 v103, v97
	v_add_f32_e32 v97, 1.0, v98
	v_rcp_f32_e32 v105, v97
	v_add_f32_e32 v97, 1.0, v99
	v_pk_fma_f32 v[98:99], v[100:101], s[20:21], 0.5 op_sel_hi:[1,0,0]
	v_pk_fma_f32 v[100:101], v[102:103], s[20:21], 0.5 op_sel_hi:[1,0,0]
	v_rcp_f32_e32 v97, v97
	v_cvt_u32_f32_e32 v101, v101
	v_cvt_u32_f32_e32 v100, v100
	v_cvt_u32_f32_e32 v99, v99
	v_cvt_u32_f32_e32 v98, v98
	v_pk_fma_f32 v[102:103], v[104:105], s[20:21], 0.5 op_sel_hi:[1,0,0]
	v_lshlrev_b32_e32 v101, 8, v101
	v_lshlrev_b32_e32 v100, 8, v100
	v_pk_fma_f32 v[96:97], v[96:97], s[20:21], 0.5 op_sel_hi:[1,0,0]
	v_or_b32_e32 v99, v101, v99
	v_or_b32_e32 v98, v100, v98
	v_cvt_u32_f32_sdwa v100, v103 dst_sel:WORD_1 dst_unused:UNUSED_PAD src0_sel:DWORD
	v_cvt_u32_f32_sdwa v101, v102 dst_sel:WORD_1 dst_unused:UNUSED_PAD src0_sel:DWORD
	v_cvt_u32_f32_sdwa v97, v97 dst_sel:BYTE_3 dst_unused:UNUSED_PAD src0_sel:DWORD
	v_cvt_u32_f32_sdwa v96, v96 dst_sel:BYTE_3 dst_unused:UNUSED_PAD src0_sel:DWORD
	v_or_b32_e32 v99, v99, v100
	v_or_b32_e32 v98, v98, v101
	v_or_b32_e32 v97, v99, v97
	v_or_b32_e32 v96, v98, v96
	v_lshl_add_u64 v[98:99], s[92:93], 0, v[108:109]
	v_lshl_add_u64 v[98:99], v[98:99], 0, v[140:141]
	v_add_co_u32_e32 v98, vcc, s45, v98
	v_mul_f32_e32 v92, v92, v182
	s_nop 0
	v_addc_co_u32_e32 v99, vcc, 0, v99, vcc
	global_store_dwordx2 v[98:99], v[96:97], off offset:128
	v_exp_f32_e32 v96, v92
	v_mul_f32_e32 v92, v93, v182
	v_mul_f32_e32 v94, v94, v182
	v_exp_f32_e32 v97, v92
	v_exp_f32_e32 v98, v94
	v_mul_f32_e32 v94, v95, v182
	v_add_f32_e32 v97, 1.0, v97
	v_mul_f32_e32 v88, v88, v182
	v_exp_f32_e32 v95, v94
	v_rcp_f32_e32 v94, v97
	v_add_f32_e32 v97, 1.0, v98
	v_rcp_f32_e32 v98, v97
	v_exp_f32_e32 v97, v88
	v_mul_f32_e32 v88, v89, v182
	v_exp_f32_e32 v89, v88
	v_add_f32_e32 v95, 1.0, v95
	v_mul_f32_e32 v90, v90, v182
	v_rcp_f32_e32 v88, v95
	v_add_f32_e32 v95, 1.0, v97
	v_add_f32_e32 v89, 1.0, v89
	v_mul_f32_e32 v91, v91, v182
	v_add_f32_e32 v96, 1.0, v96
	v_rcp_f32_e32 v97, v95
	v_exp_f32_e32 v90, v90
	v_rcp_f32_e32 v95, v89
	v_rcp_f32_e32 v96, v96
	v_exp_f32_e32 v91, v91
	v_add_f32_e32 v89, 1.0, v90
	v_pk_fma_f32 v[94:95], v[94:95], s[20:21], 0.5 op_sel_hi:[1,0,0]
	v_rcp_f32_e32 v99, v89
	v_add_f32_e32 v89, 1.0, v91
	v_pk_fma_f32 v[90:91], v[96:97], s[20:21], 0.5 op_sel_hi:[1,0,0]
	v_cvt_u32_f32_e32 v95, v95
	v_cvt_u32_f32_e32 v94, v94
	v_rcp_f32_e32 v89, v89
	v_cvt_u32_f32_e32 v91, v91
	v_cvt_u32_f32_e32 v90, v90
; __device__ __forceinline__ float sigmoidf_(float z) { return __builtin_amdgcn_rcpf(1.0f + __builtin_amdgcn_exp2f(-1.4426950408889634f * z)); }
;     __device__ __forceinline__ float compute(const Pre& p, f32x4 (&acc)[2][2][4][2], const f32x4 (&cv)[2][2], const pg8::Unit& u, int ai, int m, int wr, int wc, int fr, int fq) const {
;     ...
;                 const int col = u.pn * 256 + ct; float w[8];
; #pragma unroll
;                 for (int j = 0; j < 8; ++j) w[j] = sigmoidf_(v[j] * rs) * 255.0f + 0.5f;
;                 u32x2 cd; cd.x = (unsigned)w[0] | ((unsigned)w[1] << 8) | ((unsigned)w[2] << 16) | ((unsigned)w[3] << 24); cd.y = (unsigned)w[4] | ((unsigned)w[5] << 8) | ((unsigned)w[6] << 16) | ((unsigned)w[7] << 24);
;                 *(u32x2*)(ws + WS_G8 + (size_t)row * 2048 + col) = cd;
	v_pk_fma_f32 v[96:97], v[98:99], s[20:21], 0.5 op_sel_hi:[1,0,0]
	v_lshlrev_b32_e32 v95, 8, v95
	v_lshlrev_b32_e32 v94, 8, v94
	v_pk_fma_f32 v[88:89], v[88:89], s[20:21], 0.5 op_sel_hi:[1,0,0]
	v_or_b32_e32 v91, v95, v91
	v_or_b32_e32 v90, v94, v90
	v_cvt_u32_f32_sdwa v94, v97 dst_sel:WORD_1 dst_unused:UNUSED_PAD src0_sel:DWORD
	v_cvt_u32_f32_sdwa v95, v96 dst_sel:WORD_1 dst_unused:UNUSED_PAD src0_sel:DWORD
	v_cvt_u32_f32_sdwa v89, v89 dst_sel:BYTE_3 dst_unused:UNUSED_PAD src0_sel:DWORD
	v_cvt_u32_f32_sdwa v88, v88 dst_sel:BYTE_3 dst_unused:UNUSED_PAD src0_sel:DWORD
	v_lshlrev_b64 v[92:93], 11, v[152:153]
	v_or_b32_e32 v91, v91, v94
	v_or_b32_e32 v90, v90, v95
	v_or_b32_e32 v89, v91, v89
	v_or_b32_e32 v88, v90, v88
	v_lshl_add_u64 v[90:91], s[14:15], 0, v[92:93]
	v_mul_f32_e32 v85, v85, v182
	v_mul_f32_e32 v86, v86, v182
	v_lshl_add_u64 v[90:91], v[90:91], 0, v[140:141]
	v_exp_f32_e32 v85, v85
	global_store_dwordx2 v[90:91], v[88:89], off
	v_exp_f32_e32 v88, v86
	v_mul_f32_e32 v86, v87, v182
	v_exp_f32_e32 v87, v86
	v_add_f32_e32 v85, 1.0, v85
	v_mul_f32_e32 v80, v80, v182
	v_rcp_f32_e32 v86, v85
	v_add_f32_e32 v85, 1.0, v88
	v_mul_f32_e32 v84, v84, v182
	v_rcp_f32_e32 v88, v85
	v_add_f32_e32 v85, 1.0, v87
	v_exp_f32_e32 v87, v80
	v_mul_f32_e32 v80, v81, v182
	v_exp_f32_e32 v84, v84
	v_exp_f32_e32 v81, v80
	v_mul_f32_e32 v82, v82, v182
	v_mul_f32_e32 v83, v83, v182
	v_add_f32_e32 v84, 1.0, v84
	v_rcp_f32_e32 v80, v85
	v_add_f32_e32 v85, 1.0, v87
	v_add_f32_e32 v81, 1.0, v81
	v_exp_f32_e32 v82, v82
	v_rcp_f32_e32 v84, v84
	v_rcp_f32_e32 v85, v85
	v_exp_f32_e32 v83, v83
	v_rcp_f32_e32 v87, v81
	v_add_f32_e32 v81, 1.0, v82
	v_rcp_f32_e32 v89, v81
	v_add_f32_e32 v81, 1.0, v83
	v_pk_fma_f32 v[82:83], v[84:85], s[20:21], 0.5 op_sel_hi:[1,0,0]
	v_pk_fma_f32 v[84:85], v[86:87], s[20:21], 0.5 op_sel_hi:[1,0,0]
	v_rcp_f32_e32 v81, v81
	v_cvt_u32_f32_e32 v85, v85
	v_cvt_u32_f32_e32 v84, v84
	v_cvt_u32_f32_e32 v83, v83
	v_cvt_u32_f32_e32 v82, v82
	v_pk_fma_f32 v[86:87], v[88:89], s[20:21], 0.5 op_sel_hi:[1,0,0]
	v_lshlrev_b32_e32 v85, 8, v85
	v_lshlrev_b32_e32 v84, 8, v84
	v_pk_fma_f32 v[80:81], v[80:81], s[20:21], 0.5 op_sel_hi:[1,0,0]
	v_or_b32_e32 v83, v85, v83
	v_or_b32_e32 v82, v84, v82
	v_cvt_u32_f32_sdwa v84, v87 dst_sel:WORD_1 dst_unused:UNUSED_PAD src0_sel:DWORD
	v_cvt_u32_f32_sdwa v85, v86 dst_sel:WORD_1 dst_unused:UNUSED_PAD src0_sel:DWORD
	v_cvt_u32_f32_sdwa v81, v81 dst_sel:BYTE_3 dst_unused:UNUSED_PAD src0_sel:DWORD
	v_cvt_u32_f32_sdwa v80, v80 dst_sel:BYTE_3 dst_unused:UNUSED_PAD src0_sel:DWORD
	v_or_b32_e32 v83, v83, v84
	v_or_b32_e32 v82, v82, v85
	v_or_b32_e32 v81, v83, v81
	v_or_b32_e32 v80, v82, v80
	v_lshl_add_u64 v[82:83], s[92:93], 0, v[92:93]
	v_lshl_add_u64 v[82:83], v[82:83], 0, v[140:141]
	v_add_co_u32_e32 v82, vcc, s45, v82
	v_mul_f32_e32 v76, v76, v166
	s_nop 0
	v_addc_co_u32_e32 v83, vcc, 0, v83, vcc
	global_store_dwordx2 v[82:83], v[80:81], off offset:128
	v_exp_f32_e32 v80, v76
	v_mul_f32_e32 v76, v77, v166
	v_mul_f32_e32 v78, v78, v166
	v_exp_f32_e32 v81, v76
	v_exp_f32_e32 v82, v78
	v_mul_f32_e32 v78, v79, v166
	v_add_f32_e32 v81, 1.0, v81
	v_mul_f32_e32 v72, v72, v166
	v_exp_f32_e32 v79, v78
	v_rcp_f32_e32 v78, v81
	v_add_f32_e32 v81, 1.0, v82
	v_rcp_f32_e32 v82, v81
	v_exp_f32_e32 v81, v72
	v_mul_f32_e32 v72, v73, v166
	v_exp_f32_e32 v73, v72
	v_add_f32_e32 v79, 1.0, v79
	v_mul_f32_e32 v74, v74, v166
	v_rcp_f32_e32 v72, v79
	v_add_f32_e32 v79, 1.0, v81
	v_add_f32_e32 v73, 1.0, v73
	v_mul_f32_e32 v75, v75, v166
	v_add_f32_e32 v80, 1.0, v80
	v_rcp_f32_e32 v81, v79
	v_exp_f32_e32 v74, v74
	v_rcp_f32_e32 v79, v73
	v_rcp_f32_e32 v80, v80
	v_exp_f32_e32 v75, v75
	v_add_f32_e32 v73, 1.0, v74
	v_pk_fma_f32 v[78:79], v[78:79], s[20:21], 0.5 op_sel_hi:[1,0,0]
	v_rcp_f32_e32 v83, v73
	v_add_f32_e32 v73, 1.0, v75
	v_pk_fma_f32 v[74:75], v[80:81], s[20:21], 0.5 op_sel_hi:[1,0,0]
	v_cvt_u32_f32_e32 v79, v79
	v_cvt_u32_f32_e32 v78, v78
	v_rcp_f32_e32 v73, v73
	v_cvt_u32_f32_e32 v75, v75
	v_cvt_u32_f32_e32 v74, v74
	v_pk_fma_f32 v[80:81], v[82:83], s[20:21], 0.5 op_sel_hi:[1,0,0]
	v_lshlrev_b32_e32 v79, 8, v79
	v_lshlrev_b32_e32 v78, 8, v78
	v_pk_fma_f32 v[72:73], v[72:73], s[20:21], 0.5 op_sel_hi:[1,0,0]
	v_or_b32_e32 v75, v79, v75
	v_or_b32_e32 v74, v78, v74
	v_cvt_u32_f32_sdwa v78, v81 dst_sel:WORD_1 dst_unused:UNUSED_PAD src0_sel:DWORD
	v_cvt_u32_f32_sdwa v79, v80 dst_sel:WORD_1 dst_unused:UNUSED_PAD src0_sel:DWORD
	v_cvt_u32_f32_sdwa v73, v73 dst_sel:BYTE_3 dst_unused:UNUSED_PAD src0_sel:DWORD
	v_cvt_u32_f32_sdwa v72, v72 dst_sel:BYTE_3 dst_unused:UNUSED_PAD src0_sel:DWORD
	v_lshlrev_b64 v[76:77], 11, v[150:151]
	v_or_b32_e32 v75, v75, v78
	v_or_b32_e32 v74, v74, v79
	v_or_b32_e32 v73, v75, v73
	v_or_b32_e32 v72, v74, v72
	v_lshl_add_u64 v[74:75], s[14:15], 0, v[76:77]
	v_mul_f32_e32 v69, v69, v166
	v_mul_f32_e32 v70, v70, v166
	v_lshl_add_u64 v[74:75], v[74:75], 0, v[140:141]
	v_exp_f32_e32 v69, v69
	global_store_dwordx2 v[74:75], v[72:73], off
	v_exp_f32_e32 v72, v70
	v_mul_f32_e32 v70, v71, v166
	v_exp_f32_e32 v71, v70
	v_add_f32_e32 v69, 1.0, v69
	v_mul_f32_e32 v64, v64, v166
	v_rcp_f32_e32 v70, v69
	v_add_f32_e32 v69, 1.0, v72
	v_mul_f32_e32 v68, v68, v166
	v_rcp_f32_e32 v72, v69
	v_add_f32_e32 v69, 1.0, v71
	v_exp_f32_e32 v71, v64
	v_mul_f32_e32 v64, v65, v166
	v_exp_f32_e32 v68, v68
	v_exp_f32_e32 v65, v64
	v_mul_f32_e32 v66, v66, v166
	v_mul_f32_e32 v67, v67, v166
	v_add_f32_e32 v68, 1.0, v68
	v_rcp_f32_e32 v64, v69
	v_add_f32_e32 v69, 1.0, v71
	v_add_f32_e32 v65, 1.0, v65
	v_exp_f32_e32 v66, v66
	v_rcp_f32_e32 v68, v68
	v_rcp_f32_e32 v69, v69
	v_exp_f32_e32 v67, v67
	v_rcp_f32_e32 v71, v65
	v_add_f32_e32 v65, 1.0, v66
; __device__ __forceinline__ float sigmoidf_(float z) { return __builtin_amdgcn_rcpf(1.0f + __builtin_amdgcn_exp2f(-1.4426950408889634f * z)); }
;     __device__ __forceinline__ float compute(const Pre& p, f32x4 (&acc)[2][2][4][2], const f32x4 (&cv)[2][2], const pg8::Unit& u, int ai, int m, int wr, int wc, int fr, int fq) const {
;     ...
;                 const int col = u.pn * 256 + ct; float w[8];
; #pragma unroll
;                 for (int j = 0; j < 8; ++j) w[j] = sigmoidf_(v[j] * rs) * 255.0f + 0.5f;
;                 u32x2 cd; cd.x = (unsigned)w[0] | ((unsigned)w[1] << 8) | ((unsigned)w[2] << 16) | ((unsigned)w[3] << 24); cd.y = (unsigned)w[4] | ((unsigned)w[5] << 8) | ((unsigned)w[6] << 16) | ((unsigned)w[7] << 24);
;                 *(u32x2*)(ws + WS_G8 + (size_t)row * 2048 + col) = cd;
	v_rcp_f32_e32 v73, v65
	v_add_f32_e32 v65, 1.0, v67
	v_pk_fma_f32 v[66:67], v[68:69], s[20:21], 0.5 op_sel_hi:[1,0,0]
	v_pk_fma_f32 v[68:69], v[70:71], s[20:21], 0.5 op_sel_hi:[1,0,0]
	v_rcp_f32_e32 v65, v65
	v_cvt_u32_f32_e32 v69, v69
	v_cvt_u32_f32_e32 v68, v68
	v_cvt_u32_f32_e32 v67, v67
	v_cvt_u32_f32_e32 v66, v66
	v_pk_fma_f32 v[70:71], v[72:73], s[20:21], 0.5 op_sel_hi:[1,0,0]
	v_lshlrev_b32_e32 v69, 8, v69
	v_lshlrev_b32_e32 v68, 8, v68
	v_pk_fma_f32 v[64:65], v[64:65], s[20:21], 0.5 op_sel_hi:[1,0,0]
	v_or_b32_e32 v67, v69, v67
	v_or_b32_e32 v66, v68, v66
	v_cvt_u32_f32_sdwa v68, v71 dst_sel:WORD_1 dst_unused:UNUSED_PAD src0_sel:DWORD
	v_cvt_u32_f32_sdwa v69, v70 dst_sel:WORD_1 dst_unused:UNUSED_PAD src0_sel:DWORD
	v_cvt_u32_f32_sdwa v65, v65 dst_sel:BYTE_3 dst_unused:UNUSED_PAD src0_sel:DWORD
	v_cvt_u32_f32_sdwa v64, v64 dst_sel:BYTE_3 dst_unused:UNUSED_PAD src0_sel:DWORD
	v_or_b32_e32 v67, v67, v68
	v_or_b32_e32 v66, v66, v69
	v_or_b32_e32 v65, v67, v65
	v_or_b32_e32 v64, v66, v64
	v_lshl_add_u64 v[66:67], s[92:93], 0, v[76:77]
	v_lshl_add_u64 v[66:67], v[66:67], 0, v[140:141]
	v_add_co_u32_e32 v66, vcc, s45, v66
	v_mul_f32_e32 v60, v60, v165
	s_nop 0
	v_addc_co_u32_e32 v67, vcc, 0, v67, vcc
	global_store_dwordx2 v[66:67], v[64:65], off offset:128
	v_exp_f32_e32 v64, v60
	v_mul_f32_e32 v60, v61, v165
	v_mul_f32_e32 v62, v62, v165
	v_exp_f32_e32 v65, v60
	v_exp_f32_e32 v66, v62
	v_mul_f32_e32 v62, v63, v165
	v_add_f32_e32 v65, 1.0, v65
	v_mul_f32_e32 v56, v56, v165
	v_exp_f32_e32 v63, v62
	v_rcp_f32_e32 v62, v65
	v_add_f32_e32 v65, 1.0, v66
	v_rcp_f32_e32 v66, v65
	v_exp_f32_e32 v65, v56
	v_mul_f32_e32 v56, v57, v165
	v_exp_f32_e32 v57, v56
	v_add_f32_e32 v63, 1.0, v63
	v_mul_f32_e32 v58, v58, v165
	v_rcp_f32_e32 v56, v63
	v_add_f32_e32 v63, 1.0, v65
	v_add_f32_e32 v57, 1.0, v57
	v_mul_f32_e32 v59, v59, v165
	v_add_f32_e32 v64, 1.0, v64
	v_rcp_f32_e32 v65, v63
	v_exp_f32_e32 v58, v58
	v_rcp_f32_e32 v63, v57
	v_rcp_f32_e32 v64, v64
	v_exp_f32_e32 v59, v59
	v_add_f32_e32 v57, 1.0, v58
	v_pk_fma_f32 v[62:63], v[62:63], s[20:21], 0.5 op_sel_hi:[1,0,0]
	v_rcp_f32_e32 v67, v57
	v_add_f32_e32 v57, 1.0, v59
	v_pk_fma_f32 v[58:59], v[64:65], s[20:21], 0.5 op_sel_hi:[1,0,0]
	v_cvt_u32_f32_e32 v63, v63
	v_cvt_u32_f32_e32 v62, v62
	v_rcp_f32_e32 v57, v57
	v_cvt_u32_f32_e32 v59, v59
	v_cvt_u32_f32_e32 v58, v58
	v_pk_fma_f32 v[64:65], v[66:67], s[20:21], 0.5 op_sel_hi:[1,0,0]
	v_lshlrev_b32_e32 v63, 8, v63
	v_lshlrev_b32_e32 v62, 8, v62
	v_pk_fma_f32 v[56:57], v[56:57], s[20:21], 0.5 op_sel_hi:[1,0,0]
	v_or_b32_e32 v59, v63, v59
	v_or_b32_e32 v58, v62, v58
	v_cvt_u32_f32_sdwa v62, v65 dst_sel:WORD_1 dst_unused:UNUSED_PAD src0_sel:DWORD
	v_cvt_u32_f32_sdwa v63, v64 dst_sel:WORD_1 dst_unused:UNUSED_PAD src0_sel:DWORD
	v_cvt_u32_f32_sdwa v57, v57 dst_sel:BYTE_3 dst_unused:UNUSED_PAD src0_sel:DWORD
	v_cvt_u32_f32_sdwa v56, v56 dst_sel:BYTE_3 dst_unused:UNUSED_PAD src0_sel:DWORD
	v_lshlrev_b64 v[60:61], 11, v[148:149]
	v_or_b32_e32 v59, v59, v62
	v_or_b32_e32 v58, v58, v63
	v_or_b32_e32 v57, v59, v57
	v_or_b32_e32 v56, v58, v56
	v_lshl_add_u64 v[58:59], s[14:15], 0, v[60:61]
	v_mul_f32_e32 v53, v53, v165
	v_mul_f32_e32 v54, v54, v165
	v_lshl_add_u64 v[58:59], v[58:59], 0, v[140:141]
	v_exp_f32_e32 v53, v53
	global_store_dwordx2 v[58:59], v[56:57], off
	v_exp_f32_e32 v56, v54
	v_mul_f32_e32 v54, v55, v165
	v_exp_f32_e32 v55, v54
	v_add_f32_e32 v53, 1.0, v53
	v_mul_f32_e32 v48, v48, v165
	v_rcp_f32_e32 v54, v53
	v_add_f32_e32 v53, 1.0, v56
	v_mul_f32_e32 v52, v52, v165
	v_rcp_f32_e32 v56, v53
	v_add_f32_e32 v53, 1.0, v55
	v_exp_f32_e32 v55, v48
	v_mul_f32_e32 v48, v49, v165
	v_exp_f32_e32 v52, v52
	v_exp_f32_e32 v49, v48
	v_mul_f32_e32 v50, v50, v165
	v_mul_f32_e32 v51, v51, v165
	v_add_f32_e32 v52, 1.0, v52
	v_rcp_f32_e32 v48, v53
	v_add_f32_e32 v53, 1.0, v55
	v_add_f32_e32 v49, 1.0, v49
	v_exp_f32_e32 v50, v50
	v_rcp_f32_e32 v52, v52
	v_rcp_f32_e32 v53, v53
	v_exp_f32_e32 v51, v51
	v_rcp_f32_e32 v55, v49
	v_add_f32_e32 v49, 1.0, v50
	v_rcp_f32_e32 v57, v49
	v_add_f32_e32 v49, 1.0, v51
	v_pk_fma_f32 v[50:51], v[52:53], s[20:21], 0.5 op_sel_hi:[1,0,0]
	v_pk_fma_f32 v[52:53], v[54:55], s[20:21], 0.5 op_sel_hi:[1,0,0]
	v_rcp_f32_e32 v49, v49
	v_cvt_u32_f32_e32 v53, v53
	v_cvt_u32_f32_e32 v52, v52
	v_cvt_u32_f32_e32 v51, v51
	v_cvt_u32_f32_e32 v50, v50
	v_pk_fma_f32 v[54:55], v[56:57], s[20:21], 0.5 op_sel_hi:[1,0,0]
	v_lshlrev_b32_e32 v53, 8, v53
	v_lshlrev_b32_e32 v52, 8, v52
	v_pk_fma_f32 v[48:49], v[48:49], s[20:21], 0.5 op_sel_hi:[1,0,0]
	v_or_b32_e32 v51, v53, v51
	v_or_b32_e32 v50, v52, v50
	v_cvt_u32_f32_sdwa v52, v55 dst_sel:WORD_1 dst_unused:UNUSED_PAD src0_sel:DWORD
	v_cvt_u32_f32_sdwa v53, v54 dst_sel:WORD_1 dst_unused:UNUSED_PAD src0_sel:DWORD
	v_cvt_u32_f32_sdwa v49, v49 dst_sel:BYTE_3 dst_unused:UNUSED_PAD src0_sel:DWORD
	v_cvt_u32_f32_sdwa v48, v48 dst_sel:BYTE_3 dst_unused:UNUSED_PAD src0_sel:DWORD
	v_or_b32_e32 v51, v51, v52
	v_or_b32_e32 v50, v50, v53
	v_or_b32_e32 v49, v51, v49
	v_or_b32_e32 v48, v50, v48
	v_lshl_add_u64 v[50:51], s[92:93], 0, v[60:61]
	v_lshl_add_u64 v[50:51], v[50:51], 0, v[140:141]
	v_add_co_u32_e32 v50, vcc, s45, v50
	v_mul_f32_e32 v44, v44, v164
	s_nop 0
	v_addc_co_u32_e32 v51, vcc, 0, v51, vcc
	global_store_dwordx2 v[50:51], v[48:49], off offset:128
	v_exp_f32_e32 v48, v44
	v_mul_f32_e32 v44, v45, v164
	v_mul_f32_e32 v46, v46, v164
	v_exp_f32_e32 v49, v44
	v_exp_f32_e32 v50, v46
	v_mul_f32_e32 v46, v47, v164
	v_add_f32_e32 v49, 1.0, v49
	v_mul_f32_e32 v40, v40, v164
	v_exp_f32_e32 v47, v46
	v_rcp_f32_e32 v46, v49
	v_add_f32_e32 v49, 1.0, v50
	v_rcp_f32_e32 v50, v49
	v_exp_f32_e32 v49, v40
	v_mul_f32_e32 v40, v41, v164
; __device__ __forceinline__ float sigmoidf_(float z) { return __builtin_amdgcn_rcpf(1.0f + __builtin_amdgcn_exp2f(-1.4426950408889634f * z)); }
;     __device__ __forceinline__ float compute(const Pre& p, f32x4 (&acc)[2][2][4][2], const f32x4 (&cv)[2][2], const pg8::Unit& u, int ai, int m, int wr, int wc, int fr, int fq) const {
;     ...
;                 const int col = u.pn * 256 + ct; float w[8];
; #pragma unroll
;                 for (int j = 0; j < 8; ++j) w[j] = sigmoidf_(v[j] * rs) * 255.0f + 0.5f;
;                 u32x2 cd; cd.x = (unsigned)w[0] | ((unsigned)w[1] << 8) | ((unsigned)w[2] << 16) | ((unsigned)w[3] << 24); cd.y = (unsigned)w[4] | ((unsigned)w[5] << 8) | ((unsigned)w[6] << 16) | ((unsigned)w[7] << 24);
;                 *(u32x2*)(ws + WS_G8 + (size_t)row * 2048 + col) = cd;
	v_exp_f32_e32 v41, v40
	v_add_f32_e32 v47, 1.0, v47
	v_mul_f32_e32 v42, v42, v164
	v_rcp_f32_e32 v40, v47
	v_add_f32_e32 v47, 1.0, v49
	v_add_f32_e32 v41, 1.0, v41
	v_mul_f32_e32 v43, v43, v164
	v_add_f32_e32 v48, 1.0, v48
	v_rcp_f32_e32 v49, v47
	v_exp_f32_e32 v42, v42
	v_rcp_f32_e32 v47, v41
	v_rcp_f32_e32 v48, v48
	v_exp_f32_e32 v43, v43
	v_add_f32_e32 v41, 1.0, v42
	v_pk_fma_f32 v[46:47], v[46:47], s[20:21], 0.5 op_sel_hi:[1,0,0]
	v_rcp_f32_e32 v51, v41
	v_add_f32_e32 v41, 1.0, v43
	v_pk_fma_f32 v[42:43], v[48:49], s[20:21], 0.5 op_sel_hi:[1,0,0]
	v_cvt_u32_f32_e32 v47, v47
	v_cvt_u32_f32_e32 v46, v46
	v_rcp_f32_e32 v41, v41
	v_cvt_u32_f32_e32 v43, v43
	v_cvt_u32_f32_e32 v42, v42
	v_pk_fma_f32 v[48:49], v[50:51], s[20:21], 0.5 op_sel_hi:[1,0,0]
	v_lshlrev_b32_e32 v47, 8, v47
	v_lshlrev_b32_e32 v46, 8, v46
	v_pk_fma_f32 v[40:41], v[40:41], s[20:21], 0.5 op_sel_hi:[1,0,0]
	v_or_b32_e32 v43, v47, v43
	v_or_b32_e32 v42, v46, v42
	v_cvt_u32_f32_sdwa v46, v49 dst_sel:WORD_1 dst_unused:UNUSED_PAD src0_sel:DWORD
	v_cvt_u32_f32_sdwa v47, v48 dst_sel:WORD_1 dst_unused:UNUSED_PAD src0_sel:DWORD
	v_cvt_u32_f32_sdwa v41, v41 dst_sel:BYTE_3 dst_unused:UNUSED_PAD src0_sel:DWORD
	v_cvt_u32_f32_sdwa v40, v40 dst_sel:BYTE_3 dst_unused:UNUSED_PAD src0_sel:DWORD
	v_lshlrev_b64 v[44:45], 11, v[146:147]
	v_or_b32_e32 v43, v43, v46
	v_or_b32_e32 v42, v42, v47
	v_or_b32_e32 v41, v43, v41
	v_or_b32_e32 v40, v42, v40
	v_lshl_add_u64 v[42:43], s[14:15], 0, v[44:45]
	v_mul_f32_e32 v37, v37, v164
	v_mul_f32_e32 v38, v38, v164
	v_lshl_add_u64 v[42:43], v[42:43], 0, v[140:141]
	v_exp_f32_e32 v37, v37
	global_store_dwordx2 v[42:43], v[40:41], off
	v_exp_f32_e32 v40, v38
	v_mul_f32_e32 v38, v39, v164
	v_exp_f32_e32 v39, v38
	v_add_f32_e32 v37, 1.0, v37
	v_mul_f32_e32 v32, v32, v164
	v_rcp_f32_e32 v38, v37
	v_add_f32_e32 v37, 1.0, v40
	v_mul_f32_e32 v36, v36, v164
	v_rcp_f32_e32 v40, v37
	v_add_f32_e32 v37, 1.0, v39
	v_exp_f32_e32 v39, v32
	v_mul_f32_e32 v32, v33, v164
	v_exp_f32_e32 v36, v36
	v_exp_f32_e32 v33, v32
	v_mul_f32_e32 v34, v34, v164
	v_mul_f32_e32 v35, v35, v164
	v_add_f32_e32 v36, 1.0, v36
	v_rcp_f32_e32 v32, v37
	v_add_f32_e32 v37, 1.0, v39
	v_add_f32_e32 v33, 1.0, v33
	v_exp_f32_e32 v34, v34
	v_rcp_f32_e32 v36, v36
	v_rcp_f32_e32 v37, v37
	v_exp_f32_e32 v35, v35
	v_rcp_f32_e32 v39, v33
	v_add_f32_e32 v33, 1.0, v34
	v_rcp_f32_e32 v41, v33
	v_add_f32_e32 v33, 1.0, v35
	v_pk_fma_f32 v[34:35], v[36:37], s[20:21], 0.5 op_sel_hi:[1,0,0]
	v_pk_fma_f32 v[36:37], v[38:39], s[20:21], 0.5 op_sel_hi:[1,0,0]
	v_rcp_f32_e32 v33, v33
	v_cvt_u32_f32_e32 v37, v37
	v_cvt_u32_f32_e32 v36, v36
	v_cvt_u32_f32_e32 v35, v35
	v_cvt_u32_f32_e32 v34, v34
	v_pk_fma_f32 v[38:39], v[40:41], s[20:21], 0.5 op_sel_hi:[1,0,0]
	v_lshlrev_b32_e32 v37, 8, v37
	v_lshlrev_b32_e32 v36, 8, v36
	v_pk_fma_f32 v[32:33], v[32:33], s[20:21], 0.5 op_sel_hi:[1,0,0]
	v_or_b32_e32 v35, v37, v35
	v_or_b32_e32 v34, v36, v34
	v_cvt_u32_f32_sdwa v36, v39 dst_sel:WORD_1 dst_unused:UNUSED_PAD src0_sel:DWORD
	v_cvt_u32_f32_sdwa v37, v38 dst_sel:WORD_1 dst_unused:UNUSED_PAD src0_sel:DWORD
	v_cvt_u32_f32_sdwa v33, v33 dst_sel:BYTE_3 dst_unused:UNUSED_PAD src0_sel:DWORD
	v_cvt_u32_f32_sdwa v32, v32 dst_sel:BYTE_3 dst_unused:UNUSED_PAD src0_sel:DWORD
	v_or_b32_e32 v35, v35, v36
	v_or_b32_e32 v34, v34, v37
	v_or_b32_e32 v33, v35, v33
	v_or_b32_e32 v32, v34, v32
	v_lshl_add_u64 v[34:35], s[92:93], 0, v[44:45]
	v_lshl_add_u64 v[34:35], v[34:35], 0, v[140:141]
	v_add_co_u32_e32 v34, vcc, s45, v34
	v_mul_f32_e32 v28, v28, v163
	s_nop 0
	v_addc_co_u32_e32 v35, vcc, 0, v35, vcc
	global_store_dwordx2 v[34:35], v[32:33], off offset:128
	v_exp_f32_e32 v32, v28
	v_mul_f32_e32 v28, v29, v163
	v_mul_f32_e32 v30, v30, v163
	v_exp_f32_e32 v33, v28
	v_exp_f32_e32 v34, v30
	v_mul_f32_e32 v30, v31, v163
	v_add_f32_e32 v33, 1.0, v33
	v_mul_f32_e32 v24, v24, v163
	v_exp_f32_e32 v31, v30
	v_rcp_f32_e32 v30, v33
	v_add_f32_e32 v33, 1.0, v34
	v_rcp_f32_e32 v34, v33
	v_exp_f32_e32 v33, v24
	v_mul_f32_e32 v24, v25, v163
	v_exp_f32_e32 v25, v24
	v_add_f32_e32 v31, 1.0, v31
	v_mul_f32_e32 v26, v26, v163
	v_rcp_f32_e32 v24, v31
	v_add_f32_e32 v31, 1.0, v33
	v_add_f32_e32 v25, 1.0, v25
	v_mul_f32_e32 v27, v27, v163
	v_add_f32_e32 v32, 1.0, v32
	v_rcp_f32_e32 v33, v31
	v_exp_f32_e32 v26, v26
	v_rcp_f32_e32 v31, v25
	v_rcp_f32_e32 v32, v32
	v_exp_f32_e32 v27, v27
	v_add_f32_e32 v25, 1.0, v26
	v_pk_fma_f32 v[30:31], v[30:31], s[20:21], 0.5 op_sel_hi:[1,0,0]
	v_rcp_f32_e32 v35, v25
	v_add_f32_e32 v25, 1.0, v27
	v_pk_fma_f32 v[26:27], v[32:33], s[20:21], 0.5 op_sel_hi:[1,0,0]
	v_cvt_u32_f32_e32 v31, v31
	v_cvt_u32_f32_e32 v30, v30
	v_rcp_f32_e32 v25, v25
	v_cvt_u32_f32_e32 v27, v27
	v_cvt_u32_f32_e32 v26, v26
	v_pk_fma_f32 v[32:33], v[34:35], s[20:21], 0.5 op_sel_hi:[1,0,0]
	v_lshlrev_b32_e32 v31, 8, v31
	v_lshlrev_b32_e32 v30, 8, v30
	v_pk_fma_f32 v[24:25], v[24:25], s[20:21], 0.5 op_sel_hi:[1,0,0]
	v_or_b32_e32 v27, v31, v27
	v_or_b32_e32 v26, v30, v26
	v_cvt_u32_f32_sdwa v30, v33 dst_sel:WORD_1 dst_unused:UNUSED_PAD src0_sel:DWORD
	v_cvt_u32_f32_sdwa v31, v32 dst_sel:WORD_1 dst_unused:UNUSED_PAD src0_sel:DWORD
	v_cvt_u32_f32_sdwa v25, v25 dst_sel:BYTE_3 dst_unused:UNUSED_PAD src0_sel:DWORD
	v_cvt_u32_f32_sdwa v24, v24 dst_sel:BYTE_3 dst_unused:UNUSED_PAD src0_sel:DWORD
	v_lshlrev_b64 v[28:29], 11, v[144:145]
	v_or_b32_e32 v27, v27, v30
	v_or_b32_e32 v26, v26, v31
	v_or_b32_e32 v25, v27, v25
	v_or_b32_e32 v24, v26, v24
	v_lshl_add_u64 v[26:27], s[14:15], 0, v[28:29]
	v_mul_f32_e32 v21, v21, v163
	v_mul_f32_e32 v22, v22, v163
	v_lshl_add_u64 v[26:27], v[26:27], 0, v[140:141]
	v_exp_f32_e32 v21, v21
	global_store_dwordx2 v[26:27], v[24:25], off
; __device__ __forceinline__ float sigmoidf_(float z) { return __builtin_amdgcn_rcpf(1.0f + __builtin_amdgcn_exp2f(-1.4426950408889634f * z)); }
;     __device__ __forceinline__ float compute(const Pre& p, f32x4 (&acc)[2][2][4][2], const f32x4 (&cv)[2][2], const pg8::Unit& u, int ai, int m, int wr, int wc, int fr, int fq) const {
;     ...
;                 const int col = u.pn * 256 + ct; float w[8];
; #pragma unroll
;                 for (int j = 0; j < 8; ++j) w[j] = sigmoidf_(v[j] * rs) * 255.0f + 0.5f;
;                 u32x2 cd; cd.x = (unsigned)w[0] | ((unsigned)w[1] << 8) | ((unsigned)w[2] << 16) | ((unsigned)w[3] << 24); cd.y = (unsigned)w[4] | ((unsigned)w[5] << 8) | ((unsigned)w[6] << 16) | ((unsigned)w[7] << 24);
;                 *(u32x2*)(ws + WS_G8 + (size_t)row * 2048 + col) = cd;
	v_exp_f32_e32 v24, v22
	v_mul_f32_e32 v22, v23, v163
	v_exp_f32_e32 v23, v22
	v_add_f32_e32 v21, 1.0, v21
	v_mul_f32_e32 v16, v16, v163
	v_rcp_f32_e32 v22, v21
	v_add_f32_e32 v21, 1.0, v24
	v_mul_f32_e32 v20, v20, v163
	v_rcp_f32_e32 v24, v21
	v_add_f32_e32 v21, 1.0, v23
	v_exp_f32_e32 v23, v16
	v_mul_f32_e32 v16, v17, v163
	v_exp_f32_e32 v20, v20
	v_exp_f32_e32 v17, v16
	v_mul_f32_e32 v18, v18, v163
	v_mul_f32_e32 v19, v19, v163
	v_add_f32_e32 v20, 1.0, v20
	v_rcp_f32_e32 v16, v21
	v_add_f32_e32 v21, 1.0, v23
	v_add_f32_e32 v17, 1.0, v17
	v_exp_f32_e32 v18, v18
	v_rcp_f32_e32 v20, v20
	v_rcp_f32_e32 v21, v21
	v_exp_f32_e32 v19, v19
	v_rcp_f32_e32 v23, v17
	v_add_f32_e32 v17, 1.0, v18
	v_rcp_f32_e32 v25, v17
	v_add_f32_e32 v17, 1.0, v19
	v_pk_fma_f32 v[18:19], v[20:21], s[20:21], 0.5 op_sel_hi:[1,0,0]
	v_pk_fma_f32 v[20:21], v[22:23], s[20:21], 0.5 op_sel_hi:[1,0,0]
	v_rcp_f32_e32 v17, v17
	v_cvt_u32_f32_e32 v21, v21
	v_cvt_u32_f32_e32 v20, v20
	v_cvt_u32_f32_e32 v19, v19
	v_cvt_u32_f32_e32 v18, v18
	v_pk_fma_f32 v[22:23], v[24:25], s[20:21], 0.5 op_sel_hi:[1,0,0]
	v_lshlrev_b32_e32 v21, 8, v21
	v_lshlrev_b32_e32 v20, 8, v20
	v_pk_fma_f32 v[16:17], v[16:17], s[20:21], 0.5 op_sel_hi:[1,0,0]
	v_or_b32_e32 v19, v21, v19
	v_or_b32_e32 v18, v20, v18
	v_cvt_u32_f32_sdwa v20, v23 dst_sel:WORD_1 dst_unused:UNUSED_PAD src0_sel:DWORD
	v_cvt_u32_f32_sdwa v21, v22 dst_sel:WORD_1 dst_unused:UNUSED_PAD src0_sel:DWORD
	v_cvt_u32_f32_sdwa v17, v17 dst_sel:BYTE_3 dst_unused:UNUSED_PAD src0_sel:DWORD
	v_cvt_u32_f32_sdwa v16, v16 dst_sel:BYTE_3 dst_unused:UNUSED_PAD src0_sel:DWORD
	v_or_b32_e32 v19, v19, v20
	v_or_b32_e32 v18, v18, v21
	v_or_b32_e32 v17, v19, v17
	v_or_b32_e32 v16, v18, v16
	v_lshl_add_u64 v[18:19], s[92:93], 0, v[28:29]
	v_lshl_add_u64 v[18:19], v[18:19], 0, v[140:141]
	v_add_co_u32_e32 v18, vcc, s45, v18
	v_mul_f32_e32 v12, v12, v162
	s_nop 0
	v_addc_co_u32_e32 v19, vcc, 0, v19, vcc
	global_store_dwordx2 v[18:19], v[16:17], off offset:128
	v_exp_f32_e32 v16, v12
	v_mul_f32_e32 v12, v13, v162
	v_mul_f32_e32 v14, v14, v162
	v_exp_f32_e32 v17, v12
	v_exp_f32_e32 v18, v14
	v_mul_f32_e32 v14, v15, v162
	v_add_f32_e32 v17, 1.0, v17
	v_mul_f32_e32 v8, v8, v162
	v_exp_f32_e32 v15, v14
	v_rcp_f32_e32 v14, v17
	v_add_f32_e32 v17, 1.0, v18
	v_rcp_f32_e32 v18, v17
	v_exp_f32_e32 v17, v8
	v_mul_f32_e32 v8, v9, v162
	v_exp_f32_e32 v9, v8
	v_add_f32_e32 v15, 1.0, v15
	v_mul_f32_e32 v10, v10, v162
	v_rcp_f32_e32 v8, v15
	v_add_f32_e32 v15, 1.0, v17
	v_add_f32_e32 v9, 1.0, v9
	v_mul_f32_e32 v11, v11, v162
	v_add_f32_e32 v16, 1.0, v16
	v_rcp_f32_e32 v17, v15
	v_exp_f32_e32 v10, v10
	v_rcp_f32_e32 v15, v9
	v_rcp_f32_e32 v16, v16
	v_exp_f32_e32 v11, v11
	v_add_f32_e32 v9, 1.0, v10
	v_pk_fma_f32 v[14:15], v[14:15], s[20:21], 0.5 op_sel_hi:[1,0,0]
	v_rcp_f32_e32 v19, v9
	v_add_f32_e32 v9, 1.0, v11
	v_pk_fma_f32 v[10:11], v[16:17], s[20:21], 0.5 op_sel_hi:[1,0,0]
	v_cvt_u32_f32_e32 v15, v15
	v_cvt_u32_f32_e32 v14, v14
	v_rcp_f32_e32 v9, v9
	v_cvt_u32_f32_e32 v11, v11
	v_cvt_u32_f32_e32 v10, v10
	v_pk_fma_f32 v[16:17], v[18:19], s[20:21], 0.5 op_sel_hi:[1,0,0]
	v_lshlrev_b32_e32 v15, 8, v15
	v_lshlrev_b32_e32 v14, 8, v14
	v_pk_fma_f32 v[8:9], v[8:9], s[20:21], 0.5 op_sel_hi:[1,0,0]
	v_or_b32_e32 v11, v15, v11
	v_or_b32_e32 v10, v14, v10
	v_cvt_u32_f32_sdwa v14, v17 dst_sel:WORD_1 dst_unused:UNUSED_PAD src0_sel:DWORD
	v_cvt_u32_f32_sdwa v15, v16 dst_sel:WORD_1 dst_unused:UNUSED_PAD src0_sel:DWORD
	v_cvt_u32_f32_sdwa v9, v9 dst_sel:BYTE_3 dst_unused:UNUSED_PAD src0_sel:DWORD
	v_cvt_u32_f32_sdwa v8, v8 dst_sel:BYTE_3 dst_unused:UNUSED_PAD src0_sel:DWORD
	v_lshlrev_b64 v[12:13], 11, v[142:143]
	v_or_b32_e32 v11, v11, v14
	v_or_b32_e32 v10, v10, v15
	v_or_b32_e32 v9, v11, v9
	v_or_b32_e32 v8, v10, v8
	v_lshl_add_u64 v[10:11], s[14:15], 0, v[12:13]
	v_mul_f32_e32 v5, v5, v162
	v_mul_f32_e32 v6, v6, v162
	v_lshl_add_u64 v[10:11], v[10:11], 0, v[140:141]
	v_exp_f32_e32 v5, v5
	global_store_dwordx2 v[10:11], v[8:9], off
	v_exp_f32_e32 v8, v6
	v_mul_f32_e32 v6, v7, v162
	v_exp_f32_e32 v7, v6
	v_add_f32_e32 v5, 1.0, v5
	v_mul_f32_e32 v0, v0, v162
	v_rcp_f32_e32 v6, v5
	v_add_f32_e32 v5, 1.0, v8
	v_mul_f32_e32 v4, v4, v162
	v_rcp_f32_e32 v8, v5
	v_add_f32_e32 v5, 1.0, v7
	v_exp_f32_e32 v7, v0
	v_mul_f32_e32 v0, v1, v162
	v_exp_f32_e32 v4, v4
	v_exp_f32_e32 v1, v0
	v_mul_f32_e32 v2, v2, v162
	v_mul_f32_e32 v3, v3, v162
	v_add_f32_e32 v4, 1.0, v4
	v_rcp_f32_e32 v0, v5
	v_add_f32_e32 v5, 1.0, v7
	v_add_f32_e32 v1, 1.0, v1
	v_exp_f32_e32 v2, v2
	v_rcp_f32_e32 v4, v4
	v_rcp_f32_e32 v5, v5
	v_exp_f32_e32 v3, v3
	v_rcp_f32_e32 v7, v1
	v_add_f32_e32 v1, 1.0, v2
	v_rcp_f32_e32 v9, v1
	v_add_f32_e32 v1, 1.0, v3
	v_pk_fma_f32 v[2:3], v[4:5], s[20:21], 0.5 op_sel_hi:[1,0,0]
	v_pk_fma_f32 v[4:5], v[6:7], s[20:21], 0.5 op_sel_hi:[1,0,0]
	v_rcp_f32_e32 v1, v1
	v_cvt_u32_f32_e32 v5, v5
	v_cvt_u32_f32_e32 v4, v4
	v_cvt_u32_f32_e32 v3, v3
	v_cvt_u32_f32_e32 v2, v2
	v_pk_fma_f32 v[6:7], v[8:9], s[20:21], 0.5 op_sel_hi:[1,0,0]
	v_lshlrev_b32_e32 v5, 8, v5
	v_lshlrev_b32_e32 v4, 8, v4
	v_pk_fma_f32 v[0:1], v[0:1], s[20:21], 0.5 op_sel_hi:[1,0,0]
	v_or_b32_e32 v3, v5, v3
	v_or_b32_e32 v2, v4, v2
	v_cvt_u32_f32_sdwa v4, v7 dst_sel:WORD_1 dst_unused:UNUSED_PAD src0_sel:DWORD
	v_cvt_u32_f32_sdwa v5, v6 dst_sel:WORD_1 dst_unused:UNUSED_PAD src0_sel:DWORD
	v_cvt_u32_f32_sdwa v1, v1 dst_sel:BYTE_3 dst_unused:UNUSED_PAD src0_sel:DWORD
	v_cvt_u32_f32_sdwa v0, v0 dst_sel:BYTE_3 dst_unused:UNUSED_PAD src0_sel:DWORD
	v_or_b32_e32 v3, v3, v4
	v_or_b32_e32 v2, v2, v5
	v_or_b32_e32 v1, v3, v1
	v_or_b32_e32 v0, v2, v0
	v_lshl_add_u64 v[2:3], s[92:93], 0, v[12:13]
	v_lshl_add_u64 v[2:3], v[2:3], 0, v[140:141]
	v_add_co_u32_e32 v2, vcc, 0xb400000, v2
	s_nop 1
	v_addc_co_u32_e32 v3, vcc, 0, v3, vcc
	s_and_b64 vcc, exec, s[4:5]
	s_mov_b64 s[4:5], -1
	global_store_dwordx2 v[2:3], v[0:1], off offset:128
	s_cbranch_vccnz .LBB0_861
	s_andn2_b64 vcc, exec, s[6:7]
	s_cbranch_vccnz .LBB0_860
	s_barrier
	s_branch .LBB0_860
